# per-phase s_setprio flips removed from the four GEMM k-loops
# speedup vs baseline: 1.0096x; 1.0096x over previous
; #define G_STAGE(bufoff, gbase, voff) do { _Pragma("unroll") for (int _i = 0; _i < 2; ++_i) \
;         __builtin_amdgcn_global_load_lds((const unsigned*)((const char*)(gbase) + (voff)[_i]), (LAS unsigned*)(lds + (bufoff) + ldsw + _i * 8192), 16, 0, 0); } while (0)
; #define G_LDA(dst, b, h) do { _Pragma("unroll") for (int m = 0; m < 4; ++m) _Pragma("unroll") for (int k = 0; k < 2; ++k) dst[m][k] = *(const LAS bf16x8*)(lds + G_SA(b, h) + aoff + m * 2048 + k * 1024); } while (0)
; #define G_LDB(dst, b, h) do { _Pragma("unroll") for (int n = 0; n < 2; ++n) _Pragma("unroll") for (int k = 0; k < 2; ++k) dst[n][k] = *(const LAS bf16x8*)(lds + G_SB(b, h) + boff + n * 2048 + k * 1024); } while (0)
; #define G_MMA(ai, bj, At, Bt) do { __builtin_amdgcn_s_setprio(1); _Pragma("unroll") for (int m = 0; m < 4; ++m) _Pragma("unroll") for (int n = 0; n < 2; ++n) _Pragma("unroll") for (int k = 0; k < 2; ++k) \
;         acc[ai][bj][m][n] = __builtin_amdgcn_mfma_f32_16x16x32_bf16(Bt[n][k], At[m][k], acc[ai][bj][m][n], 0, 0, 0); __builtin_amdgcn_s_setprio(0); } while (0)
; #define G_WAIT_L(n) asm volatile("s_waitcnt lgkmcnt(" #n ")" ::: "memory")
; #define G_BAR __builtin_amdgcn_s_barrier()
; #define G_SCHED __builtin_amdgcn_sched_barrier(0)
; template <class Epi, class Sched>
; __device__ __forceinline__ void gemm_phase(LAS unsigned char* lds, const Sched& S, const Epi& E, const int K, const int lda, const int ldb, const int tid) {
;     ...
;             G_LDB(B0, 0, 0); G_SCHED; G_LDA(At, 0, 0); G_STAGE(G_SA(1, 1), a1 + hstepA, voffA);
;             G_WAIT_L(8); G_BAR; G_WAIT_L(0); G_MMA(0, 0, At, B0); G_BAR; G_SCHED;
;             G_LDB(B1, 0, 1); G_STAGE(G_SB(0, 0), b2, voffB);
;             G_BAR; G_WAIT_L(0); G_MMA(0, 1, At, B1); G_BAR;
;             G_LDA(At, 0, 1); G_STAGE(G_SA(0, 0), a2, voffA);
;             G_BAR; G_WAIT_L(0); G_MMA(1, 0, At, B0); G_BAR; G_SCHED;
.LBB0_76:
	s_add_u32 s20, s18, 0xfff80080
	s_addc_u32 s21, s19, -1
	s_add_i32 s43, 0, 0x10000
	v_add_u32_e32 v142, s43, v214
	ds_read_b128 v[130:133], v142
	ds_read_b128 v[134:137], v142 offset:1024
	ds_read_b128 v[138:141], v142 offset:2048
	ds_read_b128 v[142:145], v142 offset:3072
	s_cmp_eq_u32 s41, 28
	s_cselect_b32 s23, s11, s21
	s_cselect_b32 s22, s13, s20
	s_cselect_b32 s21, s37, s40
	s_cselect_b32 s20, s38, s39
	v_lshl_add_u64 v[188:189], s[18:19], 0, v[184:185]
	s_add_i32 m0, s29, 0xc000
	ds_read_b128 v[146:149], v216
	ds_read_b128 v[150:153], v216 offset:1024
	ds_read_b128 v[154:157], v216 offset:2048
	ds_read_b128 v[158:161], v216 offset:3072
	ds_read_b128 v[162:165], v216 offset:4096
	ds_read_b128 v[166:169], v216 offset:5120
	ds_read_b128 v[170:173], v216 offset:6144
	ds_read_b128 v[174:177], v216 offset:7168
	global_load_lds_dwordx4 v[188:189], off
	v_lshl_add_u64 v[188:189], s[18:19], 0, v[186:187]
	s_add_i32 m0, s29, 0xe000
	s_nop 0
	global_load_lds_dwordx4 v[188:189], off
	s_waitcnt lgkmcnt(8)
	s_barrier
	s_waitcnt lgkmcnt(0)
	s_waitcnt lgkmcnt(0)
	v_mfma_f32_16x16x32_bf16 v[126:129], v[130:133], v[146:149], v[126:129]
	v_mfma_f32_16x16x32_bf16 v[122:125], v[138:141], v[146:149], v[122:125]
	v_mfma_f32_16x16x32_bf16 v[110:113], v[130:133], v[154:157], v[110:113]
	v_mfma_f32_16x16x32_bf16 v[106:109], v[138:141], v[154:157], v[106:109]
	v_mfma_f32_16x16x32_bf16 v[94:97], v[130:133], v[162:165], v[94:97]
	v_mfma_f32_16x16x32_bf16 v[90:93], v[138:141], v[162:165], v[90:93]
	v_mfma_f32_16x16x32_bf16 v[78:81], v[130:133], v[170:173], v[78:81]
	v_mfma_f32_16x16x32_bf16 v[74:77], v[138:141], v[170:173], v[74:77]
	v_mfma_f32_16x16x32_bf16 v[126:129], v[134:137], v[150:153], v[126:129]
	v_mfma_f32_16x16x32_bf16 v[122:125], v[142:145], v[150:153], v[122:125]
	v_mfma_f32_16x16x32_bf16 v[110:113], v[134:137], v[158:161], v[110:113]
	v_mfma_f32_16x16x32_bf16 v[106:109], v[142:145], v[158:161], v[106:109]
	v_mfma_f32_16x16x32_bf16 v[94:97], v[134:137], v[166:169], v[94:97]
	v_mfma_f32_16x16x32_bf16 v[90:93], v[142:145], v[166:169], v[90:93]
	v_mfma_f32_16x16x32_bf16 v[78:81], v[134:137], v[174:177], v[78:81]
	v_mfma_f32_16x16x32_bf16 v[74:77], v[142:145], v[174:177], v[74:77]
	s_barrier
	s_add_i32 s62, 0, 0x14000
	v_add_u32_e32 v188, s62, v214
	s_add_i32 s43, s43, s27
	ds_read_b128 v[192:195], v188
	ds_read_b128 v[198:201], v188 offset:1024
	ds_read_b128 v[202:205], v188 offset:2048
	ds_read_b128 v[206:209], v188 offset:3072
	v_lshl_add_u64 v[188:189], s[20:21], 0, v[0:1]
	s_mov_b32 m0, s43
	v_lshl_add_u64 v[210:211], s[20:21], 0, v[178:179]
	global_load_lds_dwordx4 v[188:189], off
	s_add_i32 m0, s43, 0x2000
	s_nop 0
	global_load_lds_dwordx4 v[210:211], off
	s_barrier
	s_waitcnt lgkmcnt(0)
	s_waitcnt lgkmcnt(0)
	v_mfma_f32_16x16x32_bf16 v[118:121], v[192:195], v[146:149], v[118:121]
	v_mfma_f32_16x16x32_bf16 v[114:117], v[202:205], v[146:149], v[114:117]
	v_mfma_f32_16x16x32_bf16 v[102:105], v[192:195], v[154:157], v[102:105]
	v_mfma_f32_16x16x32_bf16 v[98:101], v[202:205], v[154:157], v[98:101]
	v_mfma_f32_16x16x32_bf16 v[86:89], v[192:195], v[162:165], v[86:89]
	v_mfma_f32_16x16x32_bf16 v[82:85], v[202:205], v[162:165], v[82:85]
	v_mfma_f32_16x16x32_bf16 v[70:73], v[192:195], v[170:173], v[70:73]
	v_mfma_f32_16x16x32_bf16 v[66:69], v[202:205], v[170:173], v[66:69]
	v_mfma_f32_16x16x32_bf16 v[118:121], v[198:201], v[150:153], v[118:121]
	v_mfma_f32_16x16x32_bf16 v[114:117], v[206:209], v[150:153], v[114:117]
	v_mfma_f32_16x16x32_bf16 v[102:105], v[198:201], v[158:161], v[102:105]
	v_mfma_f32_16x16x32_bf16 v[98:101], v[206:209], v[158:161], v[98:101]
	v_mfma_f32_16x16x32_bf16 v[86:89], v[198:201], v[166:169], v[86:89]
	v_mfma_f32_16x16x32_bf16 v[82:85], v[206:209], v[166:169], v[82:85]
	v_mfma_f32_16x16x32_bf16 v[70:73], v[198:201], v[174:177], v[70:73]
	v_mfma_f32_16x16x32_bf16 v[66:69], v[206:209], v[174:177], v[66:69]
	s_mov_b32 m0, s29
	v_lshl_add_u64 v[212:213], s[22:23], 0, v[182:183]
	s_barrier
	ds_read_b128 v[146:149], v216 offset:16384
	ds_read_b128 v[150:153], v216 offset:17408
	ds_read_b128 v[154:157], v216 offset:18432
	ds_read_b128 v[158:161], v216 offset:19456
	ds_read_b128 v[162:165], v216 offset:20480
	ds_read_b128 v[166:169], v216 offset:21504
	ds_read_b128 v[170:173], v216 offset:22528
	ds_read_b128 v[174:177], v216 offset:23552
	global_load_lds_dwordx4 v[212:213], off
	v_lshl_add_u64 v[218:219], s[22:23], 0, v[180:181]
	s_mov_b32 m0, s30
	s_nop 0
	global_load_lds_dwordx4 v[218:219], off
	s_barrier
	s_waitcnt lgkmcnt(0)
	s_waitcnt lgkmcnt(0)
	v_mfma_f32_16x16x32_bf16 v[62:65], v[130:133], v[146:149], v[62:65]
	v_mfma_f32_16x16x32_bf16 v[58:61], v[138:141], v[146:149], v[58:61]
	v_mfma_f32_16x16x32_bf16 v[46:49], v[130:133], v[154:157], v[46:49]
	v_mfma_f32_16x16x32_bf16 v[42:45], v[138:141], v[154:157], v[42:45]
	v_mfma_f32_16x16x32_bf16 v[30:33], v[130:133], v[162:165], v[30:33]
	v_mfma_f32_16x16x32_bf16 v[26:29], v[138:141], v[162:165], v[26:29]
	v_mfma_f32_16x16x32_bf16 v[14:17], v[130:133], v[170:173], v[14:17]
	v_mfma_f32_16x16x32_bf16 v[10:13], v[138:141], v[170:173], v[10:13]
	v_mfma_f32_16x16x32_bf16 v[62:65], v[134:137], v[150:153], v[62:65]
	v_mfma_f32_16x16x32_bf16 v[58:61], v[142:145], v[150:153], v[58:61]
	v_mfma_f32_16x16x32_bf16 v[46:49], v[134:137], v[158:161], v[46:49]
	v_mfma_f32_16x16x32_bf16 v[42:45], v[142:145], v[158:161], v[42:45]
	v_mfma_f32_16x16x32_bf16 v[30:33], v[134:137], v[166:169], v[30:33]
	v_mfma_f32_16x16x32_bf16 v[26:29], v[142:145], v[166:169], v[26:29]
	v_mfma_f32_16x16x32_bf16 v[14:17], v[134:137], v[174:177], v[14:17]
	v_mfma_f32_16x16x32_bf16 v[10:13], v[142:145], v[174:177], v[10:13]
	s_barrier
; #define G_STAGE(bufoff, gbase, voff) do { _Pragma("unroll") for (int _i = 0; _i < 2; ++_i) \
;         __builtin_amdgcn_global_load_lds((const unsigned*)((const char*)(gbase) + (voff)[_i]), (LAS unsigned*)(lds + (bufoff) + ldsw + _i * 8192), 16, 0, 0); } while (0)
; #define G_LDA(dst, b, h) do { _Pragma("unroll") for (int m = 0; m < 4; ++m) _Pragma("unroll") for (int k = 0; k < 2; ++k) dst[m][k] = *(const LAS bf16x8*)(lds + G_SA(b, h) + aoff + m * 2048 + k * 1024); } while (0)
; #define G_LDB(dst, b, h) do { _Pragma("unroll") for (int n = 0; n < 2; ++n) _Pragma("unroll") for (int k = 0; k < 2; ++k) dst[n][k] = *(const LAS bf16x8*)(lds + G_SB(b, h) + boff + n * 2048 + k * 1024); } while (0)
; #define G_MMA(ai, bj, At, Bt) do { __builtin_amdgcn_s_setprio(1); _Pragma("unroll") for (int m = 0; m < 4; ++m) _Pragma("unroll") for (int n = 0; n < 2; ++n) _Pragma("unroll") for (int k = 0; k < 2; ++k) \
;         acc[ai][bj][m][n] = __builtin_amdgcn_mfma_f32_16x16x32_bf16(Bt[n][k], At[m][k], acc[ai][bj][m][n], 0, 0, 0); __builtin_amdgcn_s_setprio(0); } while (0)
; #define G_WAIT_V(n) asm volatile("s_waitcnt vmcnt(" #n ")" ::: "memory")
; #define G_WAIT_L(n) asm volatile("s_waitcnt lgkmcnt(" #n ")" ::: "memory")
; #define G_BAR __builtin_amdgcn_s_barrier()
; #define G_SCHED __builtin_amdgcn_sched_barrier(0)
; template <class Epi, class Sched>
; __device__ __forceinline__ void gemm_phase(LAS unsigned char* lds, const Sched& S, const Epi& E, const int K, const int lda, const int ldb, const int tid) {
;     ...
;             G_STAGE(G_SB(0, 1), b2 + hstepB, voffB);
;             G_WAIT_V(6); G_BAR; G_MMA(1, 1, At, B1); G_BAR;
;             G_LDB(B0, 1, 0); G_SCHED; G_LDA(At, 1, 0); G_STAGE(G_SA(0, 1), a2 + hstepA, voffA);
;             G_WAIT_L(8); G_BAR; G_WAIT_L(0); G_MMA(0, 0, At, B0); G_BAR; G_SCHED;
;             G_LDB(B1, 1, 1); G_STAGE(G_SB(1, 0), b3, voffB);
;             G_BAR; G_WAIT_L(0); G_MMA(0, 1, At, B1); G_BAR;
;             G_LDA(At, 1, 1); G_STAGE(G_SA(1, 0), a3, voffA);
;             G_BAR; G_WAIT_L(0); G_MMA(1, 0, At, B0); G_BAR; G_SCHED;
	s_add_u32 s60, s20, 0x80000
	s_addc_u32 s61, s21, 0
	s_add_i32 s43, s62, s27
	v_lshl_add_u64 v[130:131], s[60:61], 0, v[0:1]
	s_mov_b32 m0, s43
	s_nop 0
	global_load_lds_dwordx4 v[130:131], off
	v_lshl_add_u64 v[130:131], s[60:61], 0, v[178:179]
	s_add_i32 m0, s43, 0x2000
	s_nop 0
	global_load_lds_dwordx4 v[130:131], off
	s_waitcnt vmcnt(6)
	s_barrier
	v_mfma_f32_16x16x32_bf16 v[54:57], v[192:195], v[146:149], v[54:57]
	v_mfma_f32_16x16x32_bf16 v[50:53], v[202:205], v[146:149], v[50:53]
	v_mfma_f32_16x16x32_bf16 v[38:41], v[192:195], v[154:157], v[38:41]
	v_mfma_f32_16x16x32_bf16 v[34:37], v[202:205], v[154:157], v[34:37]
	v_mfma_f32_16x16x32_bf16 v[22:25], v[192:195], v[162:165], v[22:25]
	v_mfma_f32_16x16x32_bf16 v[18:21], v[202:205], v[162:165], v[18:21]
	v_mfma_f32_16x16x32_bf16 v[6:9], v[192:195], v[170:173], v[6:9]
	v_mfma_f32_16x16x32_bf16 v[2:5], v[202:205], v[170:173], v[2:5]
	v_mfma_f32_16x16x32_bf16 v[54:57], v[198:201], v[150:153], v[54:57]
	v_mfma_f32_16x16x32_bf16 v[50:53], v[206:209], v[150:153], v[50:53]
	v_mfma_f32_16x16x32_bf16 v[38:41], v[198:201], v[158:161], v[38:41]
	v_mfma_f32_16x16x32_bf16 v[34:37], v[206:209], v[158:161], v[34:37]
	v_mfma_f32_16x16x32_bf16 v[22:25], v[198:201], v[166:169], v[22:25]
	v_mfma_f32_16x16x32_bf16 v[18:21], v[206:209], v[166:169], v[18:21]
	v_mfma_f32_16x16x32_bf16 v[6:9], v[198:201], v[174:177], v[6:9]
	v_mfma_f32_16x16x32_bf16 v[2:5], v[206:209], v[174:177], v[2:5]
	s_add_i32 s43, 0, 0x18000
	v_add_u32_e32 v142, s43, v214
	s_barrier
	ds_read_b128 v[130:133], v142
	ds_read_b128 v[134:137], v142 offset:1024
	ds_read_b128 v[138:141], v142 offset:2048
	ds_read_b128 v[142:145], v142 offset:3072
	s_add_u32 s22, s22, 0x80000
	s_addc_u32 s23, s23, 0
	s_mov_b32 m0, s31
	v_lshl_add_u64 v[192:193], s[22:23], 0, v[182:183]
	ds_read_b128 v[146:149], v216 offset:32768
	ds_read_b128 v[150:153], v216 offset:33792
	ds_read_b128 v[154:157], v216 offset:34816
	ds_read_b128 v[158:161], v216 offset:35840
	ds_read_b128 v[162:165], v216 offset:36864
	ds_read_b128 v[166:169], v216 offset:37888
	ds_read_b128 v[170:173], v216 offset:38912
	ds_read_b128 v[174:177], v216 offset:39936
	global_load_lds_dwordx4 v[192:193], off
	v_lshl_add_u64 v[192:193], s[22:23], 0, v[180:181]
	s_mov_b32 m0, s33
	s_nop 0
	global_load_lds_dwordx4 v[192:193], off
	s_waitcnt lgkmcnt(8)
	s_barrier
	s_waitcnt lgkmcnt(0)
	s_waitcnt lgkmcnt(0)
	v_mfma_f32_16x16x32_bf16 v[126:129], v[130:133], v[146:149], v[126:129]
	v_mfma_f32_16x16x32_bf16 v[122:125], v[138:141], v[146:149], v[122:125]
	v_mfma_f32_16x16x32_bf16 v[110:113], v[130:133], v[154:157], v[110:113]
	v_mfma_f32_16x16x32_bf16 v[106:109], v[138:141], v[154:157], v[106:109]
	v_mfma_f32_16x16x32_bf16 v[94:97], v[130:133], v[162:165], v[94:97]
	v_mfma_f32_16x16x32_bf16 v[90:93], v[138:141], v[162:165], v[90:93]
	v_mfma_f32_16x16x32_bf16 v[78:81], v[130:133], v[170:173], v[78:81]
	v_mfma_f32_16x16x32_bf16 v[74:77], v[138:141], v[170:173], v[74:77]
	v_mfma_f32_16x16x32_bf16 v[126:129], v[134:137], v[150:153], v[126:129]
	v_mfma_f32_16x16x32_bf16 v[122:125], v[142:145], v[150:153], v[122:125]
	v_mfma_f32_16x16x32_bf16 v[110:113], v[134:137], v[158:161], v[110:113]
	v_mfma_f32_16x16x32_bf16 v[106:109], v[142:145], v[158:161], v[106:109]
	v_mfma_f32_16x16x32_bf16 v[94:97], v[134:137], v[166:169], v[94:97]
	v_mfma_f32_16x16x32_bf16 v[90:93], v[142:145], v[166:169], v[90:93]
	v_mfma_f32_16x16x32_bf16 v[78:81], v[134:137], v[174:177], v[78:81]
	v_mfma_f32_16x16x32_bf16 v[74:77], v[142:145], v[174:177], v[74:77]
	s_barrier
	s_add_i32 s22, 0, 0x1c000
	s_add_i32 s23, s43, s27
	v_add_u32_e32 v206, s22, v214
	v_lshl_add_u64 v[188:189], v[188:189], 0, s[92:93]
	s_mov_b32 m0, s23
	ds_read_b128 v[192:195], v206
	ds_read_b128 v[198:201], v206 offset:1024
	ds_read_b128 v[202:205], v206 offset:2048
	ds_read_b128 v[206:209], v206 offset:3072
	global_load_lds_dwordx4 v[188:189], off
	v_lshl_add_u64 v[188:189], v[210:211], 0, s[92:93]
	s_add_i32 m0, s23, 0x2000
	s_nop 0
	global_load_lds_dwordx4 v[188:189], off
	s_barrier
	s_waitcnt lgkmcnt(0)
	s_waitcnt lgkmcnt(0)
	v_mfma_f32_16x16x32_bf16 v[118:121], v[192:195], v[146:149], v[118:121]
	v_mfma_f32_16x16x32_bf16 v[114:117], v[202:205], v[146:149], v[114:117]
	v_mfma_f32_16x16x32_bf16 v[102:105], v[192:195], v[154:157], v[102:105]
	v_mfma_f32_16x16x32_bf16 v[98:101], v[202:205], v[154:157], v[98:101]
	v_mfma_f32_16x16x32_bf16 v[86:89], v[192:195], v[162:165], v[86:89]
	v_mfma_f32_16x16x32_bf16 v[82:85], v[202:205], v[162:165], v[82:85]
	v_mfma_f32_16x16x32_bf16 v[70:73], v[192:195], v[170:173], v[70:73]
	v_mfma_f32_16x16x32_bf16 v[66:69], v[202:205], v[170:173], v[66:69]
	v_mfma_f32_16x16x32_bf16 v[118:121], v[198:201], v[150:153], v[118:121]
	v_mfma_f32_16x16x32_bf16 v[114:117], v[206:209], v[150:153], v[114:117]
	v_mfma_f32_16x16x32_bf16 v[102:105], v[198:201], v[158:161], v[102:105]
	v_mfma_f32_16x16x32_bf16 v[98:101], v[206:209], v[158:161], v[98:101]
	v_mfma_f32_16x16x32_bf16 v[86:89], v[198:201], v[166:169], v[86:89]
	v_mfma_f32_16x16x32_bf16 v[82:85], v[206:209], v[166:169], v[82:85]
	v_mfma_f32_16x16x32_bf16 v[70:73], v[198:201], v[174:177], v[70:73]
	v_mfma_f32_16x16x32_bf16 v[66:69], v[206:209], v[174:177], v[66:69]
	s_mov_b32 m0, s34
	v_lshl_add_u64 v[188:189], v[212:213], 0, s[92:93]
	s_barrier
	ds_read_b128 v[146:149], v216 offset:49152
	ds_read_b128 v[150:153], v216 offset:50176
	ds_read_b128 v[154:157], v216 offset:51200
	ds_read_b128 v[158:161], v216 offset:52224
	ds_read_b128 v[162:165], v216 offset:53248
	ds_read_b128 v[166:169], v216 offset:54272
	ds_read_b128 v[170:173], v216 offset:55296
	ds_read_b128 v[174:177], v216 offset:56320
	global_load_lds_dwordx4 v[188:189], off
	v_lshl_add_u64 v[188:189], v[218:219], 0, s[92:93]
	s_mov_b32 m0, s35
	s_nop 0
	global_load_lds_dwordx4 v[188:189], off
	s_barrier
; __device__ __forceinline__ unsigned pk_bf16(float lo, float hi) { unsigned r; asm volatile("v_cvt_pk_bf16_f32 %0, %1, %2" : "=v"(r) : "v"(lo), "v"(hi)); return r; }
; #define G_STAGE(bufoff, gbase, voff) do { _Pragma("unroll") for (int _i = 0; _i < 2; ++_i) \
;         __builtin_amdgcn_global_load_lds((const unsigned*)((const char*)(gbase) + (voff)[_i]), (LAS unsigned*)(lds + (bufoff) + ldsw + _i * 8192), 16, 0, 0); } while (0)
; #define G_BAR __builtin_amdgcn_s_barrier()
; template <class Epi, class Sched>
; __device__ __forceinline__ void gemm_phase(LAS unsigned char* lds, const Sched& S, const Epi& E, const int K, const int lda, const int ldb, const int tid) {
;     ...
;             G_BAR; G_WAIT_L(0); G_MMA(1, 0, At, B0); G_BAR; G_SCHED;
;             G_STAGE(G_SB(1, 1), b3 + hstepB, voffB);
;             G_WAIT_V(6); G_BAR; G_MMA(1, 1, At, B1); G_BAR;
;         }
;     __device__ __forceinline__ bool operator()(f32x4 (&acc)[2][2][4][2], const Unit& un, int wr, int wc, int fr, int fq) const {
;         const int c0 = un.pn * 256 + wc * 32 + 8 * fq;
;         const int rbase = un.pm * 256 + wr * 64 + fr;
; #pragma unroll
;         for (int ai = 0; ai < 2; ++ai) {
;             f32x4 xv[4][2][2];
; #pragma unroll
;             for (int m = 0; m < 4; ++m)
; #pragma unroll
;                 for (int bj = 0; bj < 2; ++bj) { const float* xp = xf + (size_t)(rbase + ai * 128 + m * 16) * D + c0 + bj * 128;
;                     xv[m][bj][0] = *(const f32x4*)xp; xv[m][bj][1] = *(const f32x4*)(xp + 4); }
; #pragma unroll
;             for (int m = 0; m < 4; ++m) {
;                 const int r = rbase + ai * 128 + m * 16;
;                 float ssq = 0.f;
; #pragma unroll
;                 for (int bj = 0; bj < 2; ++bj) {
;                     float* xp = xf + (size_t)r * D + c0 + bj * 128;
;                     const f32x4 v0 = xv[m][bj][0] + acc[ai][bj][m][0], v1 = xv[m][bj][1] + acc[ai][bj][m][1];
;                     *(f32x4*)xp = v0; *(f32x4*)(xp + 4) = v1;
;                     u32x4 w; w.x = pk_bf16(v0[0], v0[1]); w.y = pk_bf16(v0[2], v0[3]); w.z = pk_bf16(v1[0], v1[1]); w.w = pk_bf16(v1[2], v1[3]);
;                     *(u32x4*)(xb + (size_t)r * D + c0 + bj * 128) = w;
; #pragma unroll
;                     for (int j = 0; j < 4; ++j) ssq += v0[j] * v0[j] + v1[j] * v1[j];
;                 }
;                 if (rsq_next) atomicAdd(rsq_next + r, ssq);
	s_waitcnt lgkmcnt(0)
	s_waitcnt lgkmcnt(0)
	v_mfma_f32_16x16x32_bf16 v[62:65], v[130:133], v[146:149], v[62:65]
	v_mfma_f32_16x16x32_bf16 v[58:61], v[138:141], v[146:149], v[58:61]
	v_mfma_f32_16x16x32_bf16 v[46:49], v[130:133], v[154:157], v[46:49]
	v_mfma_f32_16x16x32_bf16 v[42:45], v[138:141], v[154:157], v[42:45]
	v_mfma_f32_16x16x32_bf16 v[30:33], v[130:133], v[162:165], v[30:33]
	v_mfma_f32_16x16x32_bf16 v[26:29], v[138:141], v[162:165], v[26:29]
	v_mfma_f32_16x16x32_bf16 v[14:17], v[130:133], v[170:173], v[14:17]
	v_mfma_f32_16x16x32_bf16 v[10:13], v[138:141], v[170:173], v[10:13]
	v_mfma_f32_16x16x32_bf16 v[62:65], v[134:137], v[150:153], v[62:65]
	v_mfma_f32_16x16x32_bf16 v[58:61], v[142:145], v[150:153], v[58:61]
	v_mfma_f32_16x16x32_bf16 v[46:49], v[134:137], v[158:161], v[46:49]
	v_mfma_f32_16x16x32_bf16 v[42:45], v[142:145], v[158:161], v[42:45]
	v_mfma_f32_16x16x32_bf16 v[30:33], v[134:137], v[166:169], v[30:33]
	v_mfma_f32_16x16x32_bf16 v[26:29], v[142:145], v[166:169], v[26:29]
	v_mfma_f32_16x16x32_bf16 v[14:17], v[134:137], v[174:177], v[14:17]
	v_mfma_f32_16x16x32_bf16 v[10:13], v[142:145], v[174:177], v[10:13]
	s_barrier
	s_add_u32 s20, s20, 0x80080
	s_addc_u32 s21, s21, 0
	s_add_i32 s22, s22, s27
	v_lshl_add_u64 v[130:131], s[20:21], 0, v[0:1]
	s_mov_b32 m0, s22
	s_nop 0
	global_load_lds_dwordx4 v[130:131], off
	v_lshl_add_u64 v[130:131], s[20:21], 0, v[178:179]
	s_add_i32 m0, s22, 0x2000
	s_nop 0
	global_load_lds_dwordx4 v[130:131], off
	s_waitcnt vmcnt(6)
	s_barrier
	v_mfma_f32_16x16x32_bf16 v[54:57], v[192:195], v[146:149], v[54:57]
	v_mfma_f32_16x16x32_bf16 v[50:53], v[202:205], v[146:149], v[50:53]
	v_mfma_f32_16x16x32_bf16 v[38:41], v[192:195], v[154:157], v[38:41]
	v_mfma_f32_16x16x32_bf16 v[34:37], v[202:205], v[154:157], v[34:37]
	v_mfma_f32_16x16x32_bf16 v[22:25], v[192:195], v[162:165], v[22:25]
	v_mfma_f32_16x16x32_bf16 v[18:21], v[202:205], v[162:165], v[18:21]
	v_mfma_f32_16x16x32_bf16 v[6:9], v[192:195], v[170:173], v[6:9]
	v_mfma_f32_16x16x32_bf16 v[2:5], v[202:205], v[170:173], v[2:5]
	v_mfma_f32_16x16x32_bf16 v[54:57], v[198:201], v[150:153], v[54:57]
	v_mfma_f32_16x16x32_bf16 v[50:53], v[206:209], v[150:153], v[50:53]
	v_mfma_f32_16x16x32_bf16 v[38:41], v[198:201], v[158:161], v[38:41]
	v_mfma_f32_16x16x32_bf16 v[34:37], v[206:209], v[158:161], v[34:37]
	v_mfma_f32_16x16x32_bf16 v[22:25], v[198:201], v[166:169], v[22:25]
	v_mfma_f32_16x16x32_bf16 v[18:21], v[206:209], v[166:169], v[18:21]
	v_mfma_f32_16x16x32_bf16 v[6:9], v[198:201], v[174:177], v[6:9]
	v_mfma_f32_16x16x32_bf16 v[2:5], v[206:209], v[174:177], v[2:5]
	s_add_i32 s41, s41, 2
	s_add_u32 s18, s18, 0x100
	s_addc_u32 s19, s19, 0
	s_add_u32 s39, s39, 0x100
	s_addc_u32 s40, s40, 0
	s_cmp_gt_u32 s41, 29
	s_barrier
	s_cbranch_scc0 .LBB0_76
	v_lshl_or_b32 v188, s9, 8, v215
	v_lshl_add_u32 v200, s8, 8, v197
	v_ashrrev_i32_e32 v189, 31, v188
	v_lshlrev_b64 v[230:231], 2, v[188:189]
	v_ashrrev_i32_e32 v201, 31, v200
	v_or_b32_e32 v208, 16, v200
	v_lshl_add_u64 v[198:199], s[76:77], 0, v[230:231]
	v_lshlrev_b64 v[232:233], 13, v[200:201]
	v_ashrrev_i32_e32 v209, 31, v208
	v_or_b32_e32 v204, 32, v200
	v_or_b32_e32 v202, 48, v200
	v_lshl_add_u64 v[130:131], v[198:199], 0, v[232:233]
	v_lshlrev_b64 v[212:213], 13, v[208:209]
	v_ashrrev_i32_e32 v205, 31, v204
	v_ashrrev_i32_e32 v203, 31, v202
	global_load_dwordx4 v[192:195], v[130:131], off offset:16
	global_load_dwordx4 v[218:221], v[130:131], off
	global_load_dwordx4 v[222:225], v[130:131], off offset:528
	global_load_dwordx4 v[226:229], v[130:131], off offset:512
	v_lshl_add_u64 v[130:131], v[198:199], 0, v[212:213]
	v_lshlrev_b64 v[210:211], 13, v[204:205]
	v_lshlrev_b64 v[206:207], 13, v[202:203]
	global_load_dwordx4 v[170:173], v[130:131], off offset:16
	global_load_dwordx4 v[174:177], v[130:131], off
	global_load_dwordx4 v[162:165], v[130:131], off offset:528
	global_load_dwordx4 v[166:169], v[130:131], off offset:512
	v_lshl_add_u64 v[130:131], v[198:199], 0, v[210:211]
	v_lshl_add_u64 v[134:135], v[198:199], 0, v[206:207]
	global_load_dwordx4 v[154:157], v[130:131], off offset:16
	global_load_dwordx4 v[158:161], v[130:131], off
	global_load_dwordx4 v[146:149], v[130:131], off offset:528
	global_load_dwordx4 v[150:153], v[130:131], off offset:512
	global_load_dwordx4 v[138:141], v[134:135], off offset:16
	global_load_dwordx4 v[142:145], v[134:135], off
	s_nop 0
	global_load_dwordx4 v[130:133], v[134:135], off offset:528
	s_nop 0
	global_load_dwordx4 v[134:137], v[134:135], off offset:512
	v_lshl_add_u64 v[232:233], s[76:77], 0, v[232:233]
	v_lshl_add_u64 v[230:231], v[232:233], 0, v[230:231]
	s_andn2_b64 vcc, exec, s[0:1]
	s_waitcnt vmcnt(0)
	v_pk_add_f32 v[124:125], v[124:125], v[194:195]
	v_pk_add_f32 v[126:127], v[126:127], v[218:219]
	v_lshlrev_b64 v[218:219], 12, v[200:201]
	v_pk_add_f32 v[128:129], v[128:129], v[220:221]
	v_lshl_add_u64 v[218:219], s[68:69], 0, v[218:219]
	v_pk_add_f32 v[122:123], v[122:123], v[192:193]
	global_store_dwordx4 v[230:231], v[126:129], off
	global_store_dwordx4 v[230:231], v[122:125], off offset:16
	v_cvt_pk_bf16_f32 v192, v126, v127
	v_lshl_add_u64 v[218:219], v[188:189], 1, v[218:219]
	v_pk_add_f32 v[120:121], v[120:121], v[228:229]
	v_pk_add_f32 v[118:119], v[118:119], v[226:227]
	v_cvt_pk_bf16_f32 v193, v128, v129
	v_cvt_pk_bf16_f32 v194, v122, v123
	v_cvt_pk_bf16_f32 v195, v124, v125
	global_store_dwordx4 v[218:219], v[192:195], off
	v_pk_add_f32 v[116:117], v[116:117], v[224:225]
	v_pk_add_f32 v[114:115], v[114:115], v[222:223]
	global_store_dwordx4 v[230:231], v[118:121], off offset:512
	global_store_dwordx4 v[230:231], v[114:117], off offset:528
	v_cvt_pk_bf16_f32 v192, v118, v119
	v_cvt_pk_bf16_f32 v193, v120, v121
	v_cvt_pk_bf16_f32 v194, v114, v115
	v_cvt_pk_bf16_f32 v195, v116, v117
	global_store_dwordx4 v[218:219], v[192:195], off offset:256
	s_nop 1
	v_cndmask_b32_e64 v192, 0, 1, s[0:1]
	v_cmp_ne_u32_e64 s[8:9], 1, v192
	s_cbranch_vccnz .LBB0_79
	v_mul_f32_e32 v122, v122, v122
	v_mul_f32_e32 v123, v123, v123
	v_fmac_f32_e32 v122, v126, v126
	v_fmac_f32_e32 v123, v127, v127
	v_add_f32_e32 v122, v122, v123
	v_mul_f32_e32 v123, v124, v124
	v_fmac_f32_e32 v123, v128, v128
	v_add_f32_e32 v122, v123, v122
	v_mul_f32_e32 v123, v125, v125
	v_fmac_f32_e32 v123, v129, v129
	v_mul_f32_e32 v114, v114, v114
	v_add_f32_e32 v122, v123, v122
	v_fmac_f32_e32 v114, v118, v118
	v_mul_f32_e32 v115, v115, v115
	v_add_f32_e32 v114, v114, v122
	v_fmac_f32_e32 v115, v119, v119
	v_add_f32_e32 v114, v115, v114
	v_mul_f32_e32 v115, v116, v116
	v_fmac_f32_e32 v115, v120, v120
	v_add_f32_e32 v114, v115, v114
	v_mul_f32_e32 v115, v117, v117
	v_readlane_b32 s18, v253, 49
	v_fmac_f32_e32 v115, v121, v121
	v_readlane_b32 s19, v253, 50
	v_add_f32_e32 v116, v115, v114
	s_nop 0
	v_lshl_add_u64 v[114:115], v[200:201], 2, s[18:19]
	global_atomic_add_f32 v[114:115], v116, off

; #define G_STAGE(bufoff, gbase, voff) do { _Pragma("unroll") for (int _i = 0; _i < 2; ++_i) \
;         __builtin_amdgcn_global_load_lds((const unsigned*)((const char*)(gbase) + (voff)[_i]), (LAS unsigned*)(lds + (bufoff) + ldsw + _i * 8192), 16, 0, 0); } while (0)
; #define G_LDA(dst, b, h) do { _Pragma("unroll") for (int m = 0; m < 4; ++m) _Pragma("unroll") for (int k = 0; k < 2; ++k) dst[m][k] = *(const LAS bf16x8*)(lds + G_SA(b, h) + aoff + m * 2048 + k * 1024); } while (0)
; #define G_LDB(dst, b, h) do { _Pragma("unroll") for (int n = 0; n < 2; ++n) _Pragma("unroll") for (int k = 0; k < 2; ++k) dst[n][k] = *(const LAS bf16x8*)(lds + G_SB(b, h) + boff + n * 2048 + k * 1024); } while (0)
; #define G_MMA(ai, bj, At, Bt) do { __builtin_amdgcn_s_setprio(1); _Pragma("unroll") for (int m = 0; m < 4; ++m) _Pragma("unroll") for (int n = 0; n < 2; ++n) _Pragma("unroll") for (int k = 0; k < 2; ++k) \
;         acc[ai][bj][m][n] = __builtin_amdgcn_mfma_f32_16x16x32_bf16(Bt[n][k], At[m][k], acc[ai][bj][m][n], 0, 0, 0); __builtin_amdgcn_s_setprio(0); } while (0)
; #define G_WAIT_L(n) asm volatile("s_waitcnt lgkmcnt(" #n ")" ::: "memory")
; #define G_BAR __builtin_amdgcn_s_barrier()
; #define G_SCHED __builtin_amdgcn_sched_barrier(0)
; template <class Epi, class Sched>
; __device__ __forceinline__ void gemm_phase(LAS unsigned char* lds, const Sched& S, const Epi& E, const int K, const int lda, const int ldb, const int tid) {
;     ...
;             G_LDB(B0, 0, 0); G_SCHED; G_LDA(At, 0, 0); G_STAGE(G_SA(1, 1), a1 + hstepA, voffA);
;             G_WAIT_L(8); G_BAR; G_WAIT_L(0); G_MMA(0, 0, At, B0); G_BAR; G_SCHED;
;             G_LDB(B1, 0, 1); G_STAGE(G_SB(0, 0), b2, voffB);
;             G_BAR; G_WAIT_L(0); G_MMA(0, 1, At, B1); G_BAR;
;             G_LDA(At, 0, 1); G_STAGE(G_SA(0, 0), a2, voffA);
;             G_BAR; G_WAIT_L(0); G_MMA(1, 0, At, B0); G_BAR; G_SCHED;
.LBB0_158:
	s_add_u32 s24, s26, 0xfff80080
	s_addc_u32 s25, s27, -1
	s_add_i32 s43, 0, 0x10000
	v_add_u32_e32 v0, s43, v245
	ds_read_b128 v[124:127], v0
	ds_read_b128 v[128:131], v0 offset:1024
	ds_read_b128 v[136:139], v0 offset:2048
	ds_read_b128 v[140:143], v0 offset:3072
	s_cmp_eq_u32 s33, 28
	s_cselect_b32 s29, s19, s25
	s_cselect_b32 s28, s18, s24
	s_cselect_b32 s25, s21, s11
	s_cselect_b32 s24, s20, s1
	v_lshl_add_u64 v[2:3], s[26:27], 0, v[184:185]
	s_add_i32 m0, s36, 0xc000
	ds_read_b128 v[148:151], v248
	ds_read_b128 v[152:155], v248 offset:1024
	ds_read_b128 v[156:159], v248 offset:2048
	ds_read_b128 v[160:163], v248 offset:3072
	ds_read_b128 v[164:167], v248 offset:4096
	ds_read_b128 v[168:171], v248 offset:5120
	ds_read_b128 v[172:175], v248 offset:6144
	ds_read_b128 v[192:195], v248 offset:7168
	global_load_lds_dwordx4 v[2:3], off
	v_lshl_add_u64 v[2:3], s[26:27], 0, v[186:187]
	s_add_i32 m0, s36, 0xe000
	s_nop 0
	global_load_lds_dwordx4 v[2:3], off
	s_waitcnt lgkmcnt(8)
	s_barrier
	s_waitcnt lgkmcnt(0)
	s_waitcnt lgkmcnt(0)
	v_mfma_f32_16x16x32_bf16 v[144:147], v[124:127], v[148:151], v[144:147]
	v_mfma_f32_16x16x32_bf16 v[100:103], v[136:139], v[148:151], v[100:103]
	v_mfma_f32_16x16x32_bf16 v[2:5], v[124:127], v[156:159], v[4:7]
	v_mfma_f32_16x16x32_bf16 v[60:63], v[136:139], v[156:159], v[60:63]
	v_mfma_f32_16x16x32_bf16 v[132:135], v[124:127], v[164:167], v[132:135]
	v_mfma_f32_16x16x32_bf16 v[104:107], v[136:139], v[164:167], v[104:107]
	v_mfma_f32_16x16x32_bf16 v[6:9], v[124:127], v[172:175], v[8:11]
	v_mfma_f32_16x16x32_bf16 v[72:75], v[136:139], v[172:175], v[72:75]
	v_mfma_f32_16x16x32_bf16 v[144:147], v[128:131], v[152:155], v[144:147]
	v_mfma_f32_16x16x32_bf16 v[100:103], v[140:143], v[152:155], v[100:103]
	v_mfma_f32_16x16x32_bf16 v[2:5], v[128:131], v[160:163], v[2:5]
	v_mfma_f32_16x16x32_bf16 v[60:63], v[140:143], v[160:163], v[60:63]
	v_mfma_f32_16x16x32_bf16 v[132:135], v[128:131], v[168:171], v[132:135]
	v_mfma_f32_16x16x32_bf16 v[104:107], v[140:143], v[168:171], v[104:107]
	v_mfma_f32_16x16x32_bf16 v[8:11], v[128:131], v[192:195], v[6:9]
	v_mfma_f32_16x16x32_bf16 v[72:75], v[140:143], v[192:195], v[72:75]
	s_barrier
	s_add_i32 s62, 0, 0x14000
	s_add_i32 s43, s43, s35
	v_add_u32_e32 v0, s62, v245
	v_lshl_add_u64 v[188:189], s[24:25], 0, v[178:179]
	s_mov_b32 m0, s43
	ds_read_b128 v[198:201], v0
	ds_read_b128 v[202:205], v0 offset:1024
	ds_read_b128 v[206:209], v0 offset:2048
	ds_read_b128 v[210:213], v0 offset:3072
	global_load_lds_dwordx4 v[188:189], off
	v_lshl_add_u64 v[214:215], s[24:25], 0, v[182:183]
	s_add_i32 m0, s43, 0x2000
	s_nop 0
	global_load_lds_dwordx4 v[214:215], off
	s_barrier
	s_waitcnt lgkmcnt(0)
	s_waitcnt lgkmcnt(0)
	v_mfma_f32_16x16x32_bf16 v[12:15], v[198:201], v[148:151], v[12:15]
	v_mfma_f32_16x16x32_bf16 v[56:59], v[206:209], v[148:151], v[56:59]
	v_mfma_f32_16x16x32_bf16 v[16:19], v[198:201], v[156:159], v[16:19]
	v_mfma_f32_16x16x32_bf16 v[64:67], v[206:209], v[156:159], v[64:67]
	v_mfma_f32_16x16x32_bf16 v[20:23], v[198:201], v[164:167], v[20:23]
	v_mfma_f32_16x16x32_bf16 v[68:71], v[206:209], v[164:167], v[68:71]
	v_mfma_f32_16x16x32_bf16 v[24:27], v[198:201], v[172:175], v[24:27]
	v_mfma_f32_16x16x32_bf16 v[76:79], v[206:209], v[172:175], v[76:79]
	v_mfma_f32_16x16x32_bf16 v[12:15], v[202:205], v[152:155], v[12:15]
	v_mfma_f32_16x16x32_bf16 v[56:59], v[210:213], v[152:155], v[56:59]
	v_mfma_f32_16x16x32_bf16 v[16:19], v[202:205], v[160:163], v[16:19]
	v_mfma_f32_16x16x32_bf16 v[64:67], v[210:213], v[160:163], v[64:67]
	v_mfma_f32_16x16x32_bf16 v[20:23], v[202:205], v[168:171], v[20:23]
	v_mfma_f32_16x16x32_bf16 v[68:71], v[210:213], v[168:171], v[68:71]
	v_mfma_f32_16x16x32_bf16 v[24:27], v[202:205], v[192:195], v[24:27]
	v_mfma_f32_16x16x32_bf16 v[76:79], v[210:213], v[192:195], v[76:79]
	s_mov_b32 m0, s36
	v_lshl_add_u64 v[216:217], s[28:29], 0, v[176:177]
	s_barrier
	ds_read_b128 v[148:151], v248 offset:16384
	ds_read_b128 v[152:155], v248 offset:17408
	ds_read_b128 v[156:159], v248 offset:18432
	ds_read_b128 v[160:163], v248 offset:19456
	ds_read_b128 v[164:167], v248 offset:20480
	ds_read_b128 v[168:171], v248 offset:21504
	ds_read_b128 v[172:175], v248 offset:22528
	ds_read_b128 v[192:195], v248 offset:23552
	global_load_lds_dwordx4 v[216:217], off
	v_lshl_add_u64 v[218:219], s[28:29], 0, v[180:181]
	s_mov_b32 m0, s37
	s_nop 0
	global_load_lds_dwordx4 v[218:219], off
	s_barrier
	s_waitcnt lgkmcnt(0)
	s_waitcnt lgkmcnt(0)
	v_mfma_f32_16x16x32_bf16 v[120:123], v[124:127], v[148:151], v[120:123]
	v_mfma_f32_16x16x32_bf16 v[108:111], v[136:139], v[148:151], v[108:111]
	v_mfma_f32_16x16x32_bf16 v[28:31], v[124:127], v[156:159], v[28:31]
	v_mfma_f32_16x16x32_bf16 v[84:87], v[136:139], v[156:159], v[84:87]
	v_mfma_f32_16x16x32_bf16 v[116:119], v[124:127], v[164:167], v[116:119]
	v_mfma_f32_16x16x32_bf16 v[112:115], v[136:139], v[164:167], v[112:115]
	v_mfma_f32_16x16x32_bf16 v[32:35], v[124:127], v[172:175], v[32:35]
	v_mfma_f32_16x16x32_bf16 v[96:99], v[136:139], v[172:175], v[96:99]
	v_mfma_f32_16x16x32_bf16 v[120:123], v[128:131], v[152:155], v[120:123]
	v_mfma_f32_16x16x32_bf16 v[108:111], v[140:143], v[152:155], v[108:111]
	v_mfma_f32_16x16x32_bf16 v[28:31], v[128:131], v[160:163], v[28:31]
	v_mfma_f32_16x16x32_bf16 v[84:87], v[140:143], v[160:163], v[84:87]
	v_mfma_f32_16x16x32_bf16 v[116:119], v[128:131], v[168:171], v[116:119]
	v_mfma_f32_16x16x32_bf16 v[112:115], v[140:143], v[168:171], v[112:115]
	v_mfma_f32_16x16x32_bf16 v[32:35], v[128:131], v[192:195], v[32:35]
	v_mfma_f32_16x16x32_bf16 v[96:99], v[140:143], v[192:195], v[96:99]
	s_barrier
; #define G_STAGE(bufoff, gbase, voff) do { _Pragma("unroll") for (int _i = 0; _i < 2; ++_i) \
;         __builtin_amdgcn_global_load_lds((const unsigned*)((const char*)(gbase) + (voff)[_i]), (LAS unsigned*)(lds + (bufoff) + ldsw + _i * 8192), 16, 0, 0); } while (0)
; #define G_LDA(dst, b, h) do { _Pragma("unroll") for (int m = 0; m < 4; ++m) _Pragma("unroll") for (int k = 0; k < 2; ++k) dst[m][k] = *(const LAS bf16x8*)(lds + G_SA(b, h) + aoff + m * 2048 + k * 1024); } while (0)
; #define G_LDB(dst, b, h) do { _Pragma("unroll") for (int n = 0; n < 2; ++n) _Pragma("unroll") for (int k = 0; k < 2; ++k) dst[n][k] = *(const LAS bf16x8*)(lds + G_SB(b, h) + boff + n * 2048 + k * 1024); } while (0)
; #define G_MMA(ai, bj, At, Bt) do { __builtin_amdgcn_s_setprio(1); _Pragma("unroll") for (int m = 0; m < 4; ++m) _Pragma("unroll") for (int n = 0; n < 2; ++n) _Pragma("unroll") for (int k = 0; k < 2; ++k) \
;         acc[ai][bj][m][n] = __builtin_amdgcn_mfma_f32_16x16x32_bf16(Bt[n][k], At[m][k], acc[ai][bj][m][n], 0, 0, 0); __builtin_amdgcn_s_setprio(0); } while (0)
; #define G_WAIT_V(n) asm volatile("s_waitcnt vmcnt(" #n ")" ::: "memory")
; #define G_WAIT_L(n) asm volatile("s_waitcnt lgkmcnt(" #n ")" ::: "memory")
; #define G_BAR __builtin_amdgcn_s_barrier()
; #define G_SCHED __builtin_amdgcn_sched_barrier(0)
; template <class Epi, class Sched>
; __device__ __forceinline__ void gemm_phase(LAS unsigned char* lds, const Sched& S, const Epi& E, const int K, const int lda, const int ldb, const int tid) {
;     ...
;             G_STAGE(G_SB(0, 1), b2 + hstepB, voffB);
;             G_WAIT_V(6); G_BAR; G_MMA(1, 1, At, B1); G_BAR;
;             G_LDB(B0, 1, 0); G_SCHED; G_LDA(At, 1, 0); G_STAGE(G_SA(0, 1), a2 + hstepA, voffA);
;             G_WAIT_L(8); G_BAR; G_WAIT_L(0); G_MMA(0, 0, At, B0); G_BAR; G_SCHED;
;             G_LDB(B1, 1, 1); G_STAGE(G_SB(1, 0), b3, voffB);
;             G_BAR; G_WAIT_L(0); G_MMA(0, 1, At, B1); G_BAR;
;             G_LDA(At, 1, 1); G_STAGE(G_SA(1, 0), a3, voffA);
;             G_BAR; G_WAIT_L(0); G_MMA(1, 0, At, B0); G_BAR; G_SCHED;
	s_add_u32 s60, s24, 0x80000
	s_addc_u32 s61, s25, 0
	s_add_i32 s43, s62, s35
	v_lshl_add_u64 v[6:7], s[60:61], 0, v[178:179]
	s_mov_b32 m0, s43
	s_nop 0
	global_load_lds_dwordx4 v[6:7], off
	v_lshl_add_u64 v[6:7], s[60:61], 0, v[182:183]
	s_add_i32 m0, s43, 0x2000
	s_nop 0
	global_load_lds_dwordx4 v[6:7], off
	s_waitcnt vmcnt(6)
	s_barrier
	v_mfma_f32_16x16x32_bf16 v[36:39], v[198:201], v[148:151], v[36:39]
	v_mfma_f32_16x16x32_bf16 v[80:83], v[206:209], v[148:151], v[80:83]
	v_mfma_f32_16x16x32_bf16 v[40:43], v[198:201], v[156:159], v[40:43]
	v_mfma_f32_16x16x32_bf16 v[88:91], v[206:209], v[156:159], v[88:91]
	v_mfma_f32_16x16x32_bf16 v[44:47], v[198:201], v[164:167], v[44:47]
	v_mfma_f32_16x16x32_bf16 v[92:95], v[206:209], v[164:167], v[92:95]
	v_mfma_f32_16x16x32_bf16 v[48:51], v[198:201], v[172:175], v[48:51]
	v_mfma_f32_16x16x32_bf16 v[52:55], v[206:209], v[172:175], v[52:55]
	v_mfma_f32_16x16x32_bf16 v[36:39], v[202:205], v[152:155], v[36:39]
	v_mfma_f32_16x16x32_bf16 v[80:83], v[210:213], v[152:155], v[80:83]
	v_mfma_f32_16x16x32_bf16 v[40:43], v[202:205], v[160:163], v[40:43]
	v_mfma_f32_16x16x32_bf16 v[88:91], v[210:213], v[160:163], v[88:91]
	v_mfma_f32_16x16x32_bf16 v[44:47], v[202:205], v[168:171], v[44:47]
	v_mfma_f32_16x16x32_bf16 v[92:95], v[210:213], v[168:171], v[92:95]
	v_mfma_f32_16x16x32_bf16 v[48:51], v[202:205], v[192:195], v[48:51]
	v_mfma_f32_16x16x32_bf16 v[52:55], v[210:213], v[192:195], v[52:55]
	s_add_i32 s43, 0, 0x18000
	v_add_u32_e32 v0, s43, v245
	s_barrier
	ds_read_b128 v[124:127], v0
	ds_read_b128 v[128:131], v0 offset:1024
	ds_read_b128 v[136:139], v0 offset:2048
	ds_read_b128 v[140:143], v0 offset:3072
	s_add_u32 s28, s28, 0x80000
	s_addc_u32 s29, s29, 0
	s_mov_b32 m0, s38
	v_lshl_add_u64 v[6:7], s[28:29], 0, v[176:177]
	ds_read_b128 v[148:151], v248 offset:32768
	ds_read_b128 v[152:155], v248 offset:33792
	ds_read_b128 v[156:159], v248 offset:34816
	ds_read_b128 v[160:163], v248 offset:35840
	ds_read_b128 v[164:167], v248 offset:36864
	ds_read_b128 v[168:171], v248 offset:37888
	ds_read_b128 v[172:175], v248 offset:38912
	ds_read_b128 v[192:195], v248 offset:39936
	global_load_lds_dwordx4 v[6:7], off
	v_lshl_add_u64 v[6:7], s[28:29], 0, v[180:181]
	s_mov_b32 m0, s39
	s_nop 0
	global_load_lds_dwordx4 v[6:7], off
	s_waitcnt lgkmcnt(8)
	s_barrier
	s_waitcnt lgkmcnt(0)
	s_waitcnt lgkmcnt(0)
	v_mfma_f32_16x16x32_bf16 v[144:147], v[124:127], v[148:151], v[144:147]
	v_mfma_f32_16x16x32_bf16 v[100:103], v[136:139], v[148:151], v[100:103]
	v_mfma_f32_16x16x32_bf16 v[2:5], v[124:127], v[156:159], v[2:5]
	v_mfma_f32_16x16x32_bf16 v[60:63], v[136:139], v[156:159], v[60:63]
	v_mfma_f32_16x16x32_bf16 v[132:135], v[124:127], v[164:167], v[132:135]
	v_mfma_f32_16x16x32_bf16 v[104:107], v[136:139], v[164:167], v[104:107]
	v_mfma_f32_16x16x32_bf16 v[8:11], v[124:127], v[172:175], v[8:11]
	v_mfma_f32_16x16x32_bf16 v[72:75], v[136:139], v[172:175], v[72:75]
	v_mfma_f32_16x16x32_bf16 v[144:147], v[128:131], v[152:155], v[144:147]
	v_mfma_f32_16x16x32_bf16 v[100:103], v[140:143], v[152:155], v[100:103]
	v_mfma_f32_16x16x32_bf16 v[4:7], v[128:131], v[160:163], v[2:5]
	v_mfma_f32_16x16x32_bf16 v[60:63], v[140:143], v[160:163], v[60:63]
	v_mfma_f32_16x16x32_bf16 v[132:135], v[128:131], v[168:171], v[132:135]
	v_mfma_f32_16x16x32_bf16 v[104:107], v[140:143], v[168:171], v[104:107]
	v_mfma_f32_16x16x32_bf16 v[8:11], v[128:131], v[192:195], v[8:11]
	v_mfma_f32_16x16x32_bf16 v[72:75], v[140:143], v[192:195], v[72:75]
	s_barrier
	s_add_i32 s28, 0, 0x1c000
	s_add_i32 s29, s43, s35
	v_add_u32_e32 v0, s28, v245
	v_lshl_add_u64 v[2:3], v[188:189], 0, s[92:93]
	s_mov_b32 m0, s29
	ds_read_b128 v[198:201], v0
	ds_read_b128 v[202:205], v0 offset:1024
	ds_read_b128 v[206:209], v0 offset:2048
	ds_read_b128 v[210:213], v0 offset:3072
	global_load_lds_dwordx4 v[2:3], off
	v_lshl_add_u64 v[2:3], v[214:215], 0, s[92:93]
	s_add_i32 m0, s29, 0x2000
	s_nop 0
	global_load_lds_dwordx4 v[2:3], off
	s_barrier
	s_waitcnt lgkmcnt(0)
	s_waitcnt lgkmcnt(0)
	v_mfma_f32_16x16x32_bf16 v[12:15], v[198:201], v[148:151], v[12:15]
	v_mfma_f32_16x16x32_bf16 v[56:59], v[206:209], v[148:151], v[56:59]
	v_mfma_f32_16x16x32_bf16 v[16:19], v[198:201], v[156:159], v[16:19]
	v_mfma_f32_16x16x32_bf16 v[64:67], v[206:209], v[156:159], v[64:67]
	v_mfma_f32_16x16x32_bf16 v[20:23], v[198:201], v[164:167], v[20:23]
	v_mfma_f32_16x16x32_bf16 v[68:71], v[206:209], v[164:167], v[68:71]
	v_mfma_f32_16x16x32_bf16 v[24:27], v[198:201], v[172:175], v[24:27]
	v_mfma_f32_16x16x32_bf16 v[76:79], v[206:209], v[172:175], v[76:79]
	v_mfma_f32_16x16x32_bf16 v[12:15], v[202:205], v[152:155], v[12:15]
	v_mfma_f32_16x16x32_bf16 v[56:59], v[210:213], v[152:155], v[56:59]
	v_mfma_f32_16x16x32_bf16 v[16:19], v[202:205], v[160:163], v[16:19]
	v_mfma_f32_16x16x32_bf16 v[64:67], v[210:213], v[160:163], v[64:67]
	v_mfma_f32_16x16x32_bf16 v[20:23], v[202:205], v[168:171], v[20:23]
	v_mfma_f32_16x16x32_bf16 v[68:71], v[210:213], v[168:171], v[68:71]
	v_mfma_f32_16x16x32_bf16 v[24:27], v[202:205], v[192:195], v[24:27]
	v_mfma_f32_16x16x32_bf16 v[76:79], v[210:213], v[192:195], v[76:79]
	s_mov_b32 m0, s41
	v_lshl_add_u64 v[2:3], v[216:217], 0, s[92:93]
	s_barrier
	ds_read_b128 v[148:151], v248 offset:49152
	ds_read_b128 v[152:155], v248 offset:50176
	ds_read_b128 v[156:159], v248 offset:51200
	ds_read_b128 v[160:163], v248 offset:52224
	ds_read_b128 v[164:167], v248 offset:53248
	ds_read_b128 v[168:171], v248 offset:54272
	ds_read_b128 v[172:175], v248 offset:55296
	ds_read_b128 v[192:195], v248 offset:56320
	global_load_lds_dwordx4 v[2:3], off
	v_lshl_add_u64 v[2:3], v[218:219], 0, s[92:93]
	s_mov_b32 m0, s83
	s_nop 0
	global_load_lds_dwordx4 v[2:3], off
	s_barrier
; #define G_STAGE(bufoff, gbase, voff) do { _Pragma("unroll") for (int _i = 0; _i < 2; ++_i) \
;         __builtin_amdgcn_global_load_lds((const unsigned*)((const char*)(gbase) + (voff)[_i]), (LAS unsigned*)(lds + (bufoff) + ldsw + _i * 8192), 16, 0, 0); } while (0)
; #define G_MMA(ai, bj, At, Bt) do { __builtin_amdgcn_s_setprio(1); _Pragma("unroll") for (int m = 0; m < 4; ++m) _Pragma("unroll") for (int n = 0; n < 2; ++n) _Pragma("unroll") for (int k = 0; k < 2; ++k) \
;         acc[ai][bj][m][n] = __builtin_amdgcn_mfma_f32_16x16x32_bf16(Bt[n][k], At[m][k], acc[ai][bj][m][n], 0, 0, 0); __builtin_amdgcn_s_setprio(0); } while (0)
; #define G_WAIT_V(n) asm volatile("s_waitcnt vmcnt(" #n ")" ::: "memory")
; #define G_WAIT_L(n) asm volatile("s_waitcnt lgkmcnt(" #n ")" ::: "memory")
; #define G_BAR __builtin_amdgcn_s_barrier()
; #define G_SCHED __builtin_amdgcn_sched_barrier(0)
; template <class Epi, class Sched>
; __device__ __forceinline__ void gemm_phase(LAS unsigned char* lds, const Sched& S, const Epi& E, const int K, const int lda, const int ldb, const int tid) {
;     ...
;             G_BAR; G_WAIT_L(0); G_MMA(1, 0, At, B0); G_BAR; G_SCHED;
;             G_STAGE(G_SB(1, 1), b3 + hstepB, voffB);
;             G_WAIT_V(6); G_BAR; G_MMA(1, 1, At, B1); G_BAR;
;         }
;     __device__ __forceinline__ bool operator()(f32x4 (&acc)[2][2][4][2], const Unit& un, int wr, int wc, int fr, int fq) const {
;     ...
;         u32x4 gr[2][4][2];
; #pragma unroll
;         for (int ai = 0; ai < 2; ++ai)
; #pragma unroll
;             for (int m = 0; m < 4; ++m)
; #pragma unroll
;                 for (int bj = 0; bj < 2; ++bj) gr[ai][m][bj] = *(const u32x4*)(zb + (size_t)(rbase + ai * 128 + m * 16) * ZW + ZC_GR + c0 + bj * 128);
	s_waitcnt lgkmcnt(0)
	s_waitcnt lgkmcnt(0)
	v_mfma_f32_16x16x32_bf16 v[120:123], v[124:127], v[148:151], v[120:123]
	v_mfma_f32_16x16x32_bf16 v[108:111], v[136:139], v[148:151], v[108:111]
	v_mfma_f32_16x16x32_bf16 v[28:31], v[124:127], v[156:159], v[28:31]
	v_mfma_f32_16x16x32_bf16 v[84:87], v[136:139], v[156:159], v[84:87]
	v_mfma_f32_16x16x32_bf16 v[116:119], v[124:127], v[164:167], v[116:119]
	v_mfma_f32_16x16x32_bf16 v[112:115], v[136:139], v[164:167], v[112:115]
	v_mfma_f32_16x16x32_bf16 v[32:35], v[124:127], v[172:175], v[32:35]
	v_mfma_f32_16x16x32_bf16 v[96:99], v[136:139], v[172:175], v[96:99]
	v_mfma_f32_16x16x32_bf16 v[120:123], v[128:131], v[152:155], v[120:123]
	v_mfma_f32_16x16x32_bf16 v[108:111], v[140:143], v[152:155], v[108:111]
	v_mfma_f32_16x16x32_bf16 v[28:31], v[128:131], v[160:163], v[28:31]
	v_mfma_f32_16x16x32_bf16 v[84:87], v[140:143], v[160:163], v[84:87]
	v_mfma_f32_16x16x32_bf16 v[116:119], v[128:131], v[168:171], v[116:119]
	v_mfma_f32_16x16x32_bf16 v[112:115], v[140:143], v[168:171], v[112:115]
	v_mfma_f32_16x16x32_bf16 v[32:35], v[128:131], v[192:195], v[32:35]
	v_mfma_f32_16x16x32_bf16 v[96:99], v[140:143], v[192:195], v[96:99]
	s_barrier
	s_add_u32 s24, s24, 0x80080
	s_addc_u32 s25, s25, 0
	s_add_i32 s28, s28, s35
	v_lshl_add_u64 v[2:3], s[24:25], 0, v[178:179]
	s_mov_b32 m0, s28
	s_nop 0
	global_load_lds_dwordx4 v[2:3], off
	v_lshl_add_u64 v[2:3], s[24:25], 0, v[182:183]
	s_add_i32 m0, s28, 0x2000
	s_nop 0
	global_load_lds_dwordx4 v[2:3], off
	s_waitcnt vmcnt(6)
	s_barrier
	v_mfma_f32_16x16x32_bf16 v[36:39], v[198:201], v[148:151], v[36:39]
	v_mfma_f32_16x16x32_bf16 v[80:83], v[206:209], v[148:151], v[80:83]
	v_mfma_f32_16x16x32_bf16 v[40:43], v[198:201], v[156:159], v[40:43]
	v_mfma_f32_16x16x32_bf16 v[88:91], v[206:209], v[156:159], v[88:91]
	v_mfma_f32_16x16x32_bf16 v[44:47], v[198:201], v[164:167], v[44:47]
	v_mfma_f32_16x16x32_bf16 v[92:95], v[206:209], v[164:167], v[92:95]
	v_mfma_f32_16x16x32_bf16 v[48:51], v[198:201], v[172:175], v[48:51]
	v_mfma_f32_16x16x32_bf16 v[52:55], v[206:209], v[172:175], v[52:55]
	v_mfma_f32_16x16x32_bf16 v[36:39], v[202:205], v[152:155], v[36:39]
	v_mfma_f32_16x16x32_bf16 v[80:83], v[210:213], v[152:155], v[80:83]
	v_mfma_f32_16x16x32_bf16 v[40:43], v[202:205], v[160:163], v[40:43]
	v_mfma_f32_16x16x32_bf16 v[88:91], v[210:213], v[160:163], v[88:91]
	v_mfma_f32_16x16x32_bf16 v[44:47], v[202:205], v[168:171], v[44:47]
	v_mfma_f32_16x16x32_bf16 v[92:95], v[210:213], v[168:171], v[92:95]
	v_mfma_f32_16x16x32_bf16 v[48:51], v[202:205], v[192:195], v[48:51]
	v_mfma_f32_16x16x32_bf16 v[52:55], v[210:213], v[192:195], v[52:55]
	s_add_i32 s33, s33, 2
	s_add_u32 s26, s26, 0x100
	s_addc_u32 s27, s27, 0
	s_add_u32 s1, s1, 0x100
	s_addc_u32 s11, s11, 0
	s_cmp_gt_u32 s33, 29
	s_barrier
	s_cbranch_scc0 .LBB0_158
	v_mov_b32_e32 v2, v247
	s_bitcmp1_b32 s9, 0
	v_lshl_add_u32 v188, s10, 8, v197
	s_cselect_b64 s[10:11], -1, 0
	v_ashrrev_i32_e32 v3, 31, v2
	v_lshl_or_b32 v168, s0, 8, v246
	v_lshl_add_u64 v[2:3], v[2:3], 2, s[16:17]
	s_mov_b64 s[0:1], -1
	s_and_b64 vcc, exec, s[10:11]
	s_cbranch_vccz .LBB0_173
	s_cmp_lg_u32 s9, 3
	v_ashrrev_i32_e32 v189, 31, v188
	s_cbranch_scc0 .LBB0_162
	v_readlane_b32 s0, v253, 19
	v_readlane_b32 s1, v253, 20
	v_ashrrev_i32_e32 v169, 31, v168
	v_lshlrev_b64 v[170:171], 1, v[168:169]
	v_mov_b64_e32 v[124:125], s[0:1]
	v_mad_i64_i32 v[126:127], s[0:1], v188, s74, v[124:125]
	v_lshl_add_u64 v[126:127], v[126:127], 0, v[170:171]
	s_mov_b64 s[10:11], 0x6000
	v_lshl_add_u64 v[128:129], v[126:127], 0, s[10:11]
	v_add_co_u32_e32 v126, vcc, 0x6000, v126
	v_or_b32_e32 v226, 16, v188
	s_nop 0
	v_addc_co_u32_e32 v127, vcc, 0, v127, vcc
	global_load_dwordx4 v[192:195], v[126:127], off
	global_load_dwordx4 v[202:205], v[128:129], off offset:256
	v_mad_i64_i32 v[126:127], s[0:1], v226, s74, v[124:125]
	v_lshl_add_u64 v[126:127], v[126:127], 0, v[170:171]
	v_lshl_add_u64 v[128:129], v[126:127], 0, s[10:11]
	v_add_co_u32_e32 v126, vcc, 0x6000, v126
	v_or_b32_e32 v228, 32, v188
	s_nop 0
	v_addc_co_u32_e32 v127, vcc, 0, v127, vcc
	global_load_dwordx4 v[206:209], v[126:127], off
	global_load_dwordx4 v[210:213], v[128:129], off offset:256
	v_mad_i64_i32 v[126:127], s[0:1], v228, s74, v[124:125]
	v_lshl_add_u64 v[126:127], v[126:127], 0, v[170:171]
	v_lshl_add_u64 v[128:129], v[126:127], 0, s[10:11]
	v_add_co_u32_e32 v126, vcc, 0x6000, v126
	v_or_b32_e32 v230, 48, v188
	s_nop 0
	v_addc_co_u32_e32 v127, vcc, 0, v127, vcc
	global_load_dwordx4 v[214:217], v[126:127], off
	global_load_dwordx4 v[218:221], v[128:129], off offset:256
	v_mad_i64_i32 v[126:127], s[0:1], v230, s74, v[124:125]
	v_lshl_add_u64 v[126:127], v[126:127], 0, v[170:171]
	v_lshl_add_u64 v[128:129], v[126:127], 0, s[10:11]
	v_add_co_u32_e32 v126, vcc, 0x6000, v126
	v_add_u32_e32 v200, 0x80, v188
	s_nop 0
	v_addc_co_u32_e32 v127, vcc, 0, v127, vcc
	global_load_dwordx4 v[222:225], v[126:127], off
	global_load_dwordx4 v[164:167], v[128:129], off offset:256
	v_mad_i64_i32 v[126:127], s[0:1], v200, s74, v[124:125]
	v_lshl_add_u64 v[126:127], v[126:127], 0, v[170:171]
	v_lshl_add_u64 v[128:129], v[126:127], 0, s[10:11]
	v_add_co_u32_e32 v126, vcc, 0x6000, v126
	v_add_u32_e32 v198, 0x90, v188
	s_nop 0
	v_addc_co_u32_e32 v127, vcc, 0, v127, vcc
	global_load_dwordx4 v[160:163], v[126:127], off
	global_load_dwordx4 v[156:159], v[128:129], off offset:256
	v_mad_i64_i32 v[126:127], s[0:1], v198, s74, v[124:125]
	v_lshl_add_u64 v[126:127], v[126:127], 0, v[170:171]
	v_lshl_add_u64 v[128:129], v[126:127], 0, s[10:11]
	v_add_co_u32_e32 v126, vcc, 0x6000, v126
	v_add_u32_e32 v174, 0xa0, v188
	s_nop 0
	v_addc_co_u32_e32 v127, vcc, 0, v127, vcc
	global_load_dwordx4 v[152:155], v[126:127], off
	global_load_dwordx4 v[148:151], v[128:129], off offset:256
	v_mad_i64_i32 v[126:127], s[0:1], v174, s74, v[124:125]
	v_lshl_add_u64 v[126:127], v[126:127], 0, v[170:171]
	v_add_u32_e32 v172, 0xb0, v188
	v_lshl_add_u64 v[128:129], v[126:127], 0, s[10:11]
	v_add_co_u32_e32 v126, vcc, 0x6000, v126
	v_mad_i64_i32 v[124:125], s[0:1], v172, s74, v[124:125]
	s_nop 0
	v_addc_co_u32_e32 v127, vcc, 0, v127, vcc
	v_lshl_add_u64 v[124:125], v[124:125], 0, v[170:171]
	global_load_dwordx4 v[140:143], v[126:127], off
	global_load_dwordx4 v[136:139], v[128:129], off offset:256
	v_lshl_add_u64 v[126:127], v[124:125], 0, s[10:11]
	v_add_co_u32_e32 v124, vcc, 0x6000, v124
	v_readlane_b32 s0, v253, 17
	s_nop 0
	v_addc_co_u32_e32 v125, vcc, 0, v125, vcc
	global_load_dwordx4 v[128:131], v[124:125], off
	s_nop 0
	global_load_dwordx4 v[124:127], v[126:127], off offset:256
	v_lshlrev_b64 v[232:233], 12, v[188:189]
	v_readlane_b32 s1, v253, 18
	v_ashrrev_i32_e32 v227, 31, v226
	v_ashrrev_i32_e32 v229, 31, v228
	v_lshl_add_u64 v[232:233], s[0:1], 0, v[232:233]
	v_lshl_add_u64 v[232:233], v[232:233], 0, v[170:171]
	v_ashrrev_i32_e32 v231, 31, v230
	v_ashrrev_i32_e32 v201, 31, v200
	s_waitcnt vmcnt(0)
; __device__ __forceinline__ unsigned pk_bf16(float lo, float hi) { unsigned r; asm volatile("v_cvt_pk_bf16_f32 %0, %1, %2" : "=v"(r) : "v"(lo), "v"(hi)); return r; }
; __device__ __forceinline__ float bf_lo(unsigned u) { return __uint_as_float(u << 16); }
; __device__ __forceinline__ float bf_hi(unsigned u) { return __uint_as_float(u & 0xffff0000u); }
;     __device__ __forceinline__ bool operator()(f32x4 (&acc)[2][2][4][2], const Unit& un, int wr, int wc, int fr, int fq) const {
;     ...
; #pragma unroll
;         for (int ai = 0; ai < 2; ++ai)
; #pragma unroll
;             for (int m = 0; m < 4; ++m) {
;                 const int r = rbase + ai * 128 + m * 16;
; #pragma unroll
;                 for (int bj = 0; bj < 2; ++bj) {
;                     const u32x4 b = gr[ai][m][bj];
;                     const f32x4 v0 = acc[ai][bj][m][0], v1 = acc[ai][bj][m][1];
;                     u32x4 w; w.x = pk_bf16(v0[0] * bf_lo(b.x), v0[1] * bf_hi(b.x)); w.y = pk_bf16(v0[2] * bf_lo(b.y), v0[3] * bf_hi(b.y));
;                     w.z = pk_bf16(v1[0] * bf_lo(b.z), v1[1] * bf_hi(b.z)); w.w = pk_bf16(v1[2] * bf_lo(b.w), v1[3] * bf_hi(b.w));
;                     *(u32x4*)(merged + (size_t)r * D + c0 + bj * 128) = w;
;                 }
;             }
	v_lshlrev_b32_e32 v0, 16, v192
	v_mul_f32_e32 v0, v144, v0
	v_and_b32_e32 v169, 0xffff0000, v192
	v_mul_f32_e32 v169, v145, v169
	v_cvt_pk_bf16_f32 v192, v0, v169
	v_lshlrev_b32_e32 v0, 16, v193
	v_mul_f32_e32 v0, v146, v0
	v_and_b32_e32 v169, 0xffff0000, v193
	v_mul_f32_e32 v169, v147, v169
	v_cvt_pk_bf16_f32 v193, v0, v169
	v_lshlrev_b32_e32 v0, 16, v194
	v_mul_f32_e32 v0, v100, v0
	v_and_b32_e32 v169, 0xffff0000, v194
	v_mul_f32_e32 v169, v101, v169
	v_cvt_pk_bf16_f32 v194, v0, v169
	v_lshlrev_b32_e32 v0, 16, v195
	v_mul_f32_e32 v0, v102, v0
	v_and_b32_e32 v169, 0xffff0000, v195
	v_mul_f32_e32 v169, v103, v169
	v_cvt_pk_bf16_f32 v195, v0, v169
	v_lshlrev_b32_e32 v0, 16, v202
	v_mul_f32_e32 v0, v12, v0
	v_and_b32_e32 v169, 0xffff0000, v202
	global_store_dwordx4 v[232:233], v[192:195], off
	v_mul_f32_e32 v169, v13, v169
	v_ashrrev_i32_e32 v199, 31, v198
	v_cvt_pk_bf16_f32 v192, v0, v169
	v_lshlrev_b32_e32 v0, 16, v203
	v_mul_f32_e32 v0, v14, v0
	v_and_b32_e32 v169, 0xffff0000, v203
	v_mul_f32_e32 v169, v15, v169
	v_cvt_pk_bf16_f32 v193, v0, v169
	v_lshlrev_b32_e32 v0, 16, v204
	v_mul_f32_e32 v0, v56, v0
	v_and_b32_e32 v169, 0xffff0000, v204
	v_mul_f32_e32 v169, v57, v169
	v_cvt_pk_bf16_f32 v194, v0, v169
	v_lshlrev_b32_e32 v0, 16, v205
	v_mul_f32_e32 v0, v58, v0
	v_and_b32_e32 v169, 0xffff0000, v205
	v_mul_f32_e32 v169, v59, v169
	v_cvt_pk_bf16_f32 v195, v0, v169
	v_lshlrev_b32_e32 v0, 16, v206
	v_mul_f32_e32 v0, v4, v0
	v_and_b32_e32 v169, 0xffff0000, v206
	global_store_dwordx4 v[232:233], v[192:195], off offset:256
	v_mul_f32_e32 v169, v5, v169
	v_lshlrev_b64 v[202:203], 12, v[226:227]
	v_cvt_pk_bf16_f32 v192, v0, v169
	v_lshlrev_b32_e32 v0, 16, v207
	v_mul_f32_e32 v0, v6, v0
	v_and_b32_e32 v169, 0xffff0000, v207
	v_mul_f32_e32 v169, v7, v169
	v_cvt_pk_bf16_f32 v193, v0, v169
	v_lshlrev_b32_e32 v0, 16, v208
	v_mul_f32_e32 v0, v60, v0
	v_and_b32_e32 v169, 0xffff0000, v208
	v_mul_f32_e32 v169, v61, v169
	v_cvt_pk_bf16_f32 v194, v0, v169
	v_lshlrev_b32_e32 v0, 16, v209
	v_mul_f32_e32 v0, v62, v0
	v_and_b32_e32 v169, 0xffff0000, v209
	v_mul_f32_e32 v169, v63, v169
	v_cvt_pk_bf16_f32 v195, v0, v169
	v_lshl_add_u64 v[202:203], s[0:1], 0, v[202:203]
	v_lshlrev_b32_e32 v0, 16, v210
	v_lshl_add_u64 v[202:203], v[202:203], 0, v[170:171]
	v_mul_f32_e32 v0, v16, v0
	v_and_b32_e32 v169, 0xffff0000, v210
	global_store_dwordx4 v[202:203], v[192:195], off
	v_mul_f32_e32 v169, v17, v169
	v_ashrrev_i32_e32 v175, 31, v174
	v_cvt_pk_bf16_f32 v192, v0, v169
	v_lshlrev_b32_e32 v0, 16, v211
	v_mul_f32_e32 v0, v18, v0
	v_and_b32_e32 v169, 0xffff0000, v211
	v_mul_f32_e32 v169, v19, v169
	v_cvt_pk_bf16_f32 v193, v0, v169
	v_lshlrev_b32_e32 v0, 16, v212
	v_mul_f32_e32 v0, v64, v0
	v_and_b32_e32 v169, 0xffff0000, v212
	v_mul_f32_e32 v169, v65, v169
	v_cvt_pk_bf16_f32 v194, v0, v169
	v_lshlrev_b32_e32 v0, 16, v213
	v_mul_f32_e32 v0, v66, v0
	v_and_b32_e32 v169, 0xffff0000, v213
	v_mul_f32_e32 v169, v67, v169
	v_cvt_pk_bf16_f32 v195, v0, v169
	v_lshlrev_b32_e32 v0, 16, v214
	v_mul_f32_e32 v0, v132, v0
	v_and_b32_e32 v169, 0xffff0000, v214
	global_store_dwordx4 v[202:203], v[192:195], off offset:256
	v_mul_f32_e32 v169, v133, v169
	v_lshlrev_b64 v[202:203], 12, v[228:229]
	v_cvt_pk_bf16_f32 v192, v0, v169
	v_lshlrev_b32_e32 v0, 16, v215
	v_mul_f32_e32 v0, v134, v0
	v_and_b32_e32 v169, 0xffff0000, v215
	v_mul_f32_e32 v169, v135, v169
	v_cvt_pk_bf16_f32 v193, v0, v169
	v_lshlrev_b32_e32 v0, 16, v216
	v_mul_f32_e32 v0, v104, v0
	v_and_b32_e32 v169, 0xffff0000, v216
	v_mul_f32_e32 v169, v105, v169
	v_cvt_pk_bf16_f32 v194, v0, v169
	v_lshlrev_b32_e32 v0, 16, v217
	v_mul_f32_e32 v0, v106, v0
	v_and_b32_e32 v169, 0xffff0000, v217
	v_mul_f32_e32 v169, v107, v169
	v_cvt_pk_bf16_f32 v195, v0, v169
	v_lshl_add_u64 v[202:203], s[0:1], 0, v[202:203]
	v_lshlrev_b32_e32 v0, 16, v218
	v_lshl_add_u64 v[202:203], v[202:203], 0, v[170:171]
	v_mul_f32_e32 v0, v20, v0
	v_and_b32_e32 v169, 0xffff0000, v218
	global_store_dwordx4 v[202:203], v[192:195], off
	v_mul_f32_e32 v169, v21, v169
	v_ashrrev_i32_e32 v173, 31, v172
	v_cvt_pk_bf16_f32 v192, v0, v169
	v_lshlrev_b32_e32 v0, 16, v219
	v_mul_f32_e32 v0, v22, v0
	v_and_b32_e32 v169, 0xffff0000, v219
	v_mul_f32_e32 v169, v23, v169
	v_cvt_pk_bf16_f32 v193, v0, v169
	v_lshlrev_b32_e32 v0, 16, v220
	v_mul_f32_e32 v0, v68, v0
	v_and_b32_e32 v169, 0xffff0000, v220
	v_mul_f32_e32 v169, v69, v169
	v_cvt_pk_bf16_f32 v194, v0, v169
	v_lshlrev_b32_e32 v0, 16, v221
	v_mul_f32_e32 v0, v70, v0
	v_and_b32_e32 v169, 0xffff0000, v221
	v_mul_f32_e32 v169, v71, v169
	v_cvt_pk_bf16_f32 v195, v0, v169
	v_lshlrev_b32_e32 v0, 16, v222
	v_mul_f32_e32 v0, v8, v0
	v_and_b32_e32 v169, 0xffff0000, v222
	global_store_dwordx4 v[202:203], v[192:195], off offset:256
	v_mul_f32_e32 v169, v9, v169
	v_lshlrev_b64 v[202:203], 12, v[230:231]
	v_cvt_pk_bf16_f32 v192, v0, v169
	v_lshlrev_b32_e32 v0, 16, v223
	v_mul_f32_e32 v0, v10, v0
	v_and_b32_e32 v169, 0xffff0000, v223
	v_mul_f32_e32 v169, v11, v169
	v_cvt_pk_bf16_f32 v193, v0, v169
	v_lshlrev_b32_e32 v0, 16, v224
	v_mul_f32_e32 v0, v72, v0
	v_and_b32_e32 v169, 0xffff0000, v224
	v_mul_f32_e32 v169, v73, v169
	v_cvt_pk_bf16_f32 v194, v0, v169
	v_lshlrev_b32_e32 v0, 16, v225
	v_mul_f32_e32 v0, v74, v0
	v_and_b32_e32 v169, 0xffff0000, v225
	v_mul_f32_e32 v169, v75, v169
	v_cvt_pk_bf16_f32 v195, v0, v169
	v_lshl_add_u64 v[202:203], s[0:1], 0, v[202:203]
	v_lshlrev_b32_e32 v0, 16, v164
	v_and_b32_e32 v164, 0xffff0000, v164
	v_lshl_add_u64 v[202:203], v[202:203], 0, v[170:171]
	v_mul_f32_e32 v0, v24, v0
	v_mul_f32_e32 v164, v25, v164
	global_store_dwordx4 v[202:203], v[192:195], off
	v_cvt_pk_bf16_f32 v164, v0, v164
; __device__ __forceinline__ unsigned pk_bf16(float lo, float hi) { unsigned r; asm volatile("v_cvt_pk_bf16_f32 %0, %1, %2" : "=v"(r) : "v"(lo), "v"(hi)); return r; }
; __device__ __forceinline__ float bf_lo(unsigned u) { return __uint_as_float(u << 16); }
; __device__ __forceinline__ float bf_hi(unsigned u) { return __uint_as_float(u & 0xffff0000u); }
;     __device__ __forceinline__ bool operator()(f32x4 (&acc)[2][2][4][2], const Unit& un, int wr, int wc, int fr, int fq) const {
;     ...
; #pragma unroll
;         for (int ai = 0; ai < 2; ++ai)
; #pragma unroll
;             for (int m = 0; m < 4; ++m) {
;                 const int r = rbase + ai * 128 + m * 16;
; #pragma unroll
;                 for (int bj = 0; bj < 2; ++bj) {
;                     const u32x4 b = gr[ai][m][bj];
;                     const f32x4 v0 = acc[ai][bj][m][0], v1 = acc[ai][bj][m][1];
;                     u32x4 w; w.x = pk_bf16(v0[0] * bf_lo(b.x), v0[1] * bf_hi(b.x)); w.y = pk_bf16(v0[2] * bf_lo(b.y), v0[3] * bf_hi(b.y));
;                     w.z = pk_bf16(v1[0] * bf_lo(b.z), v1[1] * bf_hi(b.z)); w.w = pk_bf16(v1[2] * bf_lo(b.w), v1[3] * bf_hi(b.w));
;                     *(u32x4*)(merged + (size_t)r * D + c0 + bj * 128) = w;
;                 }
;             }
	v_lshlrev_b32_e32 v0, 16, v165
	v_and_b32_e32 v165, 0xffff0000, v165
	v_mul_f32_e32 v0, v26, v0
	v_mul_f32_e32 v165, v27, v165
	v_cvt_pk_bf16_f32 v165, v0, v165
	v_lshlrev_b32_e32 v0, 16, v166
	v_and_b32_e32 v166, 0xffff0000, v166
	v_mul_f32_e32 v0, v76, v0
	v_mul_f32_e32 v166, v77, v166
	v_cvt_pk_bf16_f32 v166, v0, v166
	v_lshlrev_b32_e32 v0, 16, v167
	v_and_b32_e32 v167, 0xffff0000, v167
	v_mul_f32_e32 v0, v78, v0
	v_mul_f32_e32 v167, v79, v167
	v_cvt_pk_bf16_f32 v167, v0, v167
	v_lshlrev_b32_e32 v0, 16, v160
	v_and_b32_e32 v160, 0xffff0000, v160
	v_mul_f32_e32 v0, v120, v0
	v_mul_f32_e32 v160, v121, v160
	global_store_dwordx4 v[202:203], v[164:167], off offset:256
	v_cvt_pk_bf16_f32 v160, v0, v160
	v_lshlrev_b32_e32 v0, 16, v161
	v_and_b32_e32 v161, 0xffff0000, v161
	v_mul_f32_e32 v0, v122, v0
	v_mul_f32_e32 v161, v123, v161
	v_cvt_pk_bf16_f32 v161, v0, v161
	v_lshlrev_b32_e32 v0, 16, v162
	v_and_b32_e32 v162, 0xffff0000, v162
	v_mul_f32_e32 v0, v108, v0
	v_mul_f32_e32 v162, v109, v162
	v_cvt_pk_bf16_f32 v162, v0, v162
	v_lshlrev_b32_e32 v0, 16, v163
	v_and_b32_e32 v163, 0xffff0000, v163
	v_lshlrev_b64 v[164:165], 12, v[200:201]
	v_mul_f32_e32 v0, v110, v0
	v_mul_f32_e32 v163, v111, v163
	v_cvt_pk_bf16_f32 v163, v0, v163
	v_lshl_add_u64 v[164:165], s[0:1], 0, v[164:165]
	v_lshlrev_b32_e32 v0, 16, v156
	v_and_b32_e32 v156, 0xffff0000, v156
	v_lshl_add_u64 v[164:165], v[164:165], 0, v[170:171]
	v_mul_f32_e32 v0, v36, v0
	v_mul_f32_e32 v156, v37, v156
	global_store_dwordx4 v[164:165], v[160:163], off
	v_cvt_pk_bf16_f32 v156, v0, v156
	v_lshlrev_b32_e32 v0, 16, v157
	v_and_b32_e32 v157, 0xffff0000, v157
	v_mul_f32_e32 v0, v38, v0
	v_mul_f32_e32 v157, v39, v157
	v_cvt_pk_bf16_f32 v157, v0, v157
	v_lshlrev_b32_e32 v0, 16, v158
	v_and_b32_e32 v158, 0xffff0000, v158
	v_mul_f32_e32 v0, v80, v0
	v_mul_f32_e32 v158, v81, v158
	v_cvt_pk_bf16_f32 v158, v0, v158
	v_lshlrev_b32_e32 v0, 16, v159
	v_and_b32_e32 v159, 0xffff0000, v159
	v_mul_f32_e32 v0, v82, v0
	v_mul_f32_e32 v159, v83, v159
	v_cvt_pk_bf16_f32 v159, v0, v159
	v_lshlrev_b32_e32 v0, 16, v152
	v_and_b32_e32 v152, 0xffff0000, v152
	v_mul_f32_e32 v0, v28, v0
	v_mul_f32_e32 v152, v29, v152
	global_store_dwordx4 v[164:165], v[156:159], off offset:256
	v_cvt_pk_bf16_f32 v152, v0, v152
	v_lshlrev_b32_e32 v0, 16, v153
	v_and_b32_e32 v153, 0xffff0000, v153
	v_mul_f32_e32 v0, v30, v0
	v_mul_f32_e32 v153, v31, v153
	v_cvt_pk_bf16_f32 v153, v0, v153
	v_lshlrev_b32_e32 v0, 16, v154
	v_and_b32_e32 v154, 0xffff0000, v154
	v_mul_f32_e32 v0, v84, v0
	v_mul_f32_e32 v154, v85, v154
	v_cvt_pk_bf16_f32 v154, v0, v154
	v_lshlrev_b32_e32 v0, 16, v155
	v_and_b32_e32 v155, 0xffff0000, v155
	v_lshlrev_b64 v[156:157], 12, v[198:199]
	v_mul_f32_e32 v0, v86, v0
	v_mul_f32_e32 v155, v87, v155
	v_cvt_pk_bf16_f32 v155, v0, v155
	v_lshl_add_u64 v[156:157], s[0:1], 0, v[156:157]
	v_lshlrev_b32_e32 v0, 16, v148
	v_and_b32_e32 v148, 0xffff0000, v148
	v_lshl_add_u64 v[156:157], v[156:157], 0, v[170:171]
	v_mul_f32_e32 v0, v40, v0
	v_mul_f32_e32 v148, v41, v148
	global_store_dwordx4 v[156:157], v[152:155], off
	v_cvt_pk_bf16_f32 v148, v0, v148
	v_lshlrev_b32_e32 v0, 16, v149
	v_and_b32_e32 v149, 0xffff0000, v149
	v_mul_f32_e32 v0, v42, v0
	v_mul_f32_e32 v149, v43, v149
	v_cvt_pk_bf16_f32 v149, v0, v149
	v_lshlrev_b32_e32 v0, 16, v150
	v_and_b32_e32 v150, 0xffff0000, v150
	v_mul_f32_e32 v0, v88, v0
	v_mul_f32_e32 v150, v89, v150
	v_cvt_pk_bf16_f32 v150, v0, v150
	v_lshlrev_b32_e32 v0, 16, v151
	v_and_b32_e32 v151, 0xffff0000, v151
	v_mul_f32_e32 v0, v90, v0
	v_mul_f32_e32 v151, v91, v151
	v_cvt_pk_bf16_f32 v151, v0, v151
	v_lshlrev_b32_e32 v0, 16, v140
	v_and_b32_e32 v140, 0xffff0000, v140
	v_mul_f32_e32 v0, v116, v0
	v_mul_f32_e32 v140, v117, v140
	global_store_dwordx4 v[156:157], v[148:151], off offset:256
	v_cvt_pk_bf16_f32 v140, v0, v140
	v_lshlrev_b32_e32 v0, 16, v141
	v_and_b32_e32 v141, 0xffff0000, v141
	v_mul_f32_e32 v0, v118, v0
	v_mul_f32_e32 v141, v119, v141
	v_cvt_pk_bf16_f32 v141, v0, v141
	v_lshlrev_b32_e32 v0, 16, v142
	v_and_b32_e32 v142, 0xffff0000, v142
	v_mul_f32_e32 v0, v112, v0
	v_mul_f32_e32 v142, v113, v142
	v_cvt_pk_bf16_f32 v142, v0, v142
	v_lshlrev_b32_e32 v0, 16, v143
	v_and_b32_e32 v143, 0xffff0000, v143
	v_lshlrev_b64 v[148:149], 12, v[174:175]
	v_mul_f32_e32 v0, v114, v0
	v_mul_f32_e32 v143, v115, v143
	v_cvt_pk_bf16_f32 v143, v0, v143
	v_lshl_add_u64 v[148:149], s[0:1], 0, v[148:149]
	v_lshlrev_b32_e32 v0, 16, v136
	v_and_b32_e32 v136, 0xffff0000, v136
	v_lshl_add_u64 v[148:149], v[148:149], 0, v[170:171]
	v_mul_f32_e32 v0, v44, v0
	v_mul_f32_e32 v136, v45, v136
	global_store_dwordx4 v[148:149], v[140:143], off
	v_cvt_pk_bf16_f32 v136, v0, v136
	v_lshlrev_b32_e32 v0, 16, v137
	v_and_b32_e32 v137, 0xffff0000, v137
	v_mul_f32_e32 v0, v46, v0
	v_mul_f32_e32 v137, v47, v137
	v_cvt_pk_bf16_f32 v137, v0, v137
	v_lshlrev_b32_e32 v0, 16, v138
	v_and_b32_e32 v138, 0xffff0000, v138
	v_mul_f32_e32 v0, v92, v0
	v_mul_f32_e32 v138, v93, v138
	v_cvt_pk_bf16_f32 v138, v0, v138
	v_lshlrev_b32_e32 v0, 16, v139
	v_and_b32_e32 v139, 0xffff0000, v139
	v_mul_f32_e32 v0, v94, v0
	v_mul_f32_e32 v139, v95, v139
	v_cvt_pk_bf16_f32 v139, v0, v139
	v_lshlrev_b32_e32 v0, 16, v128
	v_and_b32_e32 v128, 0xffff0000, v128
	v_mul_f32_e32 v0, v32, v0
	v_mul_f32_e32 v128, v33, v128
	global_store_dwordx4 v[148:149], v[136:139], off offset:256
	v_cvt_pk_bf16_f32 v128, v0, v128
	v_lshlrev_b32_e32 v0, 16, v129
	v_and_b32_e32 v129, 0xffff0000, v129
	v_mul_f32_e32 v0, v34, v0
	v_mul_f32_e32 v129, v35, v129
	v_cvt_pk_bf16_f32 v129, v0, v129
	v_lshlrev_b32_e32 v0, 16, v130
	v_and_b32_e32 v130, 0xffff0000, v130
	v_mul_f32_e32 v0, v96, v0
	v_mul_f32_e32 v130, v97, v130
	v_cvt_pk_bf16_f32 v130, v0, v130
	v_lshlrev_b32_e32 v0, 16, v131
	v_and_b32_e32 v131, 0xffff0000, v131
	v_lshlrev_b64 v[136:137], 12, v[172:173]
	v_mul_f32_e32 v0, v98, v0
	v_mul_f32_e32 v131, v99, v131
	v_cvt_pk_bf16_f32 v131, v0, v131
	v_lshl_add_u64 v[136:137], s[0:1], 0, v[136:137]
	v_lshlrev_b32_e32 v0, 16, v124
	v_and_b32_e32 v124, 0xffff0000, v124
	v_lshl_add_u64 v[136:137], v[136:137], 0, v[170:171]
	v_mul_f32_e32 v0, v48, v0
	v_mul_f32_e32 v124, v49, v124
	global_store_dwordx4 v[136:137], v[128:131], off
	v_cvt_pk_bf16_f32 v124, v0, v124
	v_lshlrev_b32_e32 v0, 16, v125
	v_and_b32_e32 v125, 0xffff0000, v125
	v_mul_f32_e32 v0, v50, v0
	v_mul_f32_e32 v125, v51, v125
	v_cvt_pk_bf16_f32 v125, v0, v125
	v_lshlrev_b32_e32 v0, 16, v126
	v_and_b32_e32 v126, 0xffff0000, v126
	v_mul_f32_e32 v0, v52, v0
	v_mul_f32_e32 v126, v53, v126
	v_cvt_pk_bf16_f32 v126, v0, v126
	v_lshlrev_b32_e32 v0, 16, v127
	v_and_b32_e32 v127, 0xffff0000, v127
	v_mul_f32_e32 v127, v55, v127
	v_mul_f32_e32 v0, v54, v0
	v_cvt_pk_bf16_f32 v127, v0, v127
	global_store_dwordx4 v[136:137], v[124:127], off offset:256
	s_mov_b64 s[0:1], 0

; #define G_STAGE(bufoff, gbase, voff) do { _Pragma("unroll") for (int _i = 0; _i < 2; ++_i) \
;         __builtin_amdgcn_global_load_lds((const unsigned*)((const char*)(gbase) + (voff)[_i]), (LAS unsigned*)(lds + (bufoff) + ldsw + _i * 8192), 16, 0, 0); } while (0)
; #define G_LDA(dst, b, h) do { _Pragma("unroll") for (int m = 0; m < 4; ++m) _Pragma("unroll") for (int k = 0; k < 2; ++k) dst[m][k] = *(const LAS bf16x8*)(lds + G_SA(b, h) + aoff + m * 2048 + k * 1024); } while (0)
; #define G_LDB(dst, b, h) do { _Pragma("unroll") for (int n = 0; n < 2; ++n) _Pragma("unroll") for (int k = 0; k < 2; ++k) dst[n][k] = *(const LAS bf16x8*)(lds + G_SB(b, h) + boff + n * 2048 + k * 1024); } while (0)
; #define G_MMA(ai, bj, At, Bt) do { __builtin_amdgcn_s_setprio(1); _Pragma("unroll") for (int m = 0; m < 4; ++m) _Pragma("unroll") for (int n = 0; n < 2; ++n) _Pragma("unroll") for (int k = 0; k < 2; ++k) \
;         acc[ai][bj][m][n] = __builtin_amdgcn_mfma_f32_16x16x32_bf16(Bt[n][k], At[m][k], acc[ai][bj][m][n], 0, 0, 0); __builtin_amdgcn_s_setprio(0); } while (0)
; #define G_WAIT_L(n) asm volatile("s_waitcnt lgkmcnt(" #n ")" ::: "memory")
; #define G_BAR __builtin_amdgcn_s_barrier()
; #define G_SCHED __builtin_amdgcn_sched_barrier(0)
; template <class Epi, class Sched>
; __device__ __forceinline__ void gemm_phase(LAS unsigned char* lds, const Sched& S, const Epi& E, const int K, const int lda, const int ldb, const int tid) {
;     ...
;             G_LDB(B0, 0, 0); G_SCHED; G_LDA(At, 0, 0); G_STAGE(G_SA(1, 1), a1 + hstepA, voffA);
;             G_WAIT_L(8); G_BAR; G_WAIT_L(0); G_MMA(0, 0, At, B0); G_BAR; G_SCHED;
;             G_LDB(B1, 0, 1); G_STAGE(G_SB(0, 0), b2, voffB);
;             G_BAR; G_WAIT_L(0); G_MMA(0, 1, At, B1); G_BAR;
;             G_LDA(At, 0, 1); G_STAGE(G_SA(0, 0), a2, voffA);
;             G_BAR; G_WAIT_L(0); G_MMA(1, 0, At, B0); G_BAR; G_SCHED;
.LBB0_292:
	s_add_u32 s18, s16, 0xfff80080
	s_addc_u32 s19, s17, -1
	s_add_i32 s37, 0, 0x10000
	v_add_u32_e32 v142, s37, v224
	ds_read_b128 v[130:133], v142
	ds_read_b128 v[134:137], v142 offset:1024
	ds_read_b128 v[138:141], v142 offset:2048
	ds_read_b128 v[142:145], v142 offset:3072
	s_cmp_eq_u32 s36, 4
	s_cselect_b32 s21, s9, s19
	s_cselect_b32 s20, s8, s18
	s_cselect_b32 s19, s13, s11
	s_cselect_b32 s18, s12, s1
	v_lshl_add_u64 v[178:179], s[16:17], 0, v[204:205]
	s_add_i32 m0, s15, 0xc000
	ds_read_b128 v[146:149], v226
	ds_read_b128 v[150:153], v226 offset:1024
	ds_read_b128 v[154:157], v226 offset:2048
	ds_read_b128 v[158:161], v226 offset:3072
	ds_read_b128 v[162:165], v226 offset:4096
	ds_read_b128 v[166:169], v226 offset:5120
	ds_read_b128 v[170:173], v226 offset:6144
	ds_read_b128 v[174:177], v226 offset:7168
	global_load_lds_dwordx4 v[178:179], off
	v_lshl_add_u64 v[178:179], s[16:17], 0, v[206:207]
	s_add_i32 m0, s15, 0xe000
	s_nop 0
	global_load_lds_dwordx4 v[178:179], off
	s_waitcnt lgkmcnt(8)
	s_barrier
	s_waitcnt lgkmcnt(0)
	s_waitcnt lgkmcnt(0)
	v_mfma_f32_16x16x32_bf16 v[126:129], v[130:133], v[146:149], v[126:129]
	v_mfma_f32_16x16x32_bf16 v[122:125], v[138:141], v[146:149], v[122:125]
	v_mfma_f32_16x16x32_bf16 v[114:117], v[130:133], v[154:157], v[114:117]
	v_mfma_f32_16x16x32_bf16 v[106:109], v[138:141], v[154:157], v[106:109]
	v_mfma_f32_16x16x32_bf16 v[98:101], v[130:133], v[162:165], v[98:101]
	v_mfma_f32_16x16x32_bf16 v[90:93], v[138:141], v[162:165], v[90:93]
	v_mfma_f32_16x16x32_bf16 v[82:85], v[130:133], v[170:173], v[82:85]
	v_mfma_f32_16x16x32_bf16 v[74:77], v[138:141], v[170:173], v[74:77]
	v_mfma_f32_16x16x32_bf16 v[126:129], v[134:137], v[150:153], v[126:129]
	v_mfma_f32_16x16x32_bf16 v[122:125], v[142:145], v[150:153], v[122:125]
	v_mfma_f32_16x16x32_bf16 v[114:117], v[134:137], v[158:161], v[114:117]
	v_mfma_f32_16x16x32_bf16 v[106:109], v[142:145], v[158:161], v[106:109]
	v_mfma_f32_16x16x32_bf16 v[98:101], v[134:137], v[166:169], v[98:101]
	v_mfma_f32_16x16x32_bf16 v[90:93], v[142:145], v[166:169], v[90:93]
	v_mfma_f32_16x16x32_bf16 v[82:85], v[134:137], v[174:177], v[82:85]
	v_mfma_f32_16x16x32_bf16 v[74:77], v[142:145], v[174:177], v[74:77]
	s_barrier
	s_add_i32 s40, 0, 0x14000
	v_add_u32_e32 v192, s40, v224
	s_add_i32 s37, s37, s26
	ds_read_b128 v[178:181], v192
	ds_read_b128 v[182:185], v192 offset:1024
	ds_read_b128 v[186:189], v192 offset:2048
	ds_read_b128 v[208:211], v192 offset:3072
	v_lshl_add_u64 v[192:193], s[18:19], 0, v[0:1]
	s_mov_b32 m0, s37
	v_lshl_add_u64 v[194:195], s[18:19], 0, v[198:199]
	global_load_lds_dwordx4 v[192:193], off
	s_add_i32 m0, s37, 0x2000
	s_nop 0
	global_load_lds_dwordx4 v[194:195], off
	s_barrier
	s_waitcnt lgkmcnt(0)
	s_waitcnt lgkmcnt(0)
	v_mfma_f32_16x16x32_bf16 v[118:121], v[178:181], v[146:149], v[118:121]
	v_mfma_f32_16x16x32_bf16 v[110:113], v[186:189], v[146:149], v[110:113]
	v_mfma_f32_16x16x32_bf16 v[102:105], v[178:181], v[154:157], v[102:105]
	v_mfma_f32_16x16x32_bf16 v[94:97], v[186:189], v[154:157], v[94:97]
	v_mfma_f32_16x16x32_bf16 v[86:89], v[178:181], v[162:165], v[86:89]
	v_mfma_f32_16x16x32_bf16 v[78:81], v[186:189], v[162:165], v[78:81]
	v_mfma_f32_16x16x32_bf16 v[70:73], v[178:181], v[170:173], v[70:73]
	v_mfma_f32_16x16x32_bf16 v[66:69], v[186:189], v[170:173], v[66:69]
	v_mfma_f32_16x16x32_bf16 v[118:121], v[182:185], v[150:153], v[118:121]
	v_mfma_f32_16x16x32_bf16 v[110:113], v[208:211], v[150:153], v[110:113]
	v_mfma_f32_16x16x32_bf16 v[102:105], v[182:185], v[158:161], v[102:105]
	v_mfma_f32_16x16x32_bf16 v[94:97], v[208:211], v[158:161], v[94:97]
	v_mfma_f32_16x16x32_bf16 v[86:89], v[182:185], v[166:169], v[86:89]
	v_mfma_f32_16x16x32_bf16 v[78:81], v[208:211], v[166:169], v[78:81]
	v_mfma_f32_16x16x32_bf16 v[70:73], v[182:185], v[174:177], v[70:73]
	v_mfma_f32_16x16x32_bf16 v[66:69], v[208:211], v[174:177], v[66:69]
	s_mov_b32 m0, s15
	v_lshl_add_u64 v[212:213], s[20:21], 0, v[202:203]
	s_barrier
	ds_read_b128 v[146:149], v226 offset:16384
	ds_read_b128 v[150:153], v226 offset:17408
	ds_read_b128 v[154:157], v226 offset:18432
	ds_read_b128 v[158:161], v226 offset:19456
	ds_read_b128 v[162:165], v226 offset:20480
	ds_read_b128 v[166:169], v226 offset:21504
	ds_read_b128 v[170:173], v226 offset:22528
	ds_read_b128 v[174:177], v226 offset:23552
	global_load_lds_dwordx4 v[212:213], off
	v_lshl_add_u64 v[214:215], s[20:21], 0, v[200:201]
	s_mov_b32 m0, s28
	s_nop 0
	global_load_lds_dwordx4 v[214:215], off
	s_barrier
	s_waitcnt lgkmcnt(0)
	s_waitcnt lgkmcnt(0)
	v_mfma_f32_16x16x32_bf16 v[62:65], v[130:133], v[146:149], v[62:65]
	v_mfma_f32_16x16x32_bf16 v[58:61], v[138:141], v[146:149], v[58:61]
	v_mfma_f32_16x16x32_bf16 v[50:53], v[130:133], v[154:157], v[50:53]
	v_mfma_f32_16x16x32_bf16 v[42:45], v[138:141], v[154:157], v[42:45]
	v_mfma_f32_16x16x32_bf16 v[34:37], v[130:133], v[162:165], v[34:37]
	v_mfma_f32_16x16x32_bf16 v[26:29], v[138:141], v[162:165], v[26:29]
	v_mfma_f32_16x16x32_bf16 v[18:21], v[130:133], v[170:173], v[18:21]
	v_mfma_f32_16x16x32_bf16 v[10:13], v[138:141], v[170:173], v[10:13]
	v_mfma_f32_16x16x32_bf16 v[62:65], v[134:137], v[150:153], v[62:65]
	v_mfma_f32_16x16x32_bf16 v[58:61], v[142:145], v[150:153], v[58:61]
	v_mfma_f32_16x16x32_bf16 v[50:53], v[134:137], v[158:161], v[50:53]
	v_mfma_f32_16x16x32_bf16 v[42:45], v[142:145], v[158:161], v[42:45]
	v_mfma_f32_16x16x32_bf16 v[34:37], v[134:137], v[166:169], v[34:37]
	v_mfma_f32_16x16x32_bf16 v[26:29], v[142:145], v[166:169], v[26:29]
	v_mfma_f32_16x16x32_bf16 v[18:21], v[134:137], v[174:177], v[18:21]
	v_mfma_f32_16x16x32_bf16 v[10:13], v[142:145], v[174:177], v[10:13]
	s_barrier
; #define G_STAGE(bufoff, gbase, voff) do { _Pragma("unroll") for (int _i = 0; _i < 2; ++_i) \
;         __builtin_amdgcn_global_load_lds((const unsigned*)((const char*)(gbase) + (voff)[_i]), (LAS unsigned*)(lds + (bufoff) + ldsw + _i * 8192), 16, 0, 0); } while (0)
; #define G_LDA(dst, b, h) do { _Pragma("unroll") for (int m = 0; m < 4; ++m) _Pragma("unroll") for (int k = 0; k < 2; ++k) dst[m][k] = *(const LAS bf16x8*)(lds + G_SA(b, h) + aoff + m * 2048 + k * 1024); } while (0)
; #define G_LDB(dst, b, h) do { _Pragma("unroll") for (int n = 0; n < 2; ++n) _Pragma("unroll") for (int k = 0; k < 2; ++k) dst[n][k] = *(const LAS bf16x8*)(lds + G_SB(b, h) + boff + n * 2048 + k * 1024); } while (0)
; #define G_MMA(ai, bj, At, Bt) do { __builtin_amdgcn_s_setprio(1); _Pragma("unroll") for (int m = 0; m < 4; ++m) _Pragma("unroll") for (int n = 0; n < 2; ++n) _Pragma("unroll") for (int k = 0; k < 2; ++k) \
;         acc[ai][bj][m][n] = __builtin_amdgcn_mfma_f32_16x16x32_bf16(Bt[n][k], At[m][k], acc[ai][bj][m][n], 0, 0, 0); __builtin_amdgcn_s_setprio(0); } while (0)
; #define G_WAIT_V(n) asm volatile("s_waitcnt vmcnt(" #n ")" ::: "memory")
; #define G_WAIT_L(n) asm volatile("s_waitcnt lgkmcnt(" #n ")" ::: "memory")
; #define G_BAR __builtin_amdgcn_s_barrier()
; #define G_SCHED __builtin_amdgcn_sched_barrier(0)
; template <class Epi, class Sched>
; __device__ __forceinline__ void gemm_phase(LAS unsigned char* lds, const Sched& S, const Epi& E, const int K, const int lda, const int ldb, const int tid) {
;     ...
;             G_STAGE(G_SB(0, 1), b2 + hstepB, voffB);
;             G_WAIT_V(6); G_BAR; G_MMA(1, 1, At, B1); G_BAR;
;             G_LDB(B0, 1, 0); G_SCHED; G_LDA(At, 1, 0); G_STAGE(G_SA(0, 1), a2 + hstepA, voffA);
;             G_WAIT_L(8); G_BAR; G_WAIT_L(0); G_MMA(0, 0, At, B0); G_BAR; G_SCHED;
;             G_LDB(B1, 1, 1); G_STAGE(G_SB(1, 0), b3, voffB);
;             G_BAR; G_WAIT_L(0); G_MMA(0, 1, At, B1); G_BAR;
;             G_LDA(At, 1, 1); G_STAGE(G_SA(1, 0), a3, voffA);
;             G_BAR; G_WAIT_L(0); G_MMA(1, 0, At, B0); G_BAR; G_SCHED;
	s_add_u32 s38, s18, 0x20000
	s_addc_u32 s39, s19, 0
	s_add_i32 s37, s40, s26
	v_lshl_add_u64 v[130:131], s[38:39], 0, v[0:1]
	s_mov_b32 m0, s37
	s_nop 0
	global_load_lds_dwordx4 v[130:131], off
	v_lshl_add_u64 v[130:131], s[38:39], 0, v[198:199]
	s_add_i32 m0, s37, 0x2000
	s_nop 0
	global_load_lds_dwordx4 v[130:131], off
	s_waitcnt vmcnt(6)
	s_barrier
	v_mfma_f32_16x16x32_bf16 v[54:57], v[178:181], v[146:149], v[54:57]
	v_mfma_f32_16x16x32_bf16 v[46:49], v[186:189], v[146:149], v[46:49]
	v_mfma_f32_16x16x32_bf16 v[38:41], v[178:181], v[154:157], v[38:41]
	v_mfma_f32_16x16x32_bf16 v[30:33], v[186:189], v[154:157], v[30:33]
	v_mfma_f32_16x16x32_bf16 v[22:25], v[178:181], v[162:165], v[22:25]
	v_mfma_f32_16x16x32_bf16 v[14:17], v[186:189], v[162:165], v[14:17]
	v_mfma_f32_16x16x32_bf16 v[6:9], v[178:181], v[170:173], v[6:9]
	v_mfma_f32_16x16x32_bf16 v[2:5], v[186:189], v[170:173], v[2:5]
	v_mfma_f32_16x16x32_bf16 v[54:57], v[182:185], v[150:153], v[54:57]
	v_mfma_f32_16x16x32_bf16 v[46:49], v[208:211], v[150:153], v[46:49]
	v_mfma_f32_16x16x32_bf16 v[38:41], v[182:185], v[158:161], v[38:41]
	v_mfma_f32_16x16x32_bf16 v[30:33], v[208:211], v[158:161], v[30:33]
	v_mfma_f32_16x16x32_bf16 v[22:25], v[182:185], v[166:169], v[22:25]
	v_mfma_f32_16x16x32_bf16 v[14:17], v[208:211], v[166:169], v[14:17]
	v_mfma_f32_16x16x32_bf16 v[6:9], v[182:185], v[174:177], v[6:9]
	v_mfma_f32_16x16x32_bf16 v[2:5], v[208:211], v[174:177], v[2:5]
	s_add_i32 s37, 0, 0x18000
	v_add_u32_e32 v142, s37, v224
	s_barrier
	ds_read_b128 v[130:133], v142
	ds_read_b128 v[134:137], v142 offset:1024
	ds_read_b128 v[138:141], v142 offset:2048
	ds_read_b128 v[142:145], v142 offset:3072
	s_add_u32 s20, s20, 0x80000
	s_addc_u32 s21, s21, 0
	s_mov_b32 m0, s29
	v_lshl_add_u64 v[178:179], s[20:21], 0, v[202:203]
	ds_read_b128 v[146:149], v226 offset:32768
	ds_read_b128 v[150:153], v226 offset:33792
	ds_read_b128 v[154:157], v226 offset:34816
	ds_read_b128 v[158:161], v226 offset:35840
	ds_read_b128 v[162:165], v226 offset:36864
	ds_read_b128 v[166:169], v226 offset:37888
	ds_read_b128 v[170:173], v226 offset:38912
	ds_read_b128 v[174:177], v226 offset:39936
	global_load_lds_dwordx4 v[178:179], off
	v_lshl_add_u64 v[178:179], s[20:21], 0, v[200:201]
	s_mov_b32 m0, s30
	s_nop 0
	global_load_lds_dwordx4 v[178:179], off
	s_waitcnt lgkmcnt(8)
	s_barrier
	s_waitcnt lgkmcnt(0)
	s_waitcnt lgkmcnt(0)
	v_mfma_f32_16x16x32_bf16 v[126:129], v[130:133], v[146:149], v[126:129]
	v_mfma_f32_16x16x32_bf16 v[122:125], v[138:141], v[146:149], v[122:125]
	v_mfma_f32_16x16x32_bf16 v[114:117], v[130:133], v[154:157], v[114:117]
	v_mfma_f32_16x16x32_bf16 v[106:109], v[138:141], v[154:157], v[106:109]
	v_mfma_f32_16x16x32_bf16 v[98:101], v[130:133], v[162:165], v[98:101]
	v_mfma_f32_16x16x32_bf16 v[90:93], v[138:141], v[162:165], v[90:93]
	v_mfma_f32_16x16x32_bf16 v[82:85], v[130:133], v[170:173], v[82:85]
	v_mfma_f32_16x16x32_bf16 v[74:77], v[138:141], v[170:173], v[74:77]
	v_mfma_f32_16x16x32_bf16 v[126:129], v[134:137], v[150:153], v[126:129]
	v_mfma_f32_16x16x32_bf16 v[122:125], v[142:145], v[150:153], v[122:125]
	v_mfma_f32_16x16x32_bf16 v[114:117], v[134:137], v[158:161], v[114:117]
	v_mfma_f32_16x16x32_bf16 v[106:109], v[142:145], v[158:161], v[106:109]
	v_mfma_f32_16x16x32_bf16 v[98:101], v[134:137], v[166:169], v[98:101]
	v_mfma_f32_16x16x32_bf16 v[90:93], v[142:145], v[166:169], v[90:93]
	v_mfma_f32_16x16x32_bf16 v[82:85], v[134:137], v[174:177], v[82:85]
	v_mfma_f32_16x16x32_bf16 v[74:77], v[142:145], v[174:177], v[74:77]
	s_barrier
	s_add_i32 s20, 0, 0x1c000
	s_add_i32 s21, s37, s26
	v_add_u32_e32 v208, s20, v224
	v_lshl_add_u64 v[192:193], v[192:193], 0, s[92:93]
	s_mov_b32 m0, s21
	ds_read_b128 v[178:181], v208
	ds_read_b128 v[182:185], v208 offset:1024
	ds_read_b128 v[186:189], v208 offset:2048
	ds_read_b128 v[208:211], v208 offset:3072
	global_load_lds_dwordx4 v[192:193], off
	v_lshl_add_u64 v[192:193], v[194:195], 0, s[92:93]
	s_add_i32 m0, s21, 0x2000
	s_nop 0
	global_load_lds_dwordx4 v[192:193], off
	s_barrier
	s_waitcnt lgkmcnt(0)
	s_waitcnt lgkmcnt(0)
	v_mfma_f32_16x16x32_bf16 v[118:121], v[178:181], v[146:149], v[118:121]
	v_mfma_f32_16x16x32_bf16 v[110:113], v[186:189], v[146:149], v[110:113]
	v_mfma_f32_16x16x32_bf16 v[102:105], v[178:181], v[154:157], v[102:105]
	v_mfma_f32_16x16x32_bf16 v[94:97], v[186:189], v[154:157], v[94:97]
	v_mfma_f32_16x16x32_bf16 v[86:89], v[178:181], v[162:165], v[86:89]
	v_mfma_f32_16x16x32_bf16 v[78:81], v[186:189], v[162:165], v[78:81]
	v_mfma_f32_16x16x32_bf16 v[70:73], v[178:181], v[170:173], v[70:73]
	v_mfma_f32_16x16x32_bf16 v[66:69], v[186:189], v[170:173], v[66:69]
	v_mfma_f32_16x16x32_bf16 v[118:121], v[182:185], v[150:153], v[118:121]
	v_mfma_f32_16x16x32_bf16 v[110:113], v[208:211], v[150:153], v[110:113]
	v_mfma_f32_16x16x32_bf16 v[102:105], v[182:185], v[158:161], v[102:105]
	v_mfma_f32_16x16x32_bf16 v[94:97], v[208:211], v[158:161], v[94:97]
	v_mfma_f32_16x16x32_bf16 v[86:89], v[182:185], v[166:169], v[86:89]
	v_mfma_f32_16x16x32_bf16 v[78:81], v[208:211], v[166:169], v[78:81]
	v_mfma_f32_16x16x32_bf16 v[70:73], v[182:185], v[174:177], v[70:73]
	v_mfma_f32_16x16x32_bf16 v[66:69], v[208:211], v[174:177], v[66:69]
	s_mov_b32 m0, s31
	v_lshl_add_u64 v[192:193], v[212:213], 0, s[92:93]
	s_barrier
	ds_read_b128 v[146:149], v226 offset:49152
	ds_read_b128 v[150:153], v226 offset:50176
	ds_read_b128 v[154:157], v226 offset:51200
	ds_read_b128 v[158:161], v226 offset:52224
	ds_read_b128 v[162:165], v226 offset:53248
	ds_read_b128 v[166:169], v226 offset:54272
	ds_read_b128 v[170:173], v226 offset:55296
	ds_read_b128 v[174:177], v226 offset:56320
	global_load_lds_dwordx4 v[192:193], off
	v_lshl_add_u64 v[192:193], v[214:215], 0, s[92:93]
	s_mov_b32 m0, s33
	s_nop 0
	global_load_lds_dwordx4 v[192:193], off
	s_barrier
; #define G_STAGE(bufoff, gbase, voff) do { _Pragma("unroll") for (int _i = 0; _i < 2; ++_i) \
;         __builtin_amdgcn_global_load_lds((const unsigned*)((const char*)(gbase) + (voff)[_i]), (LAS unsigned*)(lds + (bufoff) + ldsw + _i * 8192), 16, 0, 0); } while (0)
; #define G_MMA(ai, bj, At, Bt) do { __builtin_amdgcn_s_setprio(1); _Pragma("unroll") for (int m = 0; m < 4; ++m) _Pragma("unroll") for (int n = 0; n < 2; ++n) _Pragma("unroll") for (int k = 0; k < 2; ++k) \
;         acc[ai][bj][m][n] = __builtin_amdgcn_mfma_f32_16x16x32_bf16(Bt[n][k], At[m][k], acc[ai][bj][m][n], 0, 0, 0); __builtin_amdgcn_s_setprio(0); } while (0)
; #define G_WAIT_V(n) asm volatile("s_waitcnt vmcnt(" #n ")" ::: "memory")
; #define G_WAIT_L(n) asm volatile("s_waitcnt lgkmcnt(" #n ")" ::: "memory")
; #define G_BAR __builtin_amdgcn_s_barrier()
; #define G_SCHED __builtin_amdgcn_sched_barrier(0)
; template <class Epi, class Sched>
; __device__ __forceinline__ void gemm_phase(LAS unsigned char* lds, const Sched& S, const Epi& E, const int K, const int lda, const int ldb, const int tid) {
;     ...
;             G_BAR; G_WAIT_L(0); G_MMA(1, 0, At, B0); G_BAR; G_SCHED;
;             G_STAGE(G_SB(1, 1), b3 + hstepB, voffB);
;             G_WAIT_V(6); G_BAR; G_MMA(1, 1, At, B1); G_BAR;
;         }
;     __device__ __forceinline__ bool operator()(f32x4 (&acc)[2][2][4][2], const Unit& un, int wr, int wc, int fr, int fq) const {
;         const int c0 = un.pn * 256 + wc * 32 + 8 * fq;
;         const int rbase = un.pm * 256 + wr * 64 + fr;
;         u32x4 g[2][4][2];
; #pragma unroll
;         for (int ai = 0; ai < 2; ++ai)
; #pragma unroll
;             for (int m = 0; m < 4; ++m)
; #pragma unroll
;                 for (int bj = 0; bj < 2; ++bj) g[ai][m][bj] = *(const u32x4*)(zb + (size_t)(rbase + ai * 128 + m * 16) * ZW + ZC_PG + c0 + bj * 128);
	s_waitcnt lgkmcnt(0)
	s_waitcnt lgkmcnt(0)
	v_mfma_f32_16x16x32_bf16 v[62:65], v[130:133], v[146:149], v[62:65]
	v_mfma_f32_16x16x32_bf16 v[58:61], v[138:141], v[146:149], v[58:61]
	v_mfma_f32_16x16x32_bf16 v[50:53], v[130:133], v[154:157], v[50:53]
	v_mfma_f32_16x16x32_bf16 v[42:45], v[138:141], v[154:157], v[42:45]
	v_mfma_f32_16x16x32_bf16 v[34:37], v[130:133], v[162:165], v[34:37]
	v_mfma_f32_16x16x32_bf16 v[26:29], v[138:141], v[162:165], v[26:29]
	v_mfma_f32_16x16x32_bf16 v[18:21], v[130:133], v[170:173], v[18:21]
	v_mfma_f32_16x16x32_bf16 v[10:13], v[138:141], v[170:173], v[10:13]
	v_mfma_f32_16x16x32_bf16 v[62:65], v[134:137], v[150:153], v[62:65]
	v_mfma_f32_16x16x32_bf16 v[58:61], v[142:145], v[150:153], v[58:61]
	v_mfma_f32_16x16x32_bf16 v[50:53], v[134:137], v[158:161], v[50:53]
	v_mfma_f32_16x16x32_bf16 v[42:45], v[142:145], v[158:161], v[42:45]
	v_mfma_f32_16x16x32_bf16 v[34:37], v[134:137], v[166:169], v[34:37]
	v_mfma_f32_16x16x32_bf16 v[26:29], v[142:145], v[166:169], v[26:29]
	v_mfma_f32_16x16x32_bf16 v[18:21], v[134:137], v[174:177], v[18:21]
	v_mfma_f32_16x16x32_bf16 v[10:13], v[142:145], v[174:177], v[10:13]
	s_barrier
	s_add_u32 s18, s18, 0x20080
	s_addc_u32 s19, s19, 0
	s_add_i32 s20, s20, s26
	v_lshl_add_u64 v[130:131], s[18:19], 0, v[0:1]
	s_mov_b32 m0, s20
	s_nop 0
	global_load_lds_dwordx4 v[130:131], off
	v_lshl_add_u64 v[130:131], s[18:19], 0, v[198:199]
	s_add_i32 m0, s20, 0x2000
	s_nop 0
	global_load_lds_dwordx4 v[130:131], off
	s_waitcnt vmcnt(6)
	s_barrier
	v_mfma_f32_16x16x32_bf16 v[54:57], v[178:181], v[146:149], v[54:57]
	v_mfma_f32_16x16x32_bf16 v[46:49], v[186:189], v[146:149], v[46:49]
	v_mfma_f32_16x16x32_bf16 v[38:41], v[178:181], v[154:157], v[38:41]
	v_mfma_f32_16x16x32_bf16 v[30:33], v[186:189], v[154:157], v[30:33]
	v_mfma_f32_16x16x32_bf16 v[22:25], v[178:181], v[162:165], v[22:25]
	v_mfma_f32_16x16x32_bf16 v[14:17], v[186:189], v[162:165], v[14:17]
	v_mfma_f32_16x16x32_bf16 v[6:9], v[178:181], v[170:173], v[6:9]
	v_mfma_f32_16x16x32_bf16 v[2:5], v[186:189], v[170:173], v[2:5]
	v_mfma_f32_16x16x32_bf16 v[54:57], v[182:185], v[150:153], v[54:57]
	v_mfma_f32_16x16x32_bf16 v[46:49], v[208:211], v[150:153], v[46:49]
	v_mfma_f32_16x16x32_bf16 v[38:41], v[182:185], v[158:161], v[38:41]
	v_mfma_f32_16x16x32_bf16 v[30:33], v[208:211], v[158:161], v[30:33]
	v_mfma_f32_16x16x32_bf16 v[22:25], v[182:185], v[166:169], v[22:25]
	v_mfma_f32_16x16x32_bf16 v[14:17], v[208:211], v[166:169], v[14:17]
	v_mfma_f32_16x16x32_bf16 v[6:9], v[182:185], v[174:177], v[6:9]
	v_mfma_f32_16x16x32_bf16 v[2:5], v[208:211], v[174:177], v[2:5]
	s_add_i32 s36, s36, 2
	s_add_u32 s16, s16, 0x100
	s_addc_u32 s17, s17, 0
	s_add_u32 s1, s1, 0x100
	s_addc_u32 s11, s11, 0
	s_cmp_gt_u32 s36, 5
	s_barrier
	s_cbranch_scc0 .LBB0_292
	v_lshl_or_b32 v130, s35, 8, v225
	v_ashrrev_i32_e32 v131, 31, v130
	v_readlane_b32 s16, v253, 19
	v_lshlrev_b64 v[208:209], 1, v[130:131]
	v_readlane_b32 s17, v253, 20
	v_lshl_add_u32 v192, s14, 8, v197
	v_or_b32_e32 v222, 16, v192
	v_lshl_add_u64 v[134:135], s[16:17], 0, v[208:209]
	v_mad_i64_i32 v[130:131], s[16:17], v192, s74, v[134:135]
	global_load_dwordx4 v[228:231], v[130:131], off
	global_load_dwordx4 v[186:189], v[130:131], off offset:256
	v_mad_i64_i32 v[130:131], s[16:17], v222, s74, v[134:135]
	global_load_dwordx4 v[182:185], v[130:131], off
	global_load_dwordx4 v[178:181], v[130:131], off offset:256
	v_or_b32_e32 v220, 32, v192
	v_mad_i64_i32 v[130:131], s[16:17], v220, s74, v[134:135]
	global_load_dwordx4 v[174:177], v[130:131], off
	global_load_dwordx4 v[170:173], v[130:131], off offset:256
	v_or_b32_e32 v218, 48, v192
	v_mad_i64_i32 v[130:131], s[16:17], v218, s74, v[134:135]
	global_load_dwordx4 v[166:169], v[130:131], off
	global_load_dwordx4 v[162:165], v[130:131], off offset:256
	v_add_u32_e32 v216, 0x80, v192
	v_mad_i64_i32 v[130:131], s[16:17], v216, s74, v[134:135]
	global_load_dwordx4 v[158:161], v[130:131], off
	global_load_dwordx4 v[154:157], v[130:131], off offset:256
	v_add_u32_e32 v214, 0x90, v192
	v_mad_i64_i32 v[130:131], s[16:17], v214, s74, v[134:135]
	v_add_u32_e32 v212, 0xa0, v192
	v_add_u32_e32 v210, 0xb0, v192
	global_load_dwordx4 v[150:153], v[130:131], off
	global_load_dwordx4 v[146:149], v[130:131], off offset:256
	v_mad_i64_i32 v[130:131], s[16:17], v212, s74, v[134:135]
	v_mad_i64_i32 v[134:135], s[16:17], v210, s74, v[134:135]
	global_load_dwordx4 v[138:141], v[130:131], off
	s_nop 0
	global_load_dwordx4 v[130:133], v[130:131], off offset:256
	s_nop 0
	global_load_dwordx4 v[142:145], v[134:135], off
	s_nop 0
	global_load_dwordx4 v[134:137], v[134:135], off offset:256
	v_ashrrev_i32_e32 v193, 31, v192
	v_lshlrev_b64 v[192:193], 12, v[192:193]
	v_ashrrev_i32_e32 v223, 31, v222
	v_ashrrev_i32_e32 v221, 31, v220
	v_ashrrev_i32_e32 v219, 31, v218
	v_ashrrev_i32_e32 v217, 31, v216
	v_ashrrev_i32_e32 v215, 31, v214
	v_ashrrev_i32_e32 v213, 31, v212
	v_ashrrev_i32_e32 v211, 31, v210
	s_and_b64 vcc, exec, s[6:7]
	s_mov_b32 s35, s0
	s_mov_b32 s14, s10
	s_mov_b64 s[16:17], s[8:9]
	s_mov_b64 s[18:19], s[12:13]
	v_readlane_b32 s40, v254, 39
	s_waitcnt vmcnt(0)
; __device__ __forceinline__ unsigned pk_bf16(float lo, float hi) { unsigned r; asm volatile("v_cvt_pk_bf16_f32 %0, %1, %2" : "=v"(r) : "v"(lo), "v"(hi)); return r; }
; __device__ __forceinline__ float bf_lo(unsigned u) { return __uint_as_float(u << 16); }
; __device__ __forceinline__ float bf_hi(unsigned u) { return __uint_as_float(u & 0xffff0000u); }
;     __device__ __forceinline__ bool operator()(f32x4 (&acc)[2][2][4][2], const Unit& un, int wr, int wc, int fr, int fq) const {
;     ...
;         for (int ai = 0; ai < 2; ++ai)
; #pragma unroll
;             for (int m = 0; m < 4; ++m)
; #pragma unroll
;                 for (int bj = 0; bj < 2; ++bj) g[ai][m][bj] = *(const u32x4*)(zb + (size_t)(rbase + ai * 128 + m * 16) * ZW + ZC_PG + c0 + bj * 128);
; #pragma unroll
;         for (int ai = 0; ai < 2; ++ai)
; #pragma unroll
;             for (int m = 0; m < 4; ++m) {
;                 const int r = rbase + ai * 128 + m * 16;
; #pragma unroll
;                 for (int bj = 0; bj < 2; ++bj) {
;                     const u32x4 gg = g[ai][m][bj];
;                     const f32x4 v0 = acc[ai][bj][m][0], v1 = acc[ai][bj][m][1];
;                     u32x4 w;
;                     w.x = pk_bf16(v0[0] * bf_lo(gg.x), v0[1] * bf_hi(gg.x)); w.y = pk_bf16(v0[2] * bf_lo(gg.y), v0[3] * bf_hi(gg.y));
;                     w.z = pk_bf16(v1[0] * bf_lo(gg.z), v1[1] * bf_hi(gg.z)); w.w = pk_bf16(v1[2] * bf_lo(gg.w), v1[3] * bf_hi(gg.w));
;                     *(u32x4*)(ain + (size_t)r * D + c0 + bj * 128) = w;
;                 }
	v_lshlrev_b32_e32 v194, 16, v228
	v_mul_f32_e32 v126, v126, v194
	v_and_b32_e32 v194, 0xffff0000, v228
	v_mul_f32_e32 v127, v127, v194
	v_cvt_pk_bf16_f32 v126, v126, v127
	v_lshlrev_b32_e32 v127, 16, v229
	v_mul_f32_e32 v127, v128, v127
	v_and_b32_e32 v128, 0xffff0000, v229
	v_mul_f32_e32 v128, v129, v128
	v_cvt_pk_bf16_f32 v127, v127, v128
	v_lshlrev_b32_e32 v128, 16, v230
	v_mul_f32_e32 v122, v122, v128
	v_and_b32_e32 v128, 0xffff0000, v230
	v_mul_f32_e32 v123, v123, v128
	v_cvt_pk_bf16_f32 v128, v122, v123
	v_lshlrev_b32_e32 v122, 16, v231
	v_and_b32_e32 v123, 0xffff0000, v231
	v_mul_f32_e32 v122, v124, v122
	v_mul_f32_e32 v123, v125, v123
	v_lshlrev_b32_e32 v124, 16, v186
	v_cvt_pk_bf16_f32 v129, v122, v123
	v_lshl_add_u64 v[122:123], s[96:97], 0, v[192:193]
	v_mul_f32_e32 v118, v118, v124
	v_and_b32_e32 v124, 0xffff0000, v186
	v_lshl_add_u64 v[122:123], v[122:123], 0, v[208:209]
	v_mul_f32_e32 v119, v119, v124
	global_store_dwordx4 v[122:123], v[126:129], off
	v_cvt_pk_bf16_f32 v118, v118, v119
	v_lshlrev_b32_e32 v119, 16, v187
	v_mul_f32_e32 v119, v120, v119
	v_and_b32_e32 v120, 0xffff0000, v187
	v_mul_f32_e32 v120, v121, v120
	v_cvt_pk_bf16_f32 v119, v119, v120
	v_lshlrev_b32_e32 v120, 16, v188
	v_mul_f32_e32 v110, v110, v120
	v_and_b32_e32 v120, 0xffff0000, v188
	v_mul_f32_e32 v111, v111, v120
	v_cvt_pk_bf16_f32 v120, v110, v111
	v_lshlrev_b32_e32 v110, 16, v189
	v_and_b32_e32 v111, 0xffff0000, v189
	v_mul_f32_e32 v110, v112, v110
	v_mul_f32_e32 v111, v113, v111
	v_cvt_pk_bf16_f32 v121, v110, v111
	v_lshlrev_b32_e32 v110, 16, v182
	v_and_b32_e32 v111, 0xffff0000, v182
	v_mul_f32_e32 v110, v114, v110
	v_mul_f32_e32 v111, v115, v111
	global_store_dwordx4 v[122:123], v[118:121], off offset:256
	v_cvt_pk_bf16_f32 v110, v110, v111
	v_lshlrev_b32_e32 v111, 16, v183
	v_and_b32_e32 v112, 0xffff0000, v183
	v_mul_f32_e32 v111, v116, v111
	v_mul_f32_e32 v112, v117, v112
	v_cvt_pk_bf16_f32 v111, v111, v112
	v_lshlrev_b32_e32 v112, 16, v184
	v_mul_f32_e32 v106, v106, v112
	v_and_b32_e32 v112, 0xffff0000, v184
	v_mul_f32_e32 v107, v107, v112
	v_cvt_pk_bf16_f32 v112, v106, v107
	v_lshlrev_b32_e32 v106, 16, v185
	v_and_b32_e32 v107, 0xffff0000, v185
	v_lshlrev_b64 v[118:119], 12, v[222:223]
	v_mul_f32_e32 v106, v108, v106
	v_mul_f32_e32 v107, v109, v107
	v_lshlrev_b32_e32 v108, 16, v178
	v_cvt_pk_bf16_f32 v113, v106, v107
	v_lshl_add_u64 v[106:107], s[96:97], 0, v[118:119]
	v_mul_f32_e32 v102, v102, v108
	v_and_b32_e32 v108, 0xffff0000, v178
	v_lshl_add_u64 v[106:107], v[106:107], 0, v[208:209]
	v_mul_f32_e32 v103, v103, v108
	global_store_dwordx4 v[106:107], v[110:113], off
	v_cvt_pk_bf16_f32 v102, v102, v103
	v_lshlrev_b32_e32 v103, 16, v179
	v_mul_f32_e32 v103, v104, v103
	v_and_b32_e32 v104, 0xffff0000, v179
	v_mul_f32_e32 v104, v105, v104
	v_cvt_pk_bf16_f32 v103, v103, v104
	v_lshlrev_b32_e32 v104, 16, v180
	v_mul_f32_e32 v94, v94, v104
	v_and_b32_e32 v104, 0xffff0000, v180
	v_mul_f32_e32 v95, v95, v104
	v_cvt_pk_bf16_f32 v104, v94, v95
	v_lshlrev_b32_e32 v94, 16, v181
	v_and_b32_e32 v95, 0xffff0000, v181
	v_mul_f32_e32 v94, v96, v94
	v_mul_f32_e32 v95, v97, v95
	v_cvt_pk_bf16_f32 v105, v94, v95
	v_lshlrev_b32_e32 v94, 16, v174
	v_and_b32_e32 v95, 0xffff0000, v174
	v_mul_f32_e32 v94, v98, v94
	v_mul_f32_e32 v95, v99, v95
	global_store_dwordx4 v[106:107], v[102:105], off offset:256
	v_cvt_pk_bf16_f32 v94, v94, v95
	v_lshlrev_b32_e32 v95, 16, v175
	v_and_b32_e32 v96, 0xffff0000, v175
	v_mul_f32_e32 v95, v100, v95
	v_mul_f32_e32 v96, v101, v96
	v_cvt_pk_bf16_f32 v95, v95, v96
	v_lshlrev_b32_e32 v96, 16, v176
	v_mul_f32_e32 v90, v90, v96
	v_and_b32_e32 v96, 0xffff0000, v176
	v_mul_f32_e32 v91, v91, v96
	v_cvt_pk_bf16_f32 v96, v90, v91
	v_lshlrev_b32_e32 v90, 16, v177
	v_and_b32_e32 v91, 0xffff0000, v177
	v_lshlrev_b64 v[102:103], 12, v[220:221]
	v_mul_f32_e32 v90, v92, v90
	v_mul_f32_e32 v91, v93, v91
	v_lshlrev_b32_e32 v92, 16, v170
	v_cvt_pk_bf16_f32 v97, v90, v91
	v_lshl_add_u64 v[90:91], s[96:97], 0, v[102:103]
	v_mul_f32_e32 v86, v86, v92
	v_and_b32_e32 v92, 0xffff0000, v170
	v_lshl_add_u64 v[90:91], v[90:91], 0, v[208:209]
	v_mul_f32_e32 v87, v87, v92
	global_store_dwordx4 v[90:91], v[94:97], off
	v_cvt_pk_bf16_f32 v86, v86, v87
	v_lshlrev_b32_e32 v87, 16, v171
	v_mul_f32_e32 v87, v88, v87
	v_and_b32_e32 v88, 0xffff0000, v171
	v_mul_f32_e32 v88, v89, v88
	v_cvt_pk_bf16_f32 v87, v87, v88
	v_lshlrev_b32_e32 v88, 16, v172
	v_mul_f32_e32 v78, v78, v88
	v_and_b32_e32 v88, 0xffff0000, v172
	v_mul_f32_e32 v79, v79, v88
	v_cvt_pk_bf16_f32 v88, v78, v79
	v_lshlrev_b32_e32 v78, 16, v173
	v_and_b32_e32 v79, 0xffff0000, v173
	v_mul_f32_e32 v78, v80, v78
	v_mul_f32_e32 v79, v81, v79
	v_cvt_pk_bf16_f32 v89, v78, v79
	v_lshlrev_b32_e32 v78, 16, v166
	v_and_b32_e32 v79, 0xffff0000, v166
	v_mul_f32_e32 v78, v82, v78
	v_mul_f32_e32 v79, v83, v79
	global_store_dwordx4 v[90:91], v[86:89], off offset:256
	v_cvt_pk_bf16_f32 v78, v78, v79
	v_lshlrev_b32_e32 v79, 16, v167
	v_and_b32_e32 v80, 0xffff0000, v167
	v_mul_f32_e32 v79, v84, v79
	v_mul_f32_e32 v80, v85, v80
	v_cvt_pk_bf16_f32 v79, v79, v80
	v_lshlrev_b32_e32 v80, 16, v168
	v_mul_f32_e32 v74, v74, v80
	v_and_b32_e32 v80, 0xffff0000, v168
	v_mul_f32_e32 v75, v75, v80
	v_cvt_pk_bf16_f32 v80, v74, v75
	v_lshlrev_b32_e32 v74, 16, v169
	v_and_b32_e32 v75, 0xffff0000, v169
	v_lshlrev_b64 v[86:87], 12, v[218:219]
	v_mul_f32_e32 v74, v76, v74
	v_mul_f32_e32 v75, v77, v75
	v_lshlrev_b32_e32 v76, 16, v162
	v_cvt_pk_bf16_f32 v81, v74, v75
	v_lshl_add_u64 v[74:75], s[96:97], 0, v[86:87]
	v_mul_f32_e32 v70, v70, v76
	v_and_b32_e32 v76, 0xffff0000, v162
	v_lshl_add_u64 v[74:75], v[74:75], 0, v[208:209]
; __device__ __forceinline__ unsigned pk_bf16(float lo, float hi) { unsigned r; asm volatile("v_cvt_pk_bf16_f32 %0, %1, %2" : "=v"(r) : "v"(lo), "v"(hi)); return r; }
; __device__ __forceinline__ float bf_lo(unsigned u) { return __uint_as_float(u << 16); }
; __device__ __forceinline__ float bf_hi(unsigned u) { return __uint_as_float(u & 0xffff0000u); }
; #define G_WAIT_V(n) asm volatile("s_waitcnt vmcnt(" #n ")" ::: "memory")
; #define G_BAR __builtin_amdgcn_s_barrier()
; template <class Epi, class Sched>
; __device__ __forceinline__ void gemm_phase(LAS unsigned char* lds, const Sched& S, const Epi& E, const int K, const int lda, const int ldb, const int tid) {
;     ...
;         cur = nxt; cA = nA; cB = nB; ++ui;
;     }
;     G_WAIT_V(0);
;     if (wr == 0) G_BAR;
;     G_BAR;
;     __device__ __forceinline__ bool operator()(f32x4 (&acc)[2][2][4][2], const Unit& un, int wr, int wc, int fr, int fq) const {
;     ...
;         for (int ai = 0; ai < 2; ++ai)
; #pragma unroll
;             for (int m = 0; m < 4; ++m) {
;                 const int r = rbase + ai * 128 + m * 16;
; #pragma unroll
;                 for (int bj = 0; bj < 2; ++bj) {
;                     const u32x4 gg = g[ai][m][bj];
;                     const f32x4 v0 = acc[ai][bj][m][0], v1 = acc[ai][bj][m][1];
;                     u32x4 w;
;                     w.x = pk_bf16(v0[0] * bf_lo(gg.x), v0[1] * bf_hi(gg.x)); w.y = pk_bf16(v0[2] * bf_lo(gg.y), v0[3] * bf_hi(gg.y));
;                     w.z = pk_bf16(v1[0] * bf_lo(gg.z), v1[1] * bf_hi(gg.z)); w.w = pk_bf16(v1[2] * bf_lo(gg.w), v1[3] * bf_hi(gg.w));
;                     *(u32x4*)(ain + (size_t)r * D + c0 + bj * 128) = w;
;                 }
	v_mul_f32_e32 v71, v71, v76
	global_store_dwordx4 v[74:75], v[78:81], off
	v_cvt_pk_bf16_f32 v70, v70, v71
	v_lshlrev_b32_e32 v71, 16, v163
	v_mul_f32_e32 v71, v72, v71
	v_and_b32_e32 v72, 0xffff0000, v163
	v_mul_f32_e32 v72, v73, v72
	v_cvt_pk_bf16_f32 v71, v71, v72
	v_lshlrev_b32_e32 v72, 16, v164
	v_mul_f32_e32 v66, v66, v72
	v_and_b32_e32 v72, 0xffff0000, v164
	v_mul_f32_e32 v67, v67, v72
	v_cvt_pk_bf16_f32 v72, v66, v67
	v_lshlrev_b32_e32 v66, 16, v165
	v_mul_f32_e32 v66, v68, v66
	v_lshlrev_b32_e32 v68, 16, v158
	v_mul_f32_e32 v62, v62, v68
	v_and_b32_e32 v68, 0xffff0000, v158
	v_and_b32_e32 v67, 0xffff0000, v165
	v_mul_f32_e32 v63, v63, v68
	v_mul_f32_e32 v67, v69, v67
	v_cvt_pk_bf16_f32 v73, v66, v67
	global_store_dwordx4 v[74:75], v[70:73], off offset:256
	v_cvt_pk_bf16_f32 v62, v62, v63
	v_lshlrev_b32_e32 v63, 16, v159
	v_mul_f32_e32 v63, v64, v63
	v_and_b32_e32 v64, 0xffff0000, v159
	v_mul_f32_e32 v64, v65, v64
	v_cvt_pk_bf16_f32 v63, v63, v64
	v_lshlrev_b32_e32 v64, 16, v160
	v_mul_f32_e32 v58, v58, v64
	v_and_b32_e32 v64, 0xffff0000, v160
	v_mul_f32_e32 v59, v59, v64
	v_cvt_pk_bf16_f32 v64, v58, v59
	v_lshlrev_b32_e32 v58, 16, v161
	v_and_b32_e32 v59, 0xffff0000, v161
	v_lshlrev_b64 v[66:67], 12, v[216:217]
	v_mul_f32_e32 v58, v60, v58
	v_mul_f32_e32 v59, v61, v59
	v_lshlrev_b32_e32 v60, 16, v154
	v_cvt_pk_bf16_f32 v65, v58, v59
	v_lshl_add_u64 v[58:59], s[96:97], 0, v[66:67]
	v_mul_f32_e32 v54, v54, v60
	v_and_b32_e32 v60, 0xffff0000, v154
	v_lshl_add_u64 v[58:59], v[58:59], 0, v[208:209]
	v_mul_f32_e32 v55, v55, v60
	global_store_dwordx4 v[58:59], v[62:65], off
	v_cvt_pk_bf16_f32 v54, v54, v55
	v_lshlrev_b32_e32 v55, 16, v155
	v_mul_f32_e32 v55, v56, v55
	v_and_b32_e32 v56, 0xffff0000, v155
	v_mul_f32_e32 v56, v57, v56
	v_cvt_pk_bf16_f32 v55, v55, v56
	v_lshlrev_b32_e32 v56, 16, v156
	v_mul_f32_e32 v46, v46, v56
	v_and_b32_e32 v56, 0xffff0000, v156
	v_mul_f32_e32 v47, v47, v56
	v_cvt_pk_bf16_f32 v56, v46, v47
	v_lshlrev_b32_e32 v46, 16, v157
	v_and_b32_e32 v47, 0xffff0000, v157
	v_mul_f32_e32 v46, v48, v46
	v_mul_f32_e32 v47, v49, v47
	v_cvt_pk_bf16_f32 v57, v46, v47
	v_lshlrev_b32_e32 v46, 16, v150
	v_and_b32_e32 v47, 0xffff0000, v150
	v_mul_f32_e32 v46, v50, v46
	v_mul_f32_e32 v47, v51, v47
	global_store_dwordx4 v[58:59], v[54:57], off offset:256
	v_cvt_pk_bf16_f32 v46, v46, v47
	v_lshlrev_b32_e32 v47, 16, v151
	v_and_b32_e32 v48, 0xffff0000, v151
	v_mul_f32_e32 v47, v52, v47
	v_mul_f32_e32 v48, v53, v48
	v_cvt_pk_bf16_f32 v47, v47, v48
	v_lshlrev_b32_e32 v48, 16, v152
	v_mul_f32_e32 v42, v42, v48
	v_and_b32_e32 v48, 0xffff0000, v152
	v_mul_f32_e32 v43, v43, v48
	v_cvt_pk_bf16_f32 v48, v42, v43
	v_lshlrev_b32_e32 v42, 16, v153
	v_and_b32_e32 v43, 0xffff0000, v153
	v_lshlrev_b64 v[54:55], 12, v[214:215]
	v_mul_f32_e32 v42, v44, v42
	v_mul_f32_e32 v43, v45, v43
	v_lshlrev_b32_e32 v44, 16, v146
	v_cvt_pk_bf16_f32 v49, v42, v43
	v_lshl_add_u64 v[42:43], s[96:97], 0, v[54:55]
	v_mul_f32_e32 v38, v38, v44
	v_and_b32_e32 v44, 0xffff0000, v146
	v_lshl_add_u64 v[42:43], v[42:43], 0, v[208:209]
	v_mul_f32_e32 v39, v39, v44
	global_store_dwordx4 v[42:43], v[46:49], off
	v_cvt_pk_bf16_f32 v38, v38, v39
	v_lshlrev_b32_e32 v39, 16, v147
	v_mul_f32_e32 v39, v40, v39
	v_and_b32_e32 v40, 0xffff0000, v147
	v_mul_f32_e32 v40, v41, v40
	v_cvt_pk_bf16_f32 v39, v39, v40
	v_lshlrev_b32_e32 v40, 16, v148
	v_mul_f32_e32 v30, v30, v40
	v_and_b32_e32 v40, 0xffff0000, v148
	v_mul_f32_e32 v31, v31, v40
	v_cvt_pk_bf16_f32 v40, v30, v31
	v_lshlrev_b32_e32 v30, 16, v149
	v_and_b32_e32 v31, 0xffff0000, v149
	v_mul_f32_e32 v30, v32, v30
	v_mul_f32_e32 v31, v33, v31
	v_cvt_pk_bf16_f32 v41, v30, v31
	v_lshlrev_b32_e32 v30, 16, v138
	v_and_b32_e32 v31, 0xffff0000, v138
	v_mul_f32_e32 v30, v34, v30
	v_mul_f32_e32 v31, v35, v31
	global_store_dwordx4 v[42:43], v[38:41], off offset:256
	v_cvt_pk_bf16_f32 v30, v30, v31
	v_lshlrev_b32_e32 v31, 16, v139
	v_and_b32_e32 v32, 0xffff0000, v139
	v_mul_f32_e32 v31, v36, v31
	v_mul_f32_e32 v32, v37, v32
	v_cvt_pk_bf16_f32 v31, v31, v32
	v_lshlrev_b32_e32 v32, 16, v140
	v_mul_f32_e32 v26, v26, v32
	v_and_b32_e32 v32, 0xffff0000, v140
	v_mul_f32_e32 v27, v27, v32
	v_cvt_pk_bf16_f32 v32, v26, v27
	v_lshlrev_b32_e32 v26, 16, v141
	v_and_b32_e32 v27, 0xffff0000, v141
	v_lshlrev_b64 v[38:39], 12, v[212:213]
	v_mul_f32_e32 v26, v28, v26
	v_mul_f32_e32 v27, v29, v27
	v_lshlrev_b32_e32 v28, 16, v130
	v_cvt_pk_bf16_f32 v33, v26, v27
	v_lshl_add_u64 v[26:27], s[96:97], 0, v[38:39]
	v_mul_f32_e32 v22, v22, v28
	v_and_b32_e32 v28, 0xffff0000, v130
	v_lshl_add_u64 v[26:27], v[26:27], 0, v[208:209]
	v_mul_f32_e32 v23, v23, v28
	global_store_dwordx4 v[26:27], v[30:33], off
	v_cvt_pk_bf16_f32 v22, v22, v23
	v_lshlrev_b32_e32 v23, 16, v131
	v_mul_f32_e32 v23, v24, v23
	v_and_b32_e32 v24, 0xffff0000, v131
	v_mul_f32_e32 v24, v25, v24
	v_cvt_pk_bf16_f32 v23, v23, v24
	v_lshlrev_b32_e32 v24, 16, v132
	v_mul_f32_e32 v14, v14, v24
	v_and_b32_e32 v24, 0xffff0000, v132
	v_mul_f32_e32 v15, v15, v24
	v_cvt_pk_bf16_f32 v24, v14, v15
	v_lshlrev_b32_e32 v14, 16, v133
	v_and_b32_e32 v15, 0xffff0000, v133
	v_mul_f32_e32 v14, v16, v14
	v_mul_f32_e32 v15, v17, v15
	v_cvt_pk_bf16_f32 v25, v14, v15
	v_lshlrev_b32_e32 v14, 16, v142
	v_and_b32_e32 v15, 0xffff0000, v142
	v_mul_f32_e32 v14, v18, v14
	v_mul_f32_e32 v15, v19, v15
	global_store_dwordx4 v[26:27], v[22:25], off offset:256
	v_cvt_pk_bf16_f32 v14, v14, v15
	v_lshlrev_b32_e32 v15, 16, v143
	v_and_b32_e32 v16, 0xffff0000, v143
	v_mul_f32_e32 v15, v20, v15
	v_mul_f32_e32 v16, v21, v16
	v_cvt_pk_bf16_f32 v15, v15, v16
	v_lshlrev_b32_e32 v16, 16, v144
	v_mul_f32_e32 v10, v10, v16
	v_and_b32_e32 v16, 0xffff0000, v144
	v_mul_f32_e32 v11, v11, v16
	v_cvt_pk_bf16_f32 v16, v10, v11
	v_lshlrev_b32_e32 v10, 16, v145
	v_and_b32_e32 v11, 0xffff0000, v145
	v_lshlrev_b64 v[22:23], 12, v[210:211]
	v_mul_f32_e32 v10, v12, v10
	v_mul_f32_e32 v11, v13, v11
	v_lshlrev_b32_e32 v12, 16, v134
	v_cvt_pk_bf16_f32 v17, v10, v11
	v_lshl_add_u64 v[10:11], s[96:97], 0, v[22:23]
	v_mul_f32_e32 v6, v6, v12
	v_and_b32_e32 v12, 0xffff0000, v134
	v_lshl_add_u64 v[10:11], v[10:11], 0, v[208:209]
	v_mul_f32_e32 v7, v7, v12
	global_store_dwordx4 v[10:11], v[14:17], off
	v_cvt_pk_bf16_f32 v6, v6, v7
	v_lshlrev_b32_e32 v7, 16, v135
	v_mul_f32_e32 v7, v8, v7
	v_and_b32_e32 v8, 0xffff0000, v135
	v_mul_f32_e32 v8, v9, v8
	v_cvt_pk_bf16_f32 v7, v7, v8
	v_lshlrev_b32_e32 v8, 16, v136
	v_mul_f32_e32 v2, v2, v8
	v_and_b32_e32 v8, 0xffff0000, v136
	v_mul_f32_e32 v3, v3, v8
	v_cvt_pk_bf16_f32 v8, v2, v3
	v_lshlrev_b32_e32 v2, 16, v137
	v_and_b32_e32 v3, 0xffff0000, v137
	v_mul_f32_e32 v2, v4, v2
	v_mul_f32_e32 v3, v5, v3
	v_cvt_pk_bf16_f32 v9, v2, v3
	global_store_dwordx4 v[10:11], v[6:9], off offset:256
	s_cbranch_vccz .LBB0_287
	s_waitcnt vmcnt(0)
	s_cmpk_gt_u32 s23, 0xff
	s_cbranch_scc1 .LBB0_296
	s_barrier

; #define G_STAGE(bufoff, gbase, voff) do { _Pragma("unroll") for (int _i = 0; _i < 2; ++_i) \
;         __builtin_amdgcn_global_load_lds((const unsigned*)((const char*)(gbase) + (voff)[_i]), (LAS unsigned*)(lds + (bufoff) + ldsw + _i * 8192), 16, 0, 0); } while (0)
; #define G_LDA(dst, b, h) do { _Pragma("unroll") for (int m = 0; m < 4; ++m) _Pragma("unroll") for (int k = 0; k < 2; ++k) dst[m][k] = *(const LAS bf16x8*)(lds + G_SA(b, h) + aoff + m * 2048 + k * 1024); } while (0)
; #define G_LDB(dst, b, h) do { _Pragma("unroll") for (int n = 0; n < 2; ++n) _Pragma("unroll") for (int k = 0; k < 2; ++k) dst[n][k] = *(const LAS bf16x8*)(lds + G_SB(b, h) + boff + n * 2048 + k * 1024); } while (0)
; #define G_MMA(ai, bj, At, Bt) do { __builtin_amdgcn_s_setprio(1); _Pragma("unroll") for (int m = 0; m < 4; ++m) _Pragma("unroll") for (int n = 0; n < 2; ++n) _Pragma("unroll") for (int k = 0; k < 2; ++k) \
;         acc[ai][bj][m][n] = __builtin_amdgcn_mfma_f32_16x16x32_bf16(Bt[n][k], At[m][k], acc[ai][bj][m][n], 0, 0, 0); __builtin_amdgcn_s_setprio(0); } while (0)
; #define G_WAIT_V(n) asm volatile("s_waitcnt vmcnt(" #n ")" ::: "memory")
; #define G_WAIT_L(n) asm volatile("s_waitcnt lgkmcnt(" #n ")" ::: "memory")
; #define G_BAR __builtin_amdgcn_s_barrier()
; #define G_SCHED __builtin_amdgcn_sched_barrier(0)
; template <class Epi, class Sched>
; __device__ __forceinline__ void gemm_phase(LAS unsigned char* lds, const Sched& S, const Epi& E, const int K, const int lda, const int ldb, const int tid) {
;     ...
;             G_LDB(B0, 0, 0); G_SCHED; G_LDA(At, 0, 0); G_STAGE(G_SA(1, 1), a1 + hstepA, voffA);
;             G_WAIT_L(8); G_BAR; G_WAIT_L(0); G_MMA(0, 0, At, B0); G_BAR; G_SCHED;
;             G_LDB(B1, 0, 1); G_STAGE(G_SB(0, 0), b2, voffB);
;             G_BAR; G_WAIT_L(0); G_MMA(0, 1, At, B1); G_BAR;
;             G_LDA(At, 0, 1); G_STAGE(G_SA(0, 0), a2, voffA);
;             G_BAR; G_WAIT_L(0); G_MMA(1, 0, At, B0); G_BAR; G_SCHED;
;             G_STAGE(G_SB(0, 1), b2 + hstepB, voffB);
;             G_WAIT_V(6); G_BAR; G_MMA(1, 1, At, B1); G_BAR;
.LBB0_556:
	s_add_u32 s20, s18, 0xfff80080
	s_addc_u32 s21, s19, -1
	s_add_i32 s43, 0, 0x10000
	v_add_u32_e32 v0, s43, v197
	ds_read_b128 v[130:133], v0
	ds_read_b128 v[134:137], v0 offset:1024
	ds_read_b128 v[138:141], v0 offset:2048
	ds_read_b128 v[142:145], v0 offset:3072
	s_cmp_eq_u32 s41, 28
	s_cselect_b32 s23, s1, s21
	s_cselect_b32 s22, s11, s20
	s_cselect_b32 s21, s13, s40
	s_cselect_b32 s20, s33, s39
	v_lshl_add_u64 v[192:193], s[18:19], 0, v[158:159]
	s_add_i32 m0, s29, 0xc000
	ds_read_b128 v[162:165], v201
	ds_read_b128 v[166:169], v201 offset:1024
	ds_read_b128 v[170:173], v201 offset:2048
	ds_read_b128 v[174:177], v201 offset:3072
	ds_read_b128 v[178:181], v201 offset:4096
	ds_read_b128 v[182:185], v201 offset:5120
	ds_read_b128 v[186:189], v201 offset:6144
	ds_read_b128 v[202:205], v201 offset:7168
	global_load_lds_dwordx4 v[192:193], off
	v_lshl_add_u64 v[192:193], s[18:19], 0, v[160:161]
	s_add_i32 m0, s29, 0xe000
	s_nop 0
	global_load_lds_dwordx4 v[192:193], off
	s_waitcnt lgkmcnt(8)
	s_barrier
	s_waitcnt lgkmcnt(0)
	s_waitcnt lgkmcnt(0)
	v_mfma_f32_16x16x32_bf16 v[126:129], v[130:133], v[162:165], v[126:129]
	v_mfma_f32_16x16x32_bf16 v[122:125], v[138:141], v[162:165], v[122:125]
	v_mfma_f32_16x16x32_bf16 v[110:113], v[130:133], v[170:173], v[110:113]
	v_mfma_f32_16x16x32_bf16 v[106:109], v[138:141], v[170:173], v[106:109]
	v_mfma_f32_16x16x32_bf16 v[94:97], v[130:133], v[178:181], v[94:97]
	v_mfma_f32_16x16x32_bf16 v[90:93], v[138:141], v[178:181], v[90:93]
	v_mfma_f32_16x16x32_bf16 v[78:81], v[130:133], v[186:189], v[78:81]
	v_mfma_f32_16x16x32_bf16 v[74:77], v[138:141], v[186:189], v[74:77]
	v_mfma_f32_16x16x32_bf16 v[126:129], v[134:137], v[166:169], v[126:129]
	v_mfma_f32_16x16x32_bf16 v[122:125], v[142:145], v[166:169], v[122:125]
	v_mfma_f32_16x16x32_bf16 v[110:113], v[134:137], v[174:177], v[110:113]
	v_mfma_f32_16x16x32_bf16 v[106:109], v[142:145], v[174:177], v[106:109]
	v_mfma_f32_16x16x32_bf16 v[94:97], v[134:137], v[182:185], v[94:97]
	v_mfma_f32_16x16x32_bf16 v[90:93], v[142:145], v[182:185], v[90:93]
	v_mfma_f32_16x16x32_bf16 v[78:81], v[134:137], v[202:205], v[78:81]
	v_mfma_f32_16x16x32_bf16 v[74:77], v[142:145], v[202:205], v[74:77]
	s_barrier
	s_add_i32 s62, 0, 0x14000
	s_add_i32 s43, s43, s27
	v_add_u32_e32 v0, s62, v197
	v_lshl_add_u64 v[192:193], s[20:21], 0, v[150:151]
	s_mov_b32 m0, s43
	ds_read_b128 v[206:209], v0
	ds_read_b128 v[210:213], v0 offset:1024
	ds_read_b128 v[214:217], v0 offset:2048
	ds_read_b128 v[218:221], v0 offset:3072
	global_load_lds_dwordx4 v[192:193], off
	v_lshl_add_u64 v[194:195], s[20:21], 0, v[146:147]
	s_add_i32 m0, s43, 0x2000
	s_nop 0
	global_load_lds_dwordx4 v[194:195], off
	s_barrier
	s_waitcnt lgkmcnt(0)
	s_waitcnt lgkmcnt(0)
	v_mfma_f32_16x16x32_bf16 v[118:121], v[206:209], v[162:165], v[118:121]
	v_mfma_f32_16x16x32_bf16 v[114:117], v[214:217], v[162:165], v[114:117]
	v_mfma_f32_16x16x32_bf16 v[102:105], v[206:209], v[170:173], v[102:105]
	v_mfma_f32_16x16x32_bf16 v[98:101], v[214:217], v[170:173], v[98:101]
	v_mfma_f32_16x16x32_bf16 v[86:89], v[206:209], v[178:181], v[86:89]
	v_mfma_f32_16x16x32_bf16 v[82:85], v[214:217], v[178:181], v[82:85]
	v_mfma_f32_16x16x32_bf16 v[70:73], v[206:209], v[186:189], v[70:73]
	v_mfma_f32_16x16x32_bf16 v[66:69], v[214:217], v[186:189], v[66:69]
	v_mfma_f32_16x16x32_bf16 v[118:121], v[210:213], v[166:169], v[118:121]
	v_mfma_f32_16x16x32_bf16 v[114:117], v[218:221], v[166:169], v[114:117]
	v_mfma_f32_16x16x32_bf16 v[102:105], v[210:213], v[174:177], v[102:105]
	v_mfma_f32_16x16x32_bf16 v[98:101], v[218:221], v[174:177], v[98:101]
	v_mfma_f32_16x16x32_bf16 v[86:89], v[210:213], v[182:185], v[86:89]
	v_mfma_f32_16x16x32_bf16 v[82:85], v[218:221], v[182:185], v[82:85]
	v_mfma_f32_16x16x32_bf16 v[70:73], v[210:213], v[202:205], v[70:73]
	v_mfma_f32_16x16x32_bf16 v[66:69], v[218:221], v[202:205], v[66:69]
	s_mov_b32 m0, s29
	v_lshl_add_u64 v[198:199], s[22:23], 0, v[152:153]
	s_barrier
	ds_read_b128 v[162:165], v201 offset:16384
	ds_read_b128 v[166:169], v201 offset:17408
	ds_read_b128 v[170:173], v201 offset:18432
	ds_read_b128 v[174:177], v201 offset:19456
	ds_read_b128 v[178:181], v201 offset:20480
	ds_read_b128 v[182:185], v201 offset:21504
	ds_read_b128 v[186:189], v201 offset:22528
	ds_read_b128 v[202:205], v201 offset:23552
	global_load_lds_dwordx4 v[198:199], off
	v_lshl_add_u64 v[222:223], s[22:23], 0, v[148:149]
	s_mov_b32 m0, s30
	s_nop 0
	global_load_lds_dwordx4 v[222:223], off
	s_barrier
	s_waitcnt lgkmcnt(0)
	s_waitcnt lgkmcnt(0)
	v_mfma_f32_16x16x32_bf16 v[62:65], v[130:133], v[162:165], v[62:65]
	v_mfma_f32_16x16x32_bf16 v[58:61], v[138:141], v[162:165], v[58:61]
	v_mfma_f32_16x16x32_bf16 v[46:49], v[130:133], v[170:173], v[46:49]
	v_mfma_f32_16x16x32_bf16 v[42:45], v[138:141], v[170:173], v[42:45]
	v_mfma_f32_16x16x32_bf16 v[30:33], v[130:133], v[178:181], v[30:33]
	v_mfma_f32_16x16x32_bf16 v[26:29], v[138:141], v[178:181], v[26:29]
	v_mfma_f32_16x16x32_bf16 v[14:17], v[130:133], v[186:189], v[14:17]
	v_mfma_f32_16x16x32_bf16 v[10:13], v[138:141], v[186:189], v[10:13]
	v_mfma_f32_16x16x32_bf16 v[62:65], v[134:137], v[166:169], v[62:65]
	v_mfma_f32_16x16x32_bf16 v[58:61], v[142:145], v[166:169], v[58:61]
	v_mfma_f32_16x16x32_bf16 v[46:49], v[134:137], v[174:177], v[46:49]
	v_mfma_f32_16x16x32_bf16 v[42:45], v[142:145], v[174:177], v[42:45]
	v_mfma_f32_16x16x32_bf16 v[30:33], v[134:137], v[182:185], v[30:33]
	v_mfma_f32_16x16x32_bf16 v[26:29], v[142:145], v[182:185], v[26:29]
	v_mfma_f32_16x16x32_bf16 v[14:17], v[134:137], v[202:205], v[14:17]
	v_mfma_f32_16x16x32_bf16 v[10:13], v[142:145], v[202:205], v[10:13]
	s_barrier
; #define G_STAGE(bufoff, gbase, voff) do { _Pragma("unroll") for (int _i = 0; _i < 2; ++_i) \
;         __builtin_amdgcn_global_load_lds((const unsigned*)((const char*)(gbase) + (voff)[_i]), (LAS unsigned*)(lds + (bufoff) + ldsw + _i * 8192), 16, 0, 0); } while (0)
; #define G_LDA(dst, b, h) do { _Pragma("unroll") for (int m = 0; m < 4; ++m) _Pragma("unroll") for (int k = 0; k < 2; ++k) dst[m][k] = *(const LAS bf16x8*)(lds + G_SA(b, h) + aoff + m * 2048 + k * 1024); } while (0)
; #define G_LDB(dst, b, h) do { _Pragma("unroll") for (int n = 0; n < 2; ++n) _Pragma("unroll") for (int k = 0; k < 2; ++k) dst[n][k] = *(const LAS bf16x8*)(lds + G_SB(b, h) + boff + n * 2048 + k * 1024); } while (0)
; #define G_MMA(ai, bj, At, Bt) do { __builtin_amdgcn_s_setprio(1); _Pragma("unroll") for (int m = 0; m < 4; ++m) _Pragma("unroll") for (int n = 0; n < 2; ++n) _Pragma("unroll") for (int k = 0; k < 2; ++k) \
;         acc[ai][bj][m][n] = __builtin_amdgcn_mfma_f32_16x16x32_bf16(Bt[n][k], At[m][k], acc[ai][bj][m][n], 0, 0, 0); __builtin_amdgcn_s_setprio(0); } while (0)
; #define G_WAIT_V(n) asm volatile("s_waitcnt vmcnt(" #n ")" ::: "memory")
; #define G_WAIT_L(n) asm volatile("s_waitcnt lgkmcnt(" #n ")" ::: "memory")
; #define G_BAR __builtin_amdgcn_s_barrier()
; #define G_SCHED __builtin_amdgcn_sched_barrier(0)
; template <class Epi, class Sched>
; __device__ __forceinline__ void gemm_phase(LAS unsigned char* lds, const Sched& S, const Epi& E, const int K, const int lda, const int ldb, const int tid) {
;     ...
;             G_STAGE(G_SB(0, 1), b2 + hstepB, voffB);
;             G_WAIT_V(6); G_BAR; G_MMA(1, 1, At, B1); G_BAR;
;             G_LDB(B0, 1, 0); G_SCHED; G_LDA(At, 1, 0); G_STAGE(G_SA(0, 1), a2 + hstepA, voffA);
;             G_WAIT_L(8); G_BAR; G_WAIT_L(0); G_MMA(0, 0, At, B0); G_BAR; G_SCHED;
;             G_LDB(B1, 1, 1); G_STAGE(G_SB(1, 0), b3, voffB);
;             G_BAR; G_WAIT_L(0); G_MMA(0, 1, At, B1); G_BAR;
;             G_LDA(At, 1, 1); G_STAGE(G_SA(1, 0), a3, voffA);
;             G_BAR; G_WAIT_L(0); G_MMA(1, 0, At, B0); G_BAR; G_SCHED;
	s_add_u32 s60, s20, 0x80000
	s_addc_u32 s61, s21, 0
	s_add_i32 s43, s62, s27
	v_lshl_add_u64 v[130:131], s[60:61], 0, v[150:151]
	s_mov_b32 m0, s43
	s_nop 0
	global_load_lds_dwordx4 v[130:131], off
	v_lshl_add_u64 v[130:131], s[60:61], 0, v[146:147]
	s_add_i32 m0, s43, 0x2000
	s_nop 0
	global_load_lds_dwordx4 v[130:131], off
	s_waitcnt vmcnt(6)
	s_barrier
	v_mfma_f32_16x16x32_bf16 v[54:57], v[206:209], v[162:165], v[54:57]
	v_mfma_f32_16x16x32_bf16 v[50:53], v[214:217], v[162:165], v[50:53]
	v_mfma_f32_16x16x32_bf16 v[38:41], v[206:209], v[170:173], v[38:41]
	v_mfma_f32_16x16x32_bf16 v[34:37], v[214:217], v[170:173], v[34:37]
	v_mfma_f32_16x16x32_bf16 v[22:25], v[206:209], v[178:181], v[22:25]
	v_mfma_f32_16x16x32_bf16 v[18:21], v[214:217], v[178:181], v[18:21]
	v_mfma_f32_16x16x32_bf16 v[6:9], v[206:209], v[186:189], v[6:9]
	v_mfma_f32_16x16x32_bf16 v[2:5], v[214:217], v[186:189], v[2:5]
	v_mfma_f32_16x16x32_bf16 v[54:57], v[210:213], v[166:169], v[54:57]
	v_mfma_f32_16x16x32_bf16 v[50:53], v[218:221], v[166:169], v[50:53]
	v_mfma_f32_16x16x32_bf16 v[38:41], v[210:213], v[174:177], v[38:41]
	v_mfma_f32_16x16x32_bf16 v[34:37], v[218:221], v[174:177], v[34:37]
	v_mfma_f32_16x16x32_bf16 v[22:25], v[210:213], v[182:185], v[22:25]
	v_mfma_f32_16x16x32_bf16 v[18:21], v[218:221], v[182:185], v[18:21]
	v_mfma_f32_16x16x32_bf16 v[6:9], v[210:213], v[202:205], v[6:9]
	v_mfma_f32_16x16x32_bf16 v[2:5], v[218:221], v[202:205], v[2:5]
	s_add_i32 s43, 0, 0x18000
	v_add_u32_e32 v0, s43, v197
	s_barrier
	ds_read_b128 v[130:133], v0
	ds_read_b128 v[134:137], v0 offset:1024
	ds_read_b128 v[138:141], v0 offset:2048
	ds_read_b128 v[142:145], v0 offset:3072
	s_add_u32 s22, s22, 0x80000
	s_addc_u32 s23, s23, 0
	s_mov_b32 m0, s31
	v_lshl_add_u64 v[206:207], s[22:23], 0, v[152:153]
	ds_read_b128 v[162:165], v201 offset:32768
	ds_read_b128 v[166:169], v201 offset:33792
	ds_read_b128 v[170:173], v201 offset:34816
	ds_read_b128 v[174:177], v201 offset:35840
	ds_read_b128 v[178:181], v201 offset:36864
	ds_read_b128 v[182:185], v201 offset:37888
	ds_read_b128 v[186:189], v201 offset:38912
	ds_read_b128 v[202:205], v201 offset:39936
	global_load_lds_dwordx4 v[206:207], off
	v_lshl_add_u64 v[206:207], s[22:23], 0, v[148:149]
	s_mov_b32 m0, s34
	s_nop 0
	global_load_lds_dwordx4 v[206:207], off
	s_waitcnt lgkmcnt(8)
	s_barrier
	s_waitcnt lgkmcnt(0)
	s_waitcnt lgkmcnt(0)
	v_mfma_f32_16x16x32_bf16 v[126:129], v[130:133], v[162:165], v[126:129]
	v_mfma_f32_16x16x32_bf16 v[122:125], v[138:141], v[162:165], v[122:125]
	v_mfma_f32_16x16x32_bf16 v[110:113], v[130:133], v[170:173], v[110:113]
	v_mfma_f32_16x16x32_bf16 v[106:109], v[138:141], v[170:173], v[106:109]
	v_mfma_f32_16x16x32_bf16 v[94:97], v[130:133], v[178:181], v[94:97]
	v_mfma_f32_16x16x32_bf16 v[90:93], v[138:141], v[178:181], v[90:93]
	v_mfma_f32_16x16x32_bf16 v[78:81], v[130:133], v[186:189], v[78:81]
	v_mfma_f32_16x16x32_bf16 v[74:77], v[138:141], v[186:189], v[74:77]
	v_mfma_f32_16x16x32_bf16 v[126:129], v[134:137], v[166:169], v[126:129]
	v_mfma_f32_16x16x32_bf16 v[122:125], v[142:145], v[166:169], v[122:125]
	v_mfma_f32_16x16x32_bf16 v[110:113], v[134:137], v[174:177], v[110:113]
	v_mfma_f32_16x16x32_bf16 v[106:109], v[142:145], v[174:177], v[106:109]
	v_mfma_f32_16x16x32_bf16 v[94:97], v[134:137], v[182:185], v[94:97]
	v_mfma_f32_16x16x32_bf16 v[90:93], v[142:145], v[182:185], v[90:93]
	v_mfma_f32_16x16x32_bf16 v[78:81], v[134:137], v[202:205], v[78:81]
	v_mfma_f32_16x16x32_bf16 v[74:77], v[142:145], v[202:205], v[74:77]
	s_barrier
	s_add_i32 s22, 0, 0x1c000
	s_add_i32 s23, s43, s27
	v_add_u32_e32 v0, s22, v197
	v_lshl_add_u64 v[192:193], v[192:193], 0, s[92:93]
	s_mov_b32 m0, s23
	ds_read_b128 v[206:209], v0
	ds_read_b128 v[210:213], v0 offset:1024
	ds_read_b128 v[214:217], v0 offset:2048
	ds_read_b128 v[218:221], v0 offset:3072
	global_load_lds_dwordx4 v[192:193], off
	v_lshl_add_u64 v[192:193], v[194:195], 0, s[92:93]
	s_add_i32 m0, s23, 0x2000
	s_nop 0
	global_load_lds_dwordx4 v[192:193], off
	s_barrier
	s_waitcnt lgkmcnt(0)
	s_waitcnt lgkmcnt(0)
	v_mfma_f32_16x16x32_bf16 v[118:121], v[206:209], v[162:165], v[118:121]
	v_mfma_f32_16x16x32_bf16 v[114:117], v[214:217], v[162:165], v[114:117]
	v_mfma_f32_16x16x32_bf16 v[102:105], v[206:209], v[170:173], v[102:105]
	v_mfma_f32_16x16x32_bf16 v[98:101], v[214:217], v[170:173], v[98:101]
	v_mfma_f32_16x16x32_bf16 v[86:89], v[206:209], v[178:181], v[86:89]
	v_mfma_f32_16x16x32_bf16 v[82:85], v[214:217], v[178:181], v[82:85]
	v_mfma_f32_16x16x32_bf16 v[70:73], v[206:209], v[186:189], v[70:73]
	v_mfma_f32_16x16x32_bf16 v[66:69], v[214:217], v[186:189], v[66:69]
	v_mfma_f32_16x16x32_bf16 v[118:121], v[210:213], v[166:169], v[118:121]
	v_mfma_f32_16x16x32_bf16 v[114:117], v[218:221], v[166:169], v[114:117]
	v_mfma_f32_16x16x32_bf16 v[102:105], v[210:213], v[174:177], v[102:105]
	v_mfma_f32_16x16x32_bf16 v[98:101], v[218:221], v[174:177], v[98:101]
	v_mfma_f32_16x16x32_bf16 v[86:89], v[210:213], v[182:185], v[86:89]
	v_mfma_f32_16x16x32_bf16 v[82:85], v[218:221], v[182:185], v[82:85]
	v_mfma_f32_16x16x32_bf16 v[70:73], v[210:213], v[202:205], v[70:73]
	v_mfma_f32_16x16x32_bf16 v[66:69], v[218:221], v[202:205], v[66:69]
	s_mov_b32 m0, s35
	v_lshl_add_u64 v[192:193], v[198:199], 0, s[92:93]
	s_barrier
	ds_read_b128 v[162:165], v201 offset:49152
	ds_read_b128 v[166:169], v201 offset:50176
	ds_read_b128 v[170:173], v201 offset:51200
	ds_read_b128 v[174:177], v201 offset:52224
	ds_read_b128 v[178:181], v201 offset:53248
	ds_read_b128 v[182:185], v201 offset:54272
	ds_read_b128 v[186:189], v201 offset:55296
	ds_read_b128 v[202:205], v201 offset:56320
	global_load_lds_dwordx4 v[192:193], off
	v_lshl_add_u64 v[192:193], v[222:223], 0, s[92:93]
	s_mov_b32 m0, s36
	s_nop 0
	global_load_lds_dwordx4 v[192:193], off
	s_barrier
; #define G_STAGE(bufoff, gbase, voff) do { _Pragma("unroll") for (int _i = 0; _i < 2; ++_i) \
;         __builtin_amdgcn_global_load_lds((const unsigned*)((const char*)(gbase) + (voff)[_i]), (LAS unsigned*)(lds + (bufoff) + ldsw + _i * 8192), 16, 0, 0); } while (0)
; #define G_MMA(ai, bj, At, Bt) do { __builtin_amdgcn_s_setprio(1); _Pragma("unroll") for (int m = 0; m < 4; ++m) _Pragma("unroll") for (int n = 0; n < 2; ++n) _Pragma("unroll") for (int k = 0; k < 2; ++k) \
;         acc[ai][bj][m][n] = __builtin_amdgcn_mfma_f32_16x16x32_bf16(Bt[n][k], At[m][k], acc[ai][bj][m][n], 0, 0, 0); __builtin_amdgcn_s_setprio(0); } while (0)
; #define G_WAIT_V(n) asm volatile("s_waitcnt vmcnt(" #n ")" ::: "memory")
; #define G_WAIT_L(n) asm volatile("s_waitcnt lgkmcnt(" #n ")" ::: "memory")
; #define G_BAR __builtin_amdgcn_s_barrier()
; template <class Epi, class Sched>
; __device__ __forceinline__ void gemm_phase(LAS unsigned char* lds, const Sched& S, const Epi& E, const int K, const int lda, const int ldb, const int tid) {
;     ...
;             G_BAR; G_WAIT_L(0); G_MMA(1, 0, At, B0); G_BAR; G_SCHED;
;             G_STAGE(G_SB(1, 1), b3 + hstepB, voffB);
;             G_WAIT_V(6); G_BAR; G_MMA(1, 1, At, B1); G_BAR;
;     template <int KIND>
;     __device__ __forceinline__ void body(f32x4 (&acc)[2][2][4][2], const Unit& un, int wr, int wc, int fr, int fq) const {
;         const int sec = un.pn >> 3, colt = (un.pn & 7) * 256, cw = wc * 32 + 8 * fq;
;         const int rbase = un.pm * 256 + wr * 64 + fr;
;         float rstd[8];
; #pragma unroll
;         for (int i = 0; i < 8; ++i) rstd[i] = rsq[rbase + (i >> 2) * 128 + (i & 3) * 16];
;         f32x4 cfv[4];
;         if (KIND == 2 || KIND == 3) {
; #pragma unroll
;             for (int t = 0; t < 4; ++t) cfv[t] = *(const f32x4*)(cf + (size_t)cw * 2 + t * 4);
;         }
; #pragma unroll
;         for (int i = 0; i < 8; ++i) rstd[i] = rsqrtf(rstd[i] * (1.0f / 2048.0f) + EPS);
; #pragma unroll
;         for (int ai = 0; ai < 2; ++ai)
; #pragma unroll
;             for (int m = 0; m < 4; ++m) {
;                 const int r = rbase + ai * 128 + m * 16;
;                 const float rs = rstd[ai * 4 + m];
;                 f32x4 v[2][2];
; #pragma unroll
;                 for (int bj = 0; bj < 2; ++bj)
; #pragma unroll
;                     for (int n = 0; n < 2; ++n) v[bj][n] = acc[ai][bj][m][n] * rs;
	s_waitcnt lgkmcnt(0)
	s_waitcnt lgkmcnt(0)
	v_mfma_f32_16x16x32_bf16 v[62:65], v[130:133], v[162:165], v[62:65]
	v_mfma_f32_16x16x32_bf16 v[58:61], v[138:141], v[162:165], v[58:61]
	v_mfma_f32_16x16x32_bf16 v[46:49], v[130:133], v[170:173], v[46:49]
	v_mfma_f32_16x16x32_bf16 v[42:45], v[138:141], v[170:173], v[42:45]
	v_mfma_f32_16x16x32_bf16 v[30:33], v[130:133], v[178:181], v[30:33]
	v_mfma_f32_16x16x32_bf16 v[26:29], v[138:141], v[178:181], v[26:29]
	v_mfma_f32_16x16x32_bf16 v[14:17], v[130:133], v[186:189], v[14:17]
	v_mfma_f32_16x16x32_bf16 v[10:13], v[138:141], v[186:189], v[10:13]
	v_mfma_f32_16x16x32_bf16 v[62:65], v[134:137], v[166:169], v[62:65]
	v_mfma_f32_16x16x32_bf16 v[58:61], v[142:145], v[166:169], v[58:61]
	v_mfma_f32_16x16x32_bf16 v[46:49], v[134:137], v[174:177], v[46:49]
	v_mfma_f32_16x16x32_bf16 v[42:45], v[142:145], v[174:177], v[42:45]
	v_mfma_f32_16x16x32_bf16 v[30:33], v[134:137], v[182:185], v[30:33]
	v_mfma_f32_16x16x32_bf16 v[26:29], v[142:145], v[182:185], v[26:29]
	v_mfma_f32_16x16x32_bf16 v[14:17], v[134:137], v[202:205], v[14:17]
	v_mfma_f32_16x16x32_bf16 v[10:13], v[142:145], v[202:205], v[10:13]
	s_barrier
	s_add_u32 s20, s20, 0x80080
	s_addc_u32 s21, s21, 0
	s_add_i32 s22, s22, s27
	v_lshl_add_u64 v[130:131], s[20:21], 0, v[150:151]
	s_mov_b32 m0, s22
	s_nop 0
	global_load_lds_dwordx4 v[130:131], off
	v_lshl_add_u64 v[130:131], s[20:21], 0, v[146:147]
	s_add_i32 m0, s22, 0x2000
	s_nop 0
	global_load_lds_dwordx4 v[130:131], off
	s_waitcnt vmcnt(6)
	s_barrier
	v_mfma_f32_16x16x32_bf16 v[54:57], v[206:209], v[162:165], v[54:57]
	v_mfma_f32_16x16x32_bf16 v[50:53], v[214:217], v[162:165], v[50:53]
	v_mfma_f32_16x16x32_bf16 v[38:41], v[206:209], v[170:173], v[38:41]
	v_mfma_f32_16x16x32_bf16 v[34:37], v[214:217], v[170:173], v[34:37]
	v_mfma_f32_16x16x32_bf16 v[22:25], v[206:209], v[178:181], v[22:25]
	v_mfma_f32_16x16x32_bf16 v[18:21], v[214:217], v[178:181], v[18:21]
	v_mfma_f32_16x16x32_bf16 v[6:9], v[206:209], v[186:189], v[6:9]
	v_mfma_f32_16x16x32_bf16 v[2:5], v[214:217], v[186:189], v[2:5]
	v_mfma_f32_16x16x32_bf16 v[54:57], v[210:213], v[166:169], v[54:57]
	v_mfma_f32_16x16x32_bf16 v[50:53], v[218:221], v[166:169], v[50:53]
	v_mfma_f32_16x16x32_bf16 v[38:41], v[210:213], v[174:177], v[38:41]
	v_mfma_f32_16x16x32_bf16 v[34:37], v[218:221], v[174:177], v[34:37]
	v_mfma_f32_16x16x32_bf16 v[22:25], v[210:213], v[182:185], v[22:25]
	v_mfma_f32_16x16x32_bf16 v[18:21], v[218:221], v[182:185], v[18:21]
	v_mfma_f32_16x16x32_bf16 v[6:9], v[210:213], v[202:205], v[6:9]
	v_mfma_f32_16x16x32_bf16 v[2:5], v[218:221], v[202:205], v[2:5]
	s_add_i32 s41, s41, 2
	s_add_u32 s18, s18, 0x100
	s_addc_u32 s19, s19, 0
	s_add_u32 s39, s39, 0x100
	s_addc_u32 s40, s40, 0
	s_cmp_gt_u32 s41, 29
	s_barrier
	s_cbranch_scc0 .LBB0_556
	s_mov_b64 s[18:19], -1
	s_cmp_gt_u32 s38, 7
	v_lshl_add_u32 v162, s0, 8, v155
	v_readlane_b32 s43, v254, 36
	v_readlane_b32 s60, v254, 37
	v_readlane_b32 s41, v254, 38
	v_readlane_b32 s40, v254, 39
	s_cbranch_scc0 .LBB0_577
	v_ashrrev_i32_e32 v163, 31, v162
	v_lshl_add_u64 v[130:131], v[162:163], 2, s[8:9]
	global_load_dword v209, v[130:131], off
	global_load_dword v208, v[130:131], off offset:64
	global_load_dword v207, v[130:131], off offset:128
	global_load_dword v206, v[130:131], off offset:192
	global_load_dword v205, v[130:131], off offset:512
	global_load_dword v204, v[130:131], off offset:576
	global_load_dword v203, v[130:131], off offset:640
	global_load_dword v202, v[130:131], off offset:704
	s_lshl_b32 s1, s38, 8
	s_ashr_i32 s18, s38, 3
	s_and_b32 s0, s38, 0xffffffd8
	s_and_b32 s11, s1, 0x700
	s_cmp_lg_u32 s0, 8
	v_add_u32_e32 v163, 0x80, v162
	s_mov_b64 s[0:1], -1
	s_cbranch_scc0 .LBB0_574
	s_mov_b64 s[22:23], -1
	s_mov_b64 s[20:21], 0
	s_cmp_lt_i32 s18, 3
	s_mov_b64 s[0:1], 0
	s_cbranch_scc1 .LBB0_569
	s_cmp_gt_i32 s18, 3
	s_cbranch_scc0 .LBB0_564
	s_cmp_eq_u32 s18, 4
	s_mov_b64 s[0:1], -1
	s_cbranch_scc0 .LBB0_563
	s_waitcnt vmcnt(0)
	v_fmamk_f32 v0, v209, 0x3a000000, v190
	v_cmp_gt_f32_e32 vcc, s78, v0
	v_mul_f32_e32 v130, 0x4b800000, v0
	v_readlane_b32 s0, v253, 19
	v_cndmask_b32_e32 v0, v0, v130, vcc
	v_rsq_f32_e32 v0, v0
	v_readlane_b32 s1, v253, 20
	s_lshl_b32 s90, s11, 1
	s_movk_i32 s13, 0x3000
	v_mul_f32_e32 v130, 0x45800000, v0
	v_cndmask_b32_e32 v0, v0, v130, vcc
	v_fmamk_f32 v130, v208, 0x3a000000, v190
	v_cmp_gt_f32_e32 vcc, s78, v130
	v_mul_f32_e32 v131, 0x4b800000, v130
	v_mov_b64_e32 v[132:133], s[0:1]
	v_cndmask_b32_e32 v130, v130, v131, vcc
	v_rsq_f32_e32 v130, v130
	v_mad_i64_i32 v[180:181], s[0:1], v162, s74, v[132:133]
	v_pk_mul_f32 v[166:167], v[128:129], v[0:1] op_sel_hi:[1,0]
	v_mul_f32_e32 v131, 0x45800000, v130
	v_cndmask_b32_e32 v144, v130, v131, vcc
	v_fmamk_f32 v130, v207, 0x3a000000, v190
	v_cmp_gt_f32_e32 vcc, s78, v130
	v_mul_f32_e32 v131, 0x4b800000, v130
	v_pk_mul_f32 v[164:165], v[126:127], v[0:1] op_sel_hi:[1,0]
	v_cndmask_b32_e32 v130, v130, v131, vcc
	v_rsq_f32_e32 v130, v130
	v_pk_mul_f32 v[168:169], v[124:125], v[0:1] op_sel_hi:[1,0]
	v_pk_mul_f32 v[170:171], v[122:123], v[0:1] op_sel_hi:[1,0]
	v_pk_mul_f32 v[172:173], v[120:121], v[0:1] op_sel_hi:[1,0]
	v_mul_f32_e32 v131, 0x45800000, v130
	v_cndmask_b32_e32 v142, v130, v131, vcc
	v_fmamk_f32 v130, v206, 0x3a000000, v190
	v_cmp_gt_f32_e32 vcc, s78, v130
	v_mul_f32_e32 v131, 0x4b800000, v130
	v_pk_mul_f32 v[174:175], v[118:119], v[0:1] op_sel_hi:[1,0]
	v_cndmask_b32_e32 v130, v130, v131, vcc
	v_rsq_f32_e32 v130, v130
	v_pk_mul_f32 v[176:177], v[116:117], v[0:1] op_sel_hi:[1,0]
	v_pk_mul_f32 v[178:179], v[114:115], v[0:1] op_sel_hi:[1,0]
	v_lshl_add_u64 v[180:181], v[180:181], 0, s[90:91]
; __device__ __forceinline__ unsigned pk_bf16(float lo, float hi) { unsigned r; asm volatile("v_cvt_pk_bf16_f32 %0, %1, %2" : "=v"(r) : "v"(lo), "v"(hi)); return r; }
;     template <int KIND>
;     __device__ __forceinline__ void body(f32x4 (&acc)[2][2][4][2], const Unit& un, int wr, int wc, int fr, int fq) const {
;     ...
;         for (int i = 0; i < 8; ++i) rstd[i] = rsqrtf(rstd[i] * (1.0f / 2048.0f) + EPS);
; #pragma unroll
;         for (int ai = 0; ai < 2; ++ai)
; #pragma unroll
;             for (int m = 0; m < 4; ++m) {
;                 const int r = rbase + ai * 128 + m * 16;
;                 const float rs = rstd[ai * 4 + m];
;                 f32x4 v[2][2];
; #pragma unroll
;                 for (int bj = 0; bj < 2; ++bj)
; #pragma unroll
;                     for (int n = 0; n < 2; ++n) v[bj][n] = acc[ai][bj][m][n] * rs;
;     ...
;                     bf16_t* zp = zb + (size_t)r * ZW + (size_t)(sec - 1) * 2048 + colt + cw;
; #pragma unroll
;                     for (int bj = 0; bj < 2; ++bj) { u32x4 w; w.x = pk_bf16(v[bj][0][0], v[bj][0][1]); w.y = pk_bf16(v[bj][0][2], v[bj][0][3]); w.z = pk_bf16(v[bj][1][0], v[bj][1][1]); w.w = pk_bf16(v[bj][1][2], v[bj][1][3]);
;                         *(u32x4*)(zp + bj * 128) = w; }
	v_mul_f32_e32 v131, 0x45800000, v130
	v_cndmask_b32_e32 v140, v130, v131, vcc
	v_fmamk_f32 v130, v205, 0x3a000000, v190
	v_cmp_gt_f32_e32 vcc, s78, v130
	v_mul_f32_e32 v131, 0x4b800000, v130
	v_lshlrev_b32_e32 v0, 1, v154
	v_cndmask_b32_e32 v130, v130, v131, vcc
	v_rsq_f32_e32 v130, v130
	v_lshl_add_u64 v[180:181], v[180:181], 0, v[0:1]
	v_cvt_pk_bf16_f32 v164, v164, v165
	v_cvt_pk_bf16_f32 v165, v166, v167
	v_mul_f32_e32 v131, 0x45800000, v130
	v_cndmask_b32_e32 v138, v130, v131, vcc
	v_fmamk_f32 v130, v204, 0x3a000000, v190
	v_cmp_gt_f32_e32 vcc, s78, v130
	v_mul_f32_e32 v131, 0x4b800000, v130
	v_cvt_pk_bf16_f32 v166, v170, v171
	v_cvt_pk_bf16_f32 v167, v168, v169
	s_mov_b64 s[22:23], 0x3000
	v_cndmask_b32_e32 v130, v130, v131, vcc
	v_rsq_f32_e32 v130, v130
	v_lshl_add_u64 v[182:183], v[180:181], 0, s[22:23]
	v_pk_mul_f32 v[170:171], v[106:107], v[144:145] op_sel_hi:[1,0]
	v_mul_f32_e32 v131, 0x45800000, v130
	v_cndmask_b32_e32 v136, v130, v131, vcc
	v_fmamk_f32 v130, v203, 0x3a000000, v190
	v_cmp_gt_f32_e32 vcc, s78, v130
	v_mul_f32_e32 v131, 0x4b800000, v130
	s_nop 0
	v_cndmask_b32_e32 v130, v130, v131, vcc
	v_rsq_f32_e32 v130, v130
	s_nop 0
	v_mul_f32_e32 v131, 0x45800000, v130
	v_cndmask_b32_e32 v134, v130, v131, vcc
	v_fmamk_f32 v130, v202, 0x3a000000, v190
	v_cmp_gt_f32_e32 vcc, s78, v130
	v_mul_f32_e32 v131, 0x4b800000, v130
	s_nop 0
	v_cndmask_b32_e32 v130, v130, v131, vcc
	v_rsq_f32_e32 v130, v130
	s_nop 0
	v_mul_f32_e32 v131, 0x45800000, v130
	v_cndmask_b32_e32 v130, v130, v131, vcc
	v_add_co_u32_e32 v168, vcc, s13, v180
	v_or_b32_e32 v131, 16, v162
	s_nop 0
	v_addc_co_u32_e32 v169, vcc, 0, v181, vcc
	global_store_dwordx4 v[168:169], v[164:167], off
	v_pk_mul_f32 v[168:169], v[108:109], v[144:145] op_sel_hi:[1,0]
	s_nop 0
	v_cvt_pk_bf16_f32 v164, v174, v175
	v_cvt_pk_bf16_f32 v165, v172, v173
	v_cvt_pk_bf16_f32 v166, v178, v179
	v_mad_i64_i32 v[178:179], s[0:1], v131, s74, v[132:133]
	v_cvt_pk_bf16_f32 v167, v176, v177
	v_lshl_add_u64 v[178:179], v[178:179], 0, s[90:91]
	global_store_dwordx4 v[182:183], v[164:167], off offset:256
	v_lshl_add_u64 v[178:179], v[178:179], 0, v[0:1]
	v_pk_mul_f32 v[172:173], v[104:105], v[144:145] op_sel_hi:[1,0]
	v_pk_mul_f32 v[166:167], v[112:113], v[144:145] op_sel_hi:[1,0]
	v_pk_mul_f32 v[164:165], v[110:111], v[144:145] op_sel_hi:[1,0]
	v_pk_mul_f32 v[174:175], v[102:103], v[144:145] op_sel_hi:[1,0]
	v_cvt_pk_bf16_f32 v164, v164, v165
	v_cvt_pk_bf16_f32 v165, v166, v167
	v_cvt_pk_bf16_f32 v166, v170, v171
	v_cvt_pk_bf16_f32 v167, v168, v169
	v_add_co_u32_e32 v168, vcc, s13, v178
	v_pk_mul_f32 v[176:177], v[100:101], v[144:145] op_sel_hi:[1,0]
	s_nop 0
	v_addc_co_u32_e32 v169, vcc, 0, v179, vcc
	v_pk_mul_f32 v[144:145], v[98:99], v[144:145] op_sel_hi:[1,0]
	v_lshl_add_u64 v[180:181], v[178:179], 0, s[22:23]
	global_store_dwordx4 v[168:169], v[164:167], off
	v_or_b32_e32 v131, 32, v162
	v_pk_mul_f32 v[168:169], v[90:91], v[142:143] op_sel_hi:[1,0]
	v_cvt_pk_bf16_f32 v164, v174, v175
	v_cvt_pk_bf16_f32 v165, v172, v173
	v_cvt_pk_bf16_f32 v166, v144, v145
	v_cvt_pk_bf16_f32 v167, v176, v177
	global_store_dwordx4 v[180:181], v[164:167], off offset:256
	v_pk_mul_f32 v[144:145], v[96:97], v[142:143] op_sel_hi:[1,0]
	v_pk_mul_f32 v[170:171], v[88:89], v[142:143] op_sel_hi:[1,0]
	v_pk_mul_f32 v[164:165], v[94:95], v[142:143] op_sel_hi:[1,0]
	v_pk_mul_f32 v[166:167], v[92:93], v[142:143] op_sel_hi:[1,0]
	v_pk_mul_f32 v[172:173], v[86:87], v[142:143] op_sel_hi:[1,0]
	v_pk_mul_f32 v[174:175], v[84:85], v[142:143] op_sel_hi:[1,0]
	v_pk_mul_f32 v[176:177], v[82:83], v[142:143] op_sel_hi:[1,0]
	v_mad_i64_i32 v[142:143], s[0:1], v131, s74, v[132:133]
	v_lshl_add_u64 v[142:143], v[142:143], 0, s[90:91]
	v_lshl_add_u64 v[178:179], v[142:143], 0, v[0:1]
	v_cvt_pk_bf16_f32 v142, v164, v165
	v_add_co_u32_e32 v164, vcc, s13, v178
	v_cvt_pk_bf16_f32 v143, v144, v145
	v_cvt_pk_bf16_f32 v144, v168, v169
	v_cvt_pk_bf16_f32 v145, v166, v167
	v_lshl_add_u64 v[180:181], v[178:179], 0, s[22:23]
	s_nop 0
	v_addc_co_u32_e32 v165, vcc, 0, v179, vcc
	global_store_dwordx4 v[164:165], v[142:145], off
	v_or_b32_e32 v131, 48, v162
	v_pk_mul_f32 v[164:165], v[76:77], v[140:141] op_sel_hi:[1,0]
	v_cvt_pk_bf16_f32 v142, v172, v173
	v_cvt_pk_bf16_f32 v143, v170, v171
	v_cvt_pk_bf16_f32 v144, v176, v177
	v_cvt_pk_bf16_f32 v145, v174, v175
	global_store_dwordx4 v[180:181], v[142:145], off offset:256
	v_pk_mul_f32 v[166:167], v[74:75], v[140:141] op_sel_hi:[1,0]
	v_pk_mul_f32 v[168:169], v[72:73], v[140:141] op_sel_hi:[1,0]
	v_pk_mul_f32 v[142:143], v[80:81], v[140:141] op_sel_hi:[1,0]
	v_pk_mul_f32 v[144:145], v[78:79], v[140:141] op_sel_hi:[1,0]
	v_pk_mul_f32 v[170:171], v[70:71], v[140:141] op_sel_hi:[1,0]
	v_pk_mul_f32 v[172:173], v[68:69], v[140:141] op_sel_hi:[1,0]
	v_pk_mul_f32 v[174:175], v[66:67], v[140:141] op_sel_hi:[1,0]
	v_mad_i64_i32 v[140:141], s[0:1], v131, s74, v[132:133]
	v_lshl_add_u64 v[140:141], v[140:141], 0, s[90:91]
	v_lshl_add_u64 v[176:177], v[140:141], 0, v[0:1]
	v_cvt_pk_bf16_f32 v140, v144, v145
	v_add_co_u32_e32 v144, vcc, s13, v176
	v_cvt_pk_bf16_f32 v141, v142, v143
	v_cvt_pk_bf16_f32 v142, v166, v167
	v_cvt_pk_bf16_f32 v143, v164, v165
	v_lshl_add_u64 v[178:179], v[176:177], 0, s[22:23]
	s_nop 0
; __device__ __forceinline__ unsigned pk_bf16(float lo, float hi) { unsigned r; asm volatile("v_cvt_pk_bf16_f32 %0, %1, %2" : "=v"(r) : "v"(lo), "v"(hi)); return r; }
;     template <int KIND>
;     __device__ __forceinline__ void body(f32x4 (&acc)[2][2][4][2], const Unit& un, int wr, int wc, int fr, int fq) const {
;     ...
;         for (int ai = 0; ai < 2; ++ai)
; #pragma unroll
;             for (int m = 0; m < 4; ++m) {
;                 const int r = rbase + ai * 128 + m * 16;
;                 const float rs = rstd[ai * 4 + m];
;                 f32x4 v[2][2];
; #pragma unroll
;                 for (int bj = 0; bj < 2; ++bj)
; #pragma unroll
;                     for (int n = 0; n < 2; ++n) v[bj][n] = acc[ai][bj][m][n] * rs;
;     ...
;                     bf16_t* zp = zb + (size_t)r * ZW + (size_t)(sec - 1) * 2048 + colt + cw;
; #pragma unroll
;                     for (int bj = 0; bj < 2; ++bj) { u32x4 w; w.x = pk_bf16(v[bj][0][0], v[bj][0][1]); w.y = pk_bf16(v[bj][0][2], v[bj][0][3]); w.z = pk_bf16(v[bj][1][0], v[bj][1][1]); w.w = pk_bf16(v[bj][1][2], v[bj][1][3]);
;                         *(u32x4*)(zp + bj * 128) = w; }
	v_addc_co_u32_e32 v145, vcc, 0, v177, vcc
	global_store_dwordx4 v[144:145], v[140:143], off
	v_pk_mul_f32 v[144:145], v[60:61], v[138:139] op_sel_hi:[1,0]
	v_pk_mul_f32 v[164:165], v[58:59], v[138:139] op_sel_hi:[1,0]
	v_cvt_pk_bf16_f32 v140, v170, v171
	v_cvt_pk_bf16_f32 v141, v168, v169
	v_cvt_pk_bf16_f32 v142, v174, v175
	v_cvt_pk_bf16_f32 v143, v172, v173
	global_store_dwordx4 v[178:179], v[140:143], off offset:256
	v_pk_mul_f32 v[166:167], v[56:57], v[138:139] op_sel_hi:[1,0]
	v_pk_mul_f32 v[168:169], v[54:55], v[138:139] op_sel_hi:[1,0]
	v_pk_mul_f32 v[140:141], v[64:65], v[138:139] op_sel_hi:[1,0]
	v_pk_mul_f32 v[142:143], v[62:63], v[138:139] op_sel_hi:[1,0]
	v_pk_mul_f32 v[170:171], v[52:53], v[138:139] op_sel_hi:[1,0]
	v_pk_mul_f32 v[172:173], v[50:51], v[138:139] op_sel_hi:[1,0]
	v_mad_i64_i32 v[138:139], s[0:1], v163, s74, v[132:133]
	v_lshl_add_u64 v[138:139], v[138:139], 0, s[90:91]
	v_lshl_add_u64 v[174:175], v[138:139], 0, v[0:1]
	v_cvt_pk_bf16_f32 v138, v142, v143
	v_add_co_u32_e32 v142, vcc, s13, v174
	v_cvt_pk_bf16_f32 v139, v140, v141
	v_cvt_pk_bf16_f32 v140, v164, v165
	v_cvt_pk_bf16_f32 v141, v144, v145
	v_lshl_add_u64 v[176:177], v[174:175], 0, s[22:23]
	s_nop 0
	v_addc_co_u32_e32 v143, vcc, 0, v175, vcc
	global_store_dwordx4 v[142:143], v[138:141], off
	v_add_u32_e32 v131, 0x90, v162
	v_pk_mul_f32 v[142:143], v[44:45], v[136:137] op_sel_hi:[1,0]
	v_cvt_pk_bf16_f32 v138, v168, v169
	v_cvt_pk_bf16_f32 v139, v166, v167
	v_cvt_pk_bf16_f32 v140, v172, v173
	v_cvt_pk_bf16_f32 v141, v170, v171
	global_store_dwordx4 v[176:177], v[138:141], off offset:256
	v_pk_mul_f32 v[144:145], v[42:43], v[136:137] op_sel_hi:[1,0]
	v_pk_mul_f32 v[164:165], v[40:41], v[136:137] op_sel_hi:[1,0]
	v_pk_mul_f32 v[138:139], v[48:49], v[136:137] op_sel_hi:[1,0]
	v_pk_mul_f32 v[140:141], v[46:47], v[136:137] op_sel_hi:[1,0]
	v_pk_mul_f32 v[166:167], v[38:39], v[136:137] op_sel_hi:[1,0]
	v_pk_mul_f32 v[168:169], v[36:37], v[136:137] op_sel_hi:[1,0]
	v_pk_mul_f32 v[170:171], v[34:35], v[136:137] op_sel_hi:[1,0]
	v_mad_i64_i32 v[136:137], s[0:1], v131, s74, v[132:133]
	v_lshl_add_u64 v[136:137], v[136:137], 0, s[90:91]
	v_lshl_add_u64 v[172:173], v[136:137], 0, v[0:1]
	v_cvt_pk_bf16_f32 v136, v140, v141
	v_add_co_u32_e32 v140, vcc, s13, v172
	v_cvt_pk_bf16_f32 v137, v138, v139
	v_cvt_pk_bf16_f32 v138, v144, v145
	v_cvt_pk_bf16_f32 v139, v142, v143
	v_lshl_add_u64 v[174:175], v[172:173], 0, s[22:23]
	s_nop 0
	v_addc_co_u32_e32 v141, vcc, 0, v173, vcc
	global_store_dwordx4 v[140:141], v[136:139], off
	v_add_u32_e32 v131, 0xa0, v162
	v_pk_mul_f32 v[140:141], v[28:29], v[134:135] op_sel_hi:[1,0]
	v_cvt_pk_bf16_f32 v136, v166, v167
	v_cvt_pk_bf16_f32 v137, v164, v165
	v_cvt_pk_bf16_f32 v138, v170, v171
	v_cvt_pk_bf16_f32 v139, v168, v169
	global_store_dwordx4 v[174:175], v[136:139], off offset:256
	v_pk_mul_f32 v[142:143], v[26:27], v[134:135] op_sel_hi:[1,0]
	v_pk_mul_f32 v[144:145], v[24:25], v[134:135] op_sel_hi:[1,0]
	v_pk_mul_f32 v[136:137], v[32:33], v[134:135] op_sel_hi:[1,0]
	v_pk_mul_f32 v[138:139], v[30:31], v[134:135] op_sel_hi:[1,0]
	v_pk_mul_f32 v[164:165], v[22:23], v[134:135] op_sel_hi:[1,0]
	v_pk_mul_f32 v[166:167], v[20:21], v[134:135] op_sel_hi:[1,0]
	v_pk_mul_f32 v[168:169], v[18:19], v[134:135] op_sel_hi:[1,0]
	v_mad_i64_i32 v[134:135], s[0:1], v131, s74, v[132:133]
	v_lshl_add_u64 v[134:135], v[134:135], 0, s[90:91]
	v_lshl_add_u64 v[170:171], v[134:135], 0, v[0:1]
	v_cvt_pk_bf16_f32 v134, v138, v139
	v_add_co_u32_e32 v138, vcc, s13, v170
	v_cvt_pk_bf16_f32 v135, v136, v137
	v_cvt_pk_bf16_f32 v136, v142, v143
	v_cvt_pk_bf16_f32 v137, v140, v141
	v_lshl_add_u64 v[172:173], v[170:171], 0, s[22:23]
	s_nop 0
	v_addc_co_u32_e32 v139, vcc, 0, v171, vcc
	global_store_dwordx4 v[138:139], v[134:137], off
	v_pk_mul_f32 v[138:139], v[12:13], v[130:131] op_sel_hi:[1,0]
	v_pk_mul_f32 v[140:141], v[10:11], v[130:131] op_sel_hi:[1,0]
	v_cvt_pk_bf16_f32 v134, v164, v165
	v_cvt_pk_bf16_f32 v135, v144, v145
	v_cvt_pk_bf16_f32 v136, v168, v169
	v_cvt_pk_bf16_f32 v137, v166, v167
	global_store_dwordx4 v[172:173], v[134:137], off offset:256
	v_pk_mul_f32 v[142:143], v[8:9], v[130:131] op_sel_hi:[1,0]
	v_pk_mul_f32 v[144:145], v[6:7], v[130:131] op_sel_hi:[1,0]
	v_pk_mul_f32 v[134:135], v[16:17], v[130:131] op_sel_hi:[1,0]
	v_pk_mul_f32 v[136:137], v[14:15], v[130:131] op_sel_hi:[1,0]
	v_pk_mul_f32 v[164:165], v[4:5], v[130:131] op_sel_hi:[1,0]
	v_pk_mul_f32 v[166:167], v[2:3], v[130:131] op_sel_hi:[1,0]
	v_add_u32_e32 v130, 0xb0, v162
	v_mad_i64_i32 v[130:131], s[0:1], v130, s74, v[132:133]
	v_lshl_add_u64 v[130:131], v[130:131], 0, s[90:91]
	v_lshl_add_u64 v[168:169], v[130:131], 0, v[0:1]
	v_cvt_pk_bf16_f32 v130, v136, v137
	v_cvt_pk_bf16_f32 v131, v134, v135
	v_add_co_u32_e32 v134, vcc, s13, v168
	v_lshl_add_u64 v[170:171], v[168:169], 0, s[22:23]
	v_cvt_pk_bf16_f32 v132, v140, v141
	v_cvt_pk_bf16_f32 v133, v138, v139
	s_nop 0
	v_addc_co_u32_e32 v135, vcc, 0, v169, vcc
	global_store_dwordx4 v[134:135], v[130:133], off
	s_mov_b64 s[0:1], 0
	s_nop 0
	v_cvt_pk_bf16_f32 v130, v144, v145
	v_cvt_pk_bf16_f32 v131, v142, v143
	v_cvt_pk_bf16_f32 v132, v166, v167
	v_cvt_pk_bf16_f32 v133, v164, v165
	global_store_dwordx4 v[170:171], v[130:133], off offset:256
